# row-block dependency counters: Wout/FFN-out (layer 0) tiles bump per-row-block counters, norm2 / next-layer norm1 wait per row instead of a grid barrier; late row last
# speedup vs baseline: 1.0068x; 1.0068x over previous
; DI void xcd_barrier(const XcdBarrier& b) {
;   asm volatile("s_waitcnt vmcnt(0)" ::: "memory");
;   __syncthreads();
;   if (threadIdx.x == 0) {
;     unsigned* bar = b.bar;
;     __builtin_amdgcn_s_waitcnt(0);
;     unsigned nloc = b.st[0], nx = b.st[1];
;     if (nloc == 0u) { xcd_barrier_complete(bar, b.x, nloc, nx); b.st[0] = nloc; b.st[1] = nx; }
; __global__ void __launch_bounds__(256, 2) mega(Params p, int ph_lo, int ph_hi) {
;     ...
;   for (int ph = ph_lo; ph < ph_hi; ++ph) {
;     if (ph > ph_lo) xcd_barrier(xb);
;     run_phase<-1>(p, ph, lds);
.LBB0_8:
	s_cmp_le_i32 s77, s80
	s_cbranch_scc1 .LBB0_62
	s_cmp_eq_u32 s77, 7
	s_cbranch_scc1 .LBB0_62
	s_cmp_eq_u32 s77, 10
	s_cbranch_scc1 .LBB0_62
	s_waitcnt vmcnt(0)
	s_barrier
	s_mov_b64 s[0:1], exec
	v_readlane_b32 s2, v251, 2
	v_readlane_b32 s3, v251, 3
	s_and_b64 s[2:3], s[0:1], s[2:3]
	s_mov_b64 exec, s[2:3]
	s_cbranch_execz .LBB0_61
	s_waitcnt vmcnt(0) expcnt(0) lgkmcnt(0)
	ds_read_b32 v3, v140
	ds_read_b32 v2, v141
	s_waitcnt lgkmcnt(1)
	v_cmp_ne_u32_e32 vcc, 0, v3
	s_cbranch_vccnz .LBB0_25
	s_mov_b32 s21, 1
	s_branch .LBB0_13

; template <class Epi>
; DI void gemm_tile(const bf16_t* __restrict__ A, int lda, const bf16_t* __restrict__ Bt, int ldb, int K, int row0, int col0, char* lds, const Epi& epi) {
;     ...
;   for (int kt = 0; kt < KT; ++kt) {
;     asm volatile("s_waitcnt vmcnt(0)" ::: "memory");
;     __syncthreads();
;     const char* sa = lds + (kt & 1) * 32768 + (wr * 64 + fr) * 128;
;     const char* sb = lds + (kt & 1) * 32768 + 16384 + (wc * 64 + fr) * 128;
; #pragma unroll
;     for (int kk = 0; kk < 2; ++kk) {
;       if (kt + 1 < KT) { if (kk == 0) stage_a(kt + 1, (kt + 1) & 1); else stage_b(kt + 1, (kt + 1) & 1); }
;       bf16x8 a[4], b[4];
;       const int co = ((kk * 4 + fq) ^ swz) * 16;
; #pragma unroll
;       for (int m = 0; m < 4; ++m) a[m] = *(const bf16x8*)(sa + m * 2048 + co);
; #pragma unroll
;       for (int n = 0; n < 4; ++n) b[n] = *(const bf16x8*)(sb + n * 2048 + co);
; #pragma unroll
;       for (int m = 0; m < 4; ++m)
; #pragma unroll
;         for (int n = 0; n < 4; ++n) acc[m][n] = __builtin_amdgcn_mfma_f32_16x16x32_bf16(b[n], a[m], acc[m][n], 0, 0, 0);
;     }
;   }
.LBB0_84:
	s_add_i32 s20, s28, 0xffff8000
	s_and_b32 s29, s28, 0x8000
	s_and_b32 s20, s20, 0x8000
	v_add_u32_e32 v102, s29, v90
	v_add_u32_e32 v110, s20, v91
	v_or_b32_e32 v136, s20, v93
	v_add_u32_e32 v103, 0x1000, v102
	v_readfirstlane_b32 s20, v102
	v_lshl_add_u64 v[94:95], v[74:75], 0, s[0:1]
	v_add_u32_e32 v104, 0x2000, v102
	s_mov_b32 m0, s20
	v_readfirstlane_b32 s20, v103
	s_waitcnt vmcnt(0)
	s_waitcnt vmcnt(0) lgkmcnt(0)
	s_barrier
	v_lshl_add_u64 v[96:97], v[76:77], 0, s[0:1]
	v_add_u32_e32 v105, 0x3000, v102
	global_load_lds_dwordx4 v[94:95], off
	s_mov_b32 m0, s20
	v_readfirstlane_b32 s20, v104
	v_add_u32_e32 v137, 0x4000, v102
	v_lshl_add_u64 v[98:99], v[78:79], 0, s[0:1]
	global_load_lds_dwordx4 v[96:97], off
	s_mov_b32 m0, s20
	v_readfirstlane_b32 s20, v105
	v_add_u32_e32 v159, 0x5000, v102
	v_lshl_add_u64 v[100:101], v[80:81], 0, s[0:1]
	global_load_lds_dwordx4 v[98:99], off
	s_mov_b32 m0, s20
	v_readfirstlane_b32 s20, v137
	v_lshl_add_u64 v[132:133], v[66:67], 0, s[0:1]
	v_add_u32_e32 v160, 0x6000, v102
	global_load_lds_dwordx4 v[100:101], off
	v_add_u32_e32 v106, v110, v92
	v_add_u32_e32 v128, v136, v92
	s_mov_b32 m0, s20
	v_readfirstlane_b32 s20, v159
	v_lshl_add_u64 v[134:135], v[68:69], 0, s[0:1]
	v_add_u32_e32 v161, 0x7000, v102
	ds_read_b128 v[94:97], v106
	ds_read_b128 v[98:101], v106 offset:2048
	ds_read_b128 v[102:105], v106 offset:4096
	ds_read_b128 v[106:109], v106 offset:6144
	ds_read_b128 v[116:119], v128 offset:16384
	ds_read_b128 v[120:123], v128 offset:18432
	ds_read_b128 v[124:127], v128 offset:20480
	ds_read_b128 v[128:131], v128 offset:22528
	global_load_lds_dwordx4 v[132:133], off
	s_mov_b32 m0, s20
	v_readfirstlane_b32 s20, v160
	v_lshl_add_u64 v[84:85], v[70:71], 0, s[0:1]
	global_load_lds_dwordx4 v[134:135], off
	s_mov_b32 m0, s20
	v_readfirstlane_b32 s20, v161
	v_lshl_add_u64 v[82:83], v[72:73], 0, s[0:1]
	global_load_lds_dwordx4 v[84:85], off
	s_mov_b32 m0, s20
	s_waitcnt lgkmcnt(0)
	v_mfma_f32_16x16x32_bf16 v[30:33], v[116:119], v[102:105], v[30:33]
	global_load_lds_dwordx4 v[82:83], off
	s_add_u32 s0, s0, 0x80
	v_mfma_f32_16x16x32_bf16 v[26:29], v[120:123], v[102:105], v[26:29]
	s_addc_u32 s1, s1, 0
	s_add_i32 s28, s28, 0x8000
	s_cmpk_eq_i32 s0, 0x1580
	v_mfma_f32_16x16x32_bf16 v[22:25], v[124:127], v[102:105], v[22:25]
	v_mfma_f32_16x16x32_bf16 v[18:21], v[128:131], v[102:105], v[18:21]
	v_add_u32_e32 v102, v110, v89
	v_add_u32_e32 v110, v136, v89
	v_mfma_f32_16x16x32_bf16 v[62:65], v[116:119], v[94:97], v[62:65]
	v_mfma_f32_16x16x32_bf16 v[58:61], v[120:123], v[94:97], v[58:61]
	v_mfma_f32_16x16x32_bf16 v[54:57], v[124:127], v[94:97], v[54:57]
	v_mfma_f32_16x16x32_bf16 v[50:53], v[128:131], v[94:97], v[50:53]
	v_mfma_f32_16x16x32_bf16 v[46:49], v[116:119], v[98:101], v[46:49]
	v_mfma_f32_16x16x32_bf16 v[42:45], v[120:123], v[98:101], v[42:45]
	v_mfma_f32_16x16x32_bf16 v[38:41], v[124:127], v[98:101], v[38:41]
	v_mfma_f32_16x16x32_bf16 v[34:37], v[128:131], v[98:101], v[34:37]
	ds_read_b128 v[82:85], v102
	ds_read_b128 v[94:97], v102 offset:2048
	ds_read_b128 v[98:101], v102 offset:4096
	ds_read_b128 v[102:105], v102 offset:6144
	v_mfma_f32_16x16x32_bf16 v[14:17], v[116:119], v[106:109], v[14:17]
	v_mfma_f32_16x16x32_bf16 v[10:13], v[120:123], v[106:109], v[10:13]
	v_mfma_f32_16x16x32_bf16 v[6:9], v[124:127], v[106:109], v[6:9]
	v_mfma_f32_16x16x32_bf16 v[2:5], v[128:131], v[106:109], v[2:5]
	ds_read_b128 v[106:109], v110 offset:16384
	ds_read_b128 v[116:119], v110 offset:18432
	ds_read_b128 v[120:123], v110 offset:20480
	ds_read_b128 v[124:127], v110 offset:22528
	s_waitcnt lgkmcnt(0)
	v_mfma_f32_16x16x32_bf16 v[62:65], v[106:109], v[82:85], v[62:65]
	v_mfma_f32_16x16x32_bf16 v[58:61], v[116:119], v[82:85], v[58:61]
	v_mfma_f32_16x16x32_bf16 v[54:57], v[120:123], v[82:85], v[54:57]
	v_mfma_f32_16x16x32_bf16 v[50:53], v[124:127], v[82:85], v[50:53]
	v_mfma_f32_16x16x32_bf16 v[46:49], v[106:109], v[94:97], v[46:49]
	v_mfma_f32_16x16x32_bf16 v[42:45], v[116:119], v[94:97], v[42:45]
	v_mfma_f32_16x16x32_bf16 v[38:41], v[120:123], v[94:97], v[38:41]
	v_mfma_f32_16x16x32_bf16 v[34:37], v[124:127], v[94:97], v[34:37]
	v_mfma_f32_16x16x32_bf16 v[30:33], v[106:109], v[98:101], v[30:33]
	v_mfma_f32_16x16x32_bf16 v[26:29], v[116:119], v[98:101], v[26:29]
	v_mfma_f32_16x16x32_bf16 v[22:25], v[120:123], v[98:101], v[22:25]
	v_mfma_f32_16x16x32_bf16 v[18:21], v[124:127], v[98:101], v[18:21]
	v_mfma_f32_16x16x32_bf16 v[14:17], v[106:109], v[102:105], v[14:17]
	v_mfma_f32_16x16x32_bf16 v[10:13], v[116:119], v[102:105], v[10:13]
	v_mfma_f32_16x16x32_bf16 v[6:9], v[120:123], v[102:105], v[6:9]
	v_mfma_f32_16x16x32_bf16 v[2:5], v[124:127], v[102:105], v[2:5]
	s_cbranch_scc0 .LBB0_84
	v_add_u32_e32 v90, s29, v93
	v_add_u32_e32 v91, s29, v91
	v_add_u32_e32 v82, v90, v92
	v_add_u32_e32 v92, v91, v92
	s_waitcnt vmcnt(0)
	s_waitcnt vmcnt(0)
	s_barrier
; template <class Epi>
; DI void gemm_tile(const bf16_t* __restrict__ A, int lda, const bf16_t* __restrict__ Bt, int ldb, int K, int row0, int col0, char* lds, const Epi& epi) {
;     ...
;       for (int m = 0; m < 4; ++m) a[m] = *(const bf16x8*)(sa + m * 2048 + co);
; #pragma unroll
;       for (int n = 0; n < 4; ++n) b[n] = *(const bf16x8*)(sb + n * 2048 + co);
; #pragma unroll
;       for (int m = 0; m < 4; ++m)
; #pragma unroll
;         for (int n = 0; n < 4; ++n) acc[m][n] = __builtin_amdgcn_mfma_f32_16x16x32_bf16(b[n], a[m], acc[m][n], 0, 0, 0);
;     }
;   }
;   epi(acc, row0 + wr * 64, col0 + wc * 64, fr, fq);
;   DI void operator()(const f32x4 (&acc)[4][4], int r0, int c0, int fr, int fq) const {
; #pragma unroll
;     for (int m = 0; m < 4; ++m) {
;       const int row = r0 + m * 16 + fr; const int b = row / TB, s = row % TB;
;       const float* src = xsrc_row(*p, from_inputs, b, s);
;       float* dst = xdst_row(*p, b, s);
;       const float* gate = p->MOD + (size_t)(l * 9 + (s < NCTX ? 8 : b)) * 6144 + gate_off;
; #pragma unroll
;       for (int n = 0; n < 4; ++n) {
;         const int col = c0 + n * 16 + fq * 4;
;         f32x4 g = *(const f32x4*)(gate + col), xv = *(const f32x4*)(src + col);
	ds_read_b128 v[66:69], v82 offset:16384
	ds_read_b128 v[74:77], v82 offset:18432
	ds_read_b128 v[70:73], v92
	ds_read_b128 v[78:81], v82 offset:20480
	ds_read_b128 v[82:85], v82 offset:22528
	s_waitcnt lgkmcnt(2)
	v_mfma_f32_16x16x32_bf16 v[62:65], v[66:69], v[70:73], v[62:65]
	v_mfma_f32_16x16x32_bf16 v[58:61], v[74:77], v[70:73], v[58:61]
	s_waitcnt lgkmcnt(1)
	v_mfma_f32_16x16x32_bf16 v[54:57], v[78:81], v[70:73], v[54:57]
	s_waitcnt lgkmcnt(0)
	v_mfma_f32_16x16x32_bf16 v[50:53], v[82:85], v[70:73], v[50:53]
	ds_read_b128 v[70:73], v92 offset:2048
	s_waitcnt lgkmcnt(0)
	v_mfma_f32_16x16x32_bf16 v[46:49], v[66:69], v[70:73], v[46:49]
	v_mfma_f32_16x16x32_bf16 v[42:45], v[74:77], v[70:73], v[42:45]
	v_mfma_f32_16x16x32_bf16 v[38:41], v[78:81], v[70:73], v[38:41]
	v_mfma_f32_16x16x32_bf16 v[34:37], v[82:85], v[70:73], v[34:37]
	ds_read_b128 v[70:73], v92 offset:4096
	s_waitcnt lgkmcnt(0)
	v_mfma_f32_16x16x32_bf16 v[30:33], v[66:69], v[70:73], v[30:33]
	v_mfma_f32_16x16x32_bf16 v[26:29], v[74:77], v[70:73], v[26:29]
	v_mfma_f32_16x16x32_bf16 v[22:25], v[78:81], v[70:73], v[22:25]
	v_mfma_f32_16x16x32_bf16 v[18:21], v[82:85], v[70:73], v[18:21]
	ds_read_b128 v[70:73], v92 offset:6144
	s_waitcnt lgkmcnt(0)
	v_mfma_f32_16x16x32_bf16 v[10:13], v[74:77], v[70:73], v[10:13]
	v_add_u32_e32 v74, v90, v89
	v_add_u32_e32 v75, v91, v89
	ds_read_b128 v[90:93], v74 offset:22528
	v_mfma_f32_16x16x32_bf16 v[14:17], v[66:69], v[70:73], v[14:17]
	ds_read_b128 v[66:69], v74 offset:16384
	ds_read_b128 v[94:97], v75 offset:6144
	v_mfma_f32_16x16x32_bf16 v[6:9], v[78:81], v[70:73], v[6:9]
	ds_read_b128 v[76:79], v74 offset:18432
	v_mfma_f32_16x16x32_bf16 v[2:5], v[82:85], v[70:73], v[2:5]
	ds_read_b128 v[80:83], v74 offset:20480
	ds_read_b128 v[70:73], v75
	s_waitcnt lgkmcnt(0)
	v_mfma_f32_16x16x32_bf16 v[62:65], v[66:69], v[70:73], v[62:65]
	v_mfma_f32_16x16x32_bf16 v[58:61], v[76:79], v[70:73], v[58:61]
	v_mfma_f32_16x16x32_bf16 v[54:57], v[80:83], v[70:73], v[54:57]
	v_mfma_f32_16x16x32_bf16 v[50:53], v[90:93], v[70:73], v[50:53]
	ds_read_b128 v[70:73], v75 offset:2048
	s_waitcnt lgkmcnt(0)
	v_mfma_f32_16x16x32_bf16 v[46:49], v[66:69], v[70:73], v[46:49]
	v_mfma_f32_16x16x32_bf16 v[42:45], v[76:79], v[70:73], v[42:45]
	v_mfma_f32_16x16x32_bf16 v[38:41], v[80:83], v[70:73], v[38:41]
	v_mfma_f32_16x16x32_bf16 v[34:37], v[90:93], v[70:73], v[34:37]
	ds_read_b128 v[70:73], v75 offset:4096
	s_waitcnt lgkmcnt(0)
	v_mfma_f32_16x16x32_bf16 v[30:33], v[66:69], v[70:73], v[30:33]
	v_mfma_f32_16x16x32_bf16 v[26:29], v[76:79], v[70:73], v[26:29]
	v_mfma_f32_16x16x32_bf16 v[22:25], v[80:83], v[70:73], v[22:25]
	v_mfma_f32_16x16x32_bf16 v[18:21], v[90:93], v[70:73], v[18:21]
	v_or_b32_e32 v70, s3, v87
	v_lshl_add_u32 v74, v88, 6, v70
	v_mfma_f32_16x16x32_bf16 v[14:17], v[66:69], v[94:97], v[14:17]
	v_mul_hi_i32 v66, v74, s47
	v_lshrrev_b32_e32 v67, 31, v66
	v_ashrrev_i32_e32 v66, 9, v66
	v_mfma_f32_16x16x32_bf16 v[10:13], v[76:79], v[94:97], v[10:13]
	v_add_u32_e32 v75, v66, v67
	v_mul_i32_i24_e32 v66, 0x900, v75
	v_sub_u32_e32 v71, v74, v66
	v_mfma_f32_16x16x32_bf16 v[6:9], v[80:83], v[94:97], v[6:9]
	v_lshlrev_b32_e32 v67, 11, v75
	v_cmp_lt_i32_e32 vcc, s33, v71
	v_mov_b64_e32 v[68:69], s[64:65]
	v_mfma_f32_16x16x32_bf16 v[2:5], v[90:93], v[94:97], v[2:5]
	v_lshlrev_b32_e32 v1, 6, v1
	v_lshlrev_b32_e32 v67, 2, v86
	v_or3_b32 v80, v1, v67, s2
	v_lshlrev_b32_e32 v66, 2, v80
	v_mov_b32_e32 v67, 0
	v_mov_b32_e32 v100, s64
	v_mov_b32_e32 v101, s65
	v_mov_b32_e32 v102, s56
	v_mov_b32_e32 v103, s57
	s_add_u32 s0, s58, 0x5000
	s_addc_u32 s1, s59, 0
	v_mov_b32_e32 v108, s0
	v_mov_b32_e32 v109, s1
	v_mov_b32_e32 v110, 8
	v_mov_b32_e32 v88, v74
	v_mul_hi_i32 v89, v88, s47
	v_lshrrev_b32_e32 v90, 31, v89
	v_ashrrev_i32_e32 v89, 9, v89
	v_add_u32_e32 v91, v89, v90
	v_mul_i32_i24_e32 v89, 0x900, v91
	v_sub_u32_e32 v92, v88, v89
	v_cmp_lt_i32_e32 vcc, s33, v92
	v_lshlrev_b32_e32 v89, 11, v91
	v_add3_u32 v89, v92, v89, s75
	v_lshl_add_u32 v90, v91, 8, v92
	v_cndmask_b32_e32 v94, v90, v89, vcc
	v_ashrrev_i32_e32 v95, 31, v94
	v_lshlrev_b64 v[96:97], 12, v[94:95]
	v_lshl_add_u64 v[96:97], v[96:97], 0, v[66:67]
	v_cndmask_b32_e32 v98, v100, v102, vcc
	v_cndmask_b32_e32 v99, v101, v103, vcc
	v_lshl_add_u64 v[224:225], v[98:99], 0, v[96:97]
	v_cndmask_b32_e32 v93, v110, v91, vcc
	v_add_u32_e32 v93, s82, v93
	v_mad_i64_i32 v[240:241], s[0:1], v93, s24, v[108:109]
	s_nop 0
	v_lshl_add_u64 v[240:241], v[240:241], 0, v[66:67]
	global_load_dwordx4 v[116:119], v[240:241], off
	global_load_dwordx4 v[120:123], v[240:241], off offset:64
	global_load_dwordx4 v[124:127], v[240:241], off offset:128
	global_load_dwordx4 v[128:131], v[240:241], off offset:192
	global_load_dwordx4 v[160:163], v[224:225], off
	global_load_dwordx4 v[164:167], v[224:225], off offset:64
	global_load_dwordx4 v[168:171], v[224:225], off offset:128
	global_load_dwordx4 v[172:175], v[224:225], off offset:192
	v_or_b32_e32 v88, 16, v74
	v_mul_hi_i32 v89, v88, s47
	v_lshrrev_b32_e32 v90, 31, v89
	v_ashrrev_i32_e32 v89, 9, v89
	v_add_u32_e32 v91, v89, v90
	v_mul_i32_i24_e32 v89, 0x900, v91
	v_sub_u32_e32 v92, v88, v89
	v_cmp_lt_i32_e32 vcc, s33, v92
	v_lshlrev_b32_e32 v89, 11, v91
	v_add3_u32 v89, v92, v89, s75
	v_lshl_add_u32 v90, v91, 8, v92
	v_cndmask_b32_e32 v94, v90, v89, vcc
	v_ashrrev_i32_e32 v95, 31, v94
	v_lshlrev_b64 v[96:97], 12, v[94:95]
	v_lshl_add_u64 v[96:97], v[96:97], 0, v[66:67]
	v_cndmask_b32_e32 v98, v100, v102, vcc
	v_cndmask_b32_e32 v99, v101, v103, vcc
	v_lshl_add_u64 v[226:227], v[98:99], 0, v[96:97]
;   DI void operator()(const f32x4 (&acc)[4][4], int r0, int c0, int fr, int fq) const {
; #pragma unroll
;     for (int m = 0; m < 4; ++m) {
;       const int row = r0 + m * 16 + fr; const int b = row / TB, s = row % TB;
;       const float* src = xsrc_row(*p, from_inputs, b, s);
;       float* dst = xdst_row(*p, b, s);
;       const float* gate = p->MOD + (size_t)(l * 9 + (s < NCTX ? 8 : b)) * 6144 + gate_off;
; #pragma unroll
;       for (int n = 0; n < 4; ++n) {
;         const int col = c0 + n * 16 + fq * 4;
;         f32x4 g = *(const f32x4*)(gate + col), xv = *(const f32x4*)(src + col);
;         *(f32x4*)(dst + col) = xv + g * acc[m][n];
;       }
;     }
	global_load_dwordx4 v[176:179], v[226:227], off
	global_load_dwordx4 v[180:183], v[226:227], off offset:64
	global_load_dwordx4 v[184:187], v[226:227], off offset:128
	global_load_dwordx4 v[188:191], v[226:227], off offset:192
	v_or_b32_e32 v88, 32, v74
	v_mul_hi_i32 v89, v88, s47
	v_lshrrev_b32_e32 v90, 31, v89
	v_ashrrev_i32_e32 v89, 9, v89
	v_add_u32_e32 v91, v89, v90
	v_mul_i32_i24_e32 v89, 0x900, v91
	v_sub_u32_e32 v92, v88, v89
	v_cmp_lt_i32_e32 vcc, s33, v92
	v_lshlrev_b32_e32 v89, 11, v91
	v_add3_u32 v89, v92, v89, s75
	v_lshl_add_u32 v90, v91, 8, v92
	v_cndmask_b32_e32 v94, v90, v89, vcc
	v_ashrrev_i32_e32 v95, 31, v94
	v_lshlrev_b64 v[96:97], 12, v[94:95]
	v_lshl_add_u64 v[96:97], v[96:97], 0, v[66:67]
	v_cndmask_b32_e32 v98, v100, v102, vcc
	v_cndmask_b32_e32 v99, v101, v103, vcc
	v_lshl_add_u64 v[228:229], v[98:99], 0, v[96:97]
	global_load_dwordx4 v[192:195], v[228:229], off
	global_load_dwordx4 v[196:199], v[228:229], off offset:64
	global_load_dwordx4 v[200:203], v[228:229], off offset:128
	global_load_dwordx4 v[204:207], v[228:229], off offset:192
	v_or_b32_e32 v88, 48, v74
	v_mul_hi_i32 v89, v88, s47
	v_lshrrev_b32_e32 v90, 31, v89
	v_ashrrev_i32_e32 v89, 9, v89
	v_add_u32_e32 v91, v89, v90
	v_mul_i32_i24_e32 v89, 0x900, v91
	v_sub_u32_e32 v92, v88, v89
	v_cmp_lt_i32_e32 vcc, s33, v92
	v_lshlrev_b32_e32 v89, 11, v91
	v_add3_u32 v89, v92, v89, s75
	v_lshl_add_u32 v90, v91, 8, v92
	v_cndmask_b32_e32 v94, v90, v89, vcc
	v_ashrrev_i32_e32 v95, 31, v94
	v_lshlrev_b64 v[96:97], 12, v[94:95]
	v_lshl_add_u64 v[96:97], v[96:97], 0, v[66:67]
	v_cndmask_b32_e32 v98, v100, v102, vcc
	v_cndmask_b32_e32 v99, v101, v103, vcc
	v_lshl_add_u64 v[230:231], v[98:99], 0, v[96:97]
	global_load_dwordx4 v[208:211], v[230:231], off
	global_load_dwordx4 v[212:215], v[230:231], off offset:64
	global_load_dwordx4 v[216:219], v[230:231], off offset:128
	global_load_dwordx4 v[220:223], v[230:231], off offset:192
	s_waitcnt vmcnt(15)
	v_pk_fma_f32 v[64:65], v[64:65], v[118:119], v[162:163]
	v_pk_fma_f32 v[62:63], v[62:63], v[116:117], v[160:161]
	global_store_dwordx4 v[224:225], v[62:65], off sc0 sc1
	s_waitcnt vmcnt(15)
	v_pk_fma_f32 v[60:61], v[60:61], v[122:123], v[166:167]
	v_pk_fma_f32 v[58:59], v[58:59], v[120:121], v[164:165]
	global_store_dwordx4 v[224:225], v[58:61], off offset:64 sc0 sc1
	s_waitcnt vmcnt(15)
	v_pk_fma_f32 v[56:57], v[56:57], v[126:127], v[170:171]
	v_pk_fma_f32 v[54:55], v[54:55], v[124:125], v[168:169]
	global_store_dwordx4 v[224:225], v[54:57], off offset:128 sc0 sc1
	s_waitcnt vmcnt(15)
	v_pk_fma_f32 v[52:53], v[52:53], v[130:131], v[174:175]
	v_pk_fma_f32 v[50:51], v[50:51], v[128:129], v[172:173]
	global_store_dwordx4 v[224:225], v[50:53], off offset:192 sc0 sc1
	s_waitcnt vmcnt(15)
	v_pk_fma_f32 v[48:49], v[48:49], v[118:119], v[178:179]
	v_pk_fma_f32 v[46:47], v[46:47], v[116:117], v[176:177]
	global_store_dwordx4 v[226:227], v[46:49], off sc0 sc1
	s_waitcnt vmcnt(15)
	v_pk_fma_f32 v[44:45], v[44:45], v[122:123], v[182:183]
	v_pk_fma_f32 v[42:43], v[42:43], v[120:121], v[180:181]
	global_store_dwordx4 v[226:227], v[42:45], off offset:64 sc0 sc1
	s_waitcnt vmcnt(15)
	v_pk_fma_f32 v[40:41], v[40:41], v[126:127], v[186:187]
	v_pk_fma_f32 v[38:39], v[38:39], v[124:125], v[184:185]
	global_store_dwordx4 v[226:227], v[38:41], off offset:128 sc0 sc1
	s_waitcnt vmcnt(15)
	v_pk_fma_f32 v[36:37], v[36:37], v[130:131], v[190:191]
	v_pk_fma_f32 v[34:35], v[34:35], v[128:129], v[188:189]
	global_store_dwordx4 v[226:227], v[34:37], off offset:192 sc0 sc1
	s_waitcnt vmcnt(15)
	v_pk_fma_f32 v[32:33], v[32:33], v[118:119], v[194:195]
	v_pk_fma_f32 v[30:31], v[30:31], v[116:117], v[192:193]
	global_store_dwordx4 v[228:229], v[30:33], off sc0 sc1
	s_waitcnt vmcnt(15)
	v_pk_fma_f32 v[28:29], v[28:29], v[122:123], v[198:199]
	v_pk_fma_f32 v[26:27], v[26:27], v[120:121], v[196:197]
	global_store_dwordx4 v[228:229], v[26:29], off offset:64 sc0 sc1
	s_waitcnt vmcnt(15)
	v_pk_fma_f32 v[24:25], v[24:25], v[126:127], v[202:203]
	v_pk_fma_f32 v[22:23], v[22:23], v[124:125], v[200:201]
	global_store_dwordx4 v[228:229], v[22:25], off offset:128 sc0 sc1
	s_waitcnt vmcnt(15)
	v_pk_fma_f32 v[20:21], v[20:21], v[130:131], v[206:207]
	v_pk_fma_f32 v[18:19], v[18:19], v[128:129], v[204:205]
	global_store_dwordx4 v[228:229], v[18:21], off offset:192 sc0 sc1
	s_waitcnt vmcnt(15)
	v_pk_fma_f32 v[16:17], v[16:17], v[118:119], v[210:211]
	v_pk_fma_f32 v[14:15], v[14:15], v[116:117], v[208:209]
	global_store_dwordx4 v[230:231], v[14:17], off sc0 sc1
	s_waitcnt vmcnt(15)
	v_pk_fma_f32 v[12:13], v[12:13], v[122:123], v[214:215]
	v_pk_fma_f32 v[10:11], v[10:11], v[120:121], v[212:213]
	global_store_dwordx4 v[230:231], v[10:13], off offset:64 sc0 sc1
	s_waitcnt vmcnt(15)
	v_pk_fma_f32 v[8:9], v[8:9], v[126:127], v[218:219]
	v_pk_fma_f32 v[6:7], v[6:7], v[124:125], v[216:217]
	global_store_dwordx4 v[230:231], v[6:9], off offset:128 sc0 sc1
	s_waitcnt vmcnt(15)
	v_pk_fma_f32 v[4:5], v[4:5], v[130:131], v[222:223]
	v_pk_fma_f32 v[2:3], v[2:3], v[128:129], v[220:221]
	global_store_dwordx4 v[230:231], v[2:5], off offset:192 sc0 sc1
	s_cmp_lg_u32 s77, 9
	s_cbranch_scc1 .Ldep_nosig_k9
	s_waitcnt vmcnt(0)
	s_barrier
	v_readfirstlane_b32 s0, v74
	s_lshr_b32 s0, s0, 7
	s_lshl_b32 s0, s0, 2
	s_add_i32 s0, s0, 0x1e40
	v_mov_b32_e32 v88, s0
	v_mov_b32_e32 v89, 1
	v_cmp_eq_u32_e32 vcc, 0, v138
	s_and_saveexec_b64 s[0:1], vcc
	global_atomic_add v88, v89, s[70:71]
	s_or_b64 exec, exec, s[0:1]
.Ldep_nosig_k9:
	s_add_i32 s27, s27, 1
	s_mov_b64 s[0:1], 0
	s_branch .LBB0_71

; DI void modnorm_rows(const Params& p, int l, int which  , bool from_inputs, bool skip_ctx, int w0, int wstride, int lane) {
;   const float* g = (which ? p.norm2_g : p.norm1_g) + l * DM;
;   f32x4 gg[4];
; #pragma unroll
;   for (int i = 0; i < 4; ++i) gg[i] = *(const f32x4*)(g + i * 256 + lane * 4);
;   const int nrows = skip_ctx ? 8 * NLAT : T_TOK;
;   auto rowof = [&](int i) -> int { return skip_ctx ? (i / NLAT) * TB + NCTX + (i % NLAT) : i; };
;   int i = w0;
;   if (i >= nrows) return;
;   f32x4 vn[4];
;   {
;     const int row = rowof(i); const float* src = xsrc_row(p, from_inputs, row / TB, row % TB);
; #pragma unroll
;     for (int q = 0; q < 4; ++q) vn[q] = *(const f32x4*)(src + q * 256 + lane * 4);
;   }
;   for (; i < nrows; i += wstride) {
;     const int row = rowof(i); const int b = row / TB, s = row % TB;
;     f32x4 v[4];
; #pragma unroll
;     for (int q = 0; q < 4; ++q) v[q] = vn[q];
;     if (i + wstride < nrows) {
;       const int rn = rowof(i + wstride); const float* src = xsrc_row(p, from_inputs, rn / TB, rn % TB);
; #pragma unroll
;       for (int q = 0; q < 4; ++q) vn[q] = *(const f32x4*)(src + q * 256 + lane * 4);
;     }
;     const float* mod = p.MOD + (size_t)(l * 9 + (s < NCTX ? 8 : b)) * 6144 + (which ? 3 * 1024 : 0);
;     f32x4 sh[4], sc[4];
; #pragma unroll
;     for (int q = 0; q < 4; ++q) { sh[q] = *(const f32x4*)(mod + q * 256 + lane * 4); sc[q] = *(const f32x4*)(mod + 1024 + q * 256 + lane * 4); }
.LBB0_228:
	s_andn2_b64 vcc, exec, s[0:1]
	s_cbranch_vccnz .LBB0_249
	v_readlane_b32 s0, v252, 9
	s_nop 1
	v_add_u32_e32 v1, s0, v158
	v_readlane_b32 s0, v250, 4
	v_readlane_b32 s1, v250, 5
	s_and_b64 s[0:1], s[0:1], exec
	s_movk_i32 s0, 0x4800
	s_cselect_b32 s26, 0x4000, s0
	v_cmp_gt_i32_e32 vcc, s26, v1
	s_and_saveexec_b64 s[2:3], vcc
	s_cbranch_execz .LBB0_248
	v_readlane_b32 s0, v252, 9
	v_lshlrev_b32_e32 v244, 4, v115
	v_lshlrev_b32_e32 v245, 3, v115
	v_add_u32_e32 v1, s0, v158
	s_nop 1
	v_readfirstlane_b32 s20, v1
	v_readlane_b32 s4, v254, 42
	v_readlane_b32 s5, v254, 43
	v_readlane_b32 s12, v254, 28
	v_readlane_b32 s13, v254, 29
	v_readlane_b32 s14, v254, 32
	v_readlane_b32 s15, v254, 33
	v_readlane_b32 s16, v253, 40
	v_readlane_b32 s17, v253, 41
	v_readlane_b32 s18, v250, 4
	v_readlane_b32 s19, v250, 5
	s_nop 3
	s_lshl_b32 s0, s49, 12
	s_add_u32 s4, s4, s0
	s_addc_u32 s5, s5, 0
	global_load_dwordx4 v[2:5], v244, s[4:5]
	global_load_dwordx4 v[6:9], v244, s[4:5] offset:1024
	global_load_dwordx4 v[10:13], v244, s[4:5] offset:2048
	global_load_dwordx4 v[14:17], v244, s[4:5] offset:3072
	s_mov_b32 s12, s56
	s_mov_b32 s13, s57
	s_mov_b32 s14, s64
	s_mov_b32 s15, s65
	s_cmp_lg_u64 s[18:19], 0
	s_cbranch_scc1 .Lnorm2_last
	s_mov_b32 s36, 0
	s_lshr_b32 s37, s20, 7
	s_and_b32 s37, s37, 15
	s_add_i32 s37, s37, 2
	s_lshr_b32 s37, s37, 1
	s_add_i32 s37, s37, 1
	s_cmp_ge_u32 s37, 9
	s_cselect_b32 s38, 9, 0
	s_sub_i32 s37, s37, s38
	s_add_i32 s6, s37, 0
	s_cmp_ge_u32 s6, 9
	s_cselect_b32 s38, 9, 0
	s_sub_i32 s6, s6, s38
	s_lshl_b32 s6, s6, 11
	s_add_i32 s6, s6, s20
	s_lshr_b32 s6, s6, 7
	s_lshl_b32 s6, s6, 2
	s_add_i32 s6, s6, 0x1c00
	v_mov_b32_e32 v110, s6
	global_load_dword v114, v110, s[70:71] sc1
	s_add_i32 s6, s37, 1
	s_cmp_ge_u32 s6, 9
	s_cselect_b32 s38, 9, 0
	s_sub_i32 s6, s6, s38
	s_lshl_b32 s6, s6, 11
	s_add_i32 s6, s6, s20
	s_lshr_b32 s6, s6, 7
	s_lshl_b32 s6, s6, 2
	s_add_i32 s6, s6, 0x1c00
	v_mov_b32_e32 v110, s6
	global_load_dword v116, v110, s[70:71] sc1
	s_add_i32 s6, s37, 2
	s_cmp_ge_u32 s6, 9
	s_cselect_b32 s38, 9, 0
	s_sub_i32 s6, s6, s38
	s_lshl_b32 s6, s6, 11
	s_add_i32 s6, s6, s20
	s_lshr_b32 s6, s6, 7
	s_lshl_b32 s6, s6, 2
	s_add_i32 s6, s6, 0x1c00
	v_mov_b32_e32 v110, s6
	global_load_dword v117, v110, s[70:71] sc1
	s_waitcnt vmcnt(2)
	v_readfirstlane_b32 s6, v114
	s_cmp_ge_u32 s6, 8
	s_cbranch_scc1 .Ldep_norm2a_ok0
	s_add_i32 s6, s37, 0
	s_cmp_ge_u32 s6, 9
	s_cselect_b32 s38, 9, 0
	s_sub_i32 s6, s6, s38
	s_lshl_b32 s6, s6, 11
	s_add_i32 s6, s6, s20
	s_lshr_b32 s6, s6, 7
	s_lshl_b32 s6, s6, 2
	s_add_i32 s6, s6, 0x1c00
	v_mov_b32_e32 v110, s6
.Ldep_norm2a_sp0:
	s_cmp_gt_u32 s36, 0x4000
	s_cbranch_scc1 .Ldep_norm2a_ok0
	s_sleep 8
	global_load_dword v114, v110, s[70:71] sc1
	s_waitcnt vmcnt(0)
	v_readfirstlane_b32 s6, v114
	s_add_i32 s36, s36, 1
	s_cmp_ge_u32 s6, 8
	s_cbranch_scc0 .Ldep_norm2a_sp0
.Ldep_norm2a_ok0:
	s_waitcnt vmcnt(1)
	v_readfirstlane_b32 s6, v116
	s_cmp_ge_u32 s6, 8
	s_cbranch_scc1 .Ldep_norm2a_ok1
	s_add_i32 s6, s37, 1
	s_cmp_ge_u32 s6, 9
	s_cselect_b32 s38, 9, 0
	s_sub_i32 s6, s6, s38
	s_lshl_b32 s6, s6, 11
	s_add_i32 s6, s6, s20
	s_lshr_b32 s6, s6, 7
	s_lshl_b32 s6, s6, 2
	s_add_i32 s6, s6, 0x1c00
	v_mov_b32_e32 v110, s6
.Ldep_norm2a_sp1:
	s_cmp_gt_u32 s36, 0x4000
	s_cbranch_scc1 .Ldep_norm2a_ok1
	s_sleep 8
	global_load_dword v116, v110, s[70:71] sc1
	s_waitcnt vmcnt(0)
	v_readfirstlane_b32 s6, v116
	s_add_i32 s36, s36, 1
	s_cmp_ge_u32 s6, 8
	s_cbranch_scc0 .Ldep_norm2a_sp1
.Ldep_norm2a_ok1:
	s_waitcnt vmcnt(0)
	v_readfirstlane_b32 s6, v117
	s_cmp_ge_u32 s6, 8
	s_cbranch_scc1 .Ldep_norm2a_ok2
	s_add_i32 s6, s37, 2
	s_cmp_ge_u32 s6, 9
	s_cselect_b32 s38, 9, 0
	s_sub_i32 s6, s6, s38
	s_lshl_b32 s6, s6, 11
	s_add_i32 s6, s6, s20
	s_lshr_b32 s6, s6, 7
	s_lshl_b32 s6, s6, 2
	s_add_i32 s6, s6, 0x1c00
	v_mov_b32_e32 v110, s6
.Ldep_norm2a_sp2:
	s_cmp_gt_u32 s36, 0x4000
	s_cbranch_scc1 .Ldep_norm2a_ok2
	s_sleep 8
	global_load_dword v117, v110, s[70:71] sc1
	s_waitcnt vmcnt(0)
	v_readfirstlane_b32 s6, v117
	s_add_i32 s36, s36, 1
	s_cmp_ge_u32 s6, 8
	s_cbranch_scc0 .Ldep_norm2a_sp2
.Ldep_norm2a_ok2:
	s_add_i32 s21, s37, 0
	s_cmp_ge_u32 s21, 9
	s_cselect_b32 s38, 9, 0
	s_sub_i32 s21, s21, s38
	s_lshl_b32 s21, s21, 11
	s_add_i32 s21, s21, s20
	s_mul_hi_u32 s7, s21, 0x38e38e39
	s_lshr_b32 s7, s7, 9
	s_mul_i32 s8, s7, 0x900
	s_sub_i32 s8, s21, s8
	s_lshl_b32 s9, s7, 11
	s_add_i32 s9, s9, s8
	s_add_i32 s9, s9, 0xffffff00
	s_lshl_b32 s10, s7, 8
	s_add_i32 s10, s10, s8
	s_cmpk_gt_i32 s8, 0xff
	s_cselect_b32 s9, s9, s10
	s_cselect_b32 s26, s12, s14
	s_cselect_b32 s27, s13, s15
	s_cselect_b32 s10, s7, 8
	s_lshl_b32 s9, s9, 12
	s_add_u32 s26, s26, s9
	s_addc_u32 s27, s27, 0
	s_add_i32 s10, s10, s82
	s_mul_i32 s10, s10, s24
	s_add_u32 s28, s58, s10
	s_addc_u32 s29, s59, 0
	s_add_u32 s28, s28, 0x3000
	s_addc_u32 s29, s29, 0
	s_add_u32 s0, s28, 0x1000
	s_addc_u32 s1, s29, 0
	global_load_dwordx4 v[18:21], v244, s[26:27] sc0 sc1
	global_load_dwordx4 v[22:25], v244, s[26:27] offset:1024 sc0 sc1
	global_load_dwordx4 v[26:29], v244, s[26:27] offset:2048 sc0 sc1
	global_load_dwordx4 v[30:33], v244, s[26:27] offset:3072 sc0 sc1
	global_load_dwordx4 v[34:37], v244, s[28:29]
	global_load_dwordx4 v[38:41], v244, s[28:29] offset:1024
	global_load_dwordx4 v[42:45], v244, s[28:29] offset:2048
	global_load_dwordx4 v[46:49], v244, s[28:29] offset:3072
	global_load_dwordx4 v[50:53], v244, s[0:1]
	global_load_dwordx4 v[54:57], v244, s[0:1] offset:1024
	global_load_dwordx4 v[58:61], v244, s[0:1] offset:2048
	global_load_dwordx4 v[62:65], v244, s[0:1] offset:3072
	s_add_i32 s21, s37, 1
	s_cmp_ge_u32 s21, 9
	s_cselect_b32 s38, 9, 0
; DI unsigned pk_bf16(float lo, float hi) { f32x2 v = {lo, hi}; bf16v2 b = __builtin_convertvector(v, bf16v2); return __builtin_bit_cast(unsigned, b); }
; DI float red64(float x) { for (int o = 32; o > 0; o >>= 1) x += __shfl_xor(x, o); return x; }
; DI void modnorm_rows(const Params& p, int l, int which  , bool from_inputs, bool skip_ctx, int w0, int wstride, int lane) {
;     ...
;   for (; i < nrows; i += wstride) {
;     const int row = rowof(i); const int b = row / TB, s = row % TB;
;     f32x4 v[4];
; #pragma unroll
;     for (int q = 0; q < 4; ++q) v[q] = vn[q];
;     if (i + wstride < nrows) {
;       const int rn = rowof(i + wstride); const float* src = xsrc_row(p, from_inputs, rn / TB, rn % TB);
; #pragma unroll
;       for (int q = 0; q < 4; ++q) vn[q] = *(const f32x4*)(src + q * 256 + lane * 4);
;     }
;     const float* mod = p.MOD + (size_t)(l * 9 + (s < NCTX ? 8 : b)) * 6144 + (which ? 3 * 1024 : 0);
;     f32x4 sh[4], sc[4];
; #pragma unroll
;     for (int q = 0; q < 4; ++q) { sh[q] = *(const f32x4*)(mod + q * 256 + lane * 4); sc[q] = *(const f32x4*)(mod + 1024 + q * 256 + lane * 4); }
;     float ss = 0.f;
; #pragma unroll
;     for (int q = 0; q < 4; ++q) ss += v[q][0] * v[q][0] + v[q][1] * v[q][1] + v[q][2] * v[q][2] + v[q][3] * v[q][3];
;     ss = red64(ss);
;     const float rs = rsqrtf(ss * (1.f / 1024.f) + EPSF);
;     bf16_t* dst = p.HY + (size_t)row * DM;
; #pragma unroll
;     for (int q = 0; q < 4; ++q) {
;       float o[4];
; #pragma unroll
;       for (int j = 0; j < 4; ++j) o[j] = (v[q][j] * rs * gg[q][j]) * (1.f + sc[q][j]) + sh[q][j];
;       u32x2 w = {pk_bf16(o[0], o[1]), pk_bf16(o[2], o[3])};
;       *(u32x2*)(dst + q * 256 + lane * 4) = w;
;     }
	s_sub_i32 s21, s21, s38
	s_lshl_b32 s21, s21, 11
	s_add_i32 s21, s21, s20
	s_mul_hi_u32 s7, s21, 0x38e38e39
	s_lshr_b32 s7, s7, 9
	s_mul_i32 s8, s7, 0x900
	s_sub_i32 s8, s21, s8
	s_lshl_b32 s9, s7, 11
	s_add_i32 s9, s9, s8
	s_add_i32 s9, s9, 0xffffff00
	s_lshl_b32 s10, s7, 8
	s_add_i32 s10, s10, s8
	s_cmpk_gt_i32 s8, 0xff
	s_cselect_b32 s9, s9, s10
	s_cselect_b32 s26, s12, s14
	s_cselect_b32 s27, s13, s15
	s_cselect_b32 s10, s7, 8
	s_lshl_b32 s9, s9, 12
	s_add_u32 s26, s26, s9
	s_addc_u32 s27, s27, 0
	s_add_i32 s10, s10, s82
	s_mul_i32 s10, s10, s24
	s_add_u32 s28, s58, s10
	s_addc_u32 s29, s59, 0
	s_add_u32 s28, s28, 0x3000
	s_addc_u32 s29, s29, 0
	s_add_u32 s0, s28, 0x1000
	s_addc_u32 s1, s29, 0
	global_load_dwordx4 v[66:69], v244, s[26:27] sc0 sc1
	global_load_dwordx4 v[70:73], v244, s[26:27] offset:1024 sc0 sc1
	global_load_dwordx4 v[74:77], v244, s[26:27] offset:2048 sc0 sc1
	global_load_dwordx4 v[78:81], v244, s[26:27] offset:3072 sc0 sc1
	global_load_dwordx4 v[82:85], v244, s[28:29]
	global_load_dwordx4 v[86:89], v244, s[28:29] offset:1024
	global_load_dwordx4 v[90:93], v244, s[28:29] offset:2048
	global_load_dwordx4 v[94:97], v244, s[28:29] offset:3072
	global_load_dwordx4 v[98:101], v244, s[0:1]
	global_load_dwordx4 v[102:105], v244, s[0:1] offset:1024
	global_load_dwordx4 v[106:109], v244, s[0:1] offset:2048
	global_load_dwordx4 v[118:121], v244, s[0:1] offset:3072
	s_add_i32 s21, s37, 2
	s_cmp_ge_u32 s21, 9
	s_cselect_b32 s38, 9, 0
	s_sub_i32 s21, s21, s38
	s_lshl_b32 s21, s21, 11
	s_add_i32 s21, s21, s20
	s_mul_hi_u32 s7, s21, 0x38e38e39
	s_lshr_b32 s7, s7, 9
	s_mul_i32 s8, s7, 0x900
	s_sub_i32 s8, s21, s8
	s_lshl_b32 s9, s7, 11
	s_add_i32 s9, s9, s8
	s_add_i32 s9, s9, 0xffffff00
	s_lshl_b32 s10, s7, 8
	s_add_i32 s10, s10, s8
	s_cmpk_gt_i32 s8, 0xff
	s_cselect_b32 s9, s9, s10
	s_cselect_b32 s26, s12, s14
	s_cselect_b32 s27, s13, s15
	s_cselect_b32 s10, s7, 8
	s_lshl_b32 s9, s9, 12
	s_add_u32 s26, s26, s9
	s_addc_u32 s27, s27, 0
	s_add_i32 s10, s10, s82
	s_mul_i32 s10, s10, s24
	s_add_u32 s28, s58, s10
	s_addc_u32 s29, s59, 0
	s_add_u32 s28, s28, 0x3000
	s_addc_u32 s29, s29, 0
	s_add_u32 s0, s28, 0x1000
	s_addc_u32 s1, s29, 0
	global_load_dwordx4 v[122:125], v244, s[26:27] sc0 sc1
	global_load_dwordx4 v[126:129], v244, s[26:27] offset:1024 sc0 sc1
	global_load_dwordx4 v[130:133], v244, s[26:27] offset:2048 sc0 sc1
	global_load_dwordx4 v[134:137], v244, s[26:27] offset:3072 sc0 sc1
	global_load_dwordx4 v[160:163], v244, s[28:29]
	global_load_dwordx4 v[164:167], v244, s[28:29] offset:1024
	global_load_dwordx4 v[168:171], v244, s[28:29] offset:2048
	global_load_dwordx4 v[172:175], v244, s[28:29] offset:3072
	global_load_dwordx4 v[176:179], v244, s[0:1]
	global_load_dwordx4 v[180:183], v244, s[0:1] offset:1024
	global_load_dwordx4 v[184:187], v244, s[0:1] offset:2048
	global_load_dwordx4 v[188:191], v244, s[0:1] offset:3072
	s_add_i32 s6, s37, 3
	s_cmp_ge_u32 s6, 9
	s_cselect_b32 s38, 9, 0
	s_sub_i32 s6, s6, s38
	s_lshl_b32 s6, s6, 11
	s_add_i32 s6, s6, s20
	s_lshr_b32 s6, s6, 7
	s_lshl_b32 s6, s6, 2
	s_add_i32 s6, s6, 0x1c00
	v_mov_b32_e32 v110, s6
	global_load_dword v114, v110, s[70:71] sc1
	s_waitcnt vmcnt(25)
	v_pk_mul_f32 v[246:247], v[18:19], v[18:19]
	v_pk_fma_f32 v[246:247], v[20:21], v[20:21], v[246:247]
	v_pk_fma_f32 v[246:247], v[22:23], v[22:23], v[246:247]
	v_pk_fma_f32 v[246:247], v[24:25], v[24:25], v[246:247]
	v_pk_fma_f32 v[246:247], v[26:27], v[26:27], v[246:247]
	v_pk_fma_f32 v[246:247], v[28:29], v[28:29], v[246:247]
	v_pk_fma_f32 v[246:247], v[30:31], v[30:31], v[246:247]
	v_pk_fma_f32 v[246:247], v[32:33], v[32:33], v[246:247]
	s_nop 0
	v_add_f32_e32 v246, v246, v247
	s_nop 1
	v_add_f32_dpp v246, v246, v246 quad_perm:[1,0,3,2] row_mask:0xf bank_mask:0xf
	s_nop 1
	v_add_f32_dpp v246, v246, v246 quad_perm:[2,3,0,1] row_mask:0xf bank_mask:0xf
	s_nop 1
	v_add_f32_dpp v246, v246, v246 row_half_mirror row_mask:0xf bank_mask:0xf
	s_nop 1
	v_add_f32_dpp v246, v246, v246 row_mirror row_mask:0xf bank_mask:0xf
	s_nop 1
	v_add_f32_dpp v246, v246, v246 row_bcast:15 row_mask:0xa bank_mask:0xf
	s_nop 1
	v_add_f32_dpp v246, v246, v246 row_bcast:31 row_mask:0xc bank_mask:0xf
	s_nop 1
	v_readlane_b32 s0, v246, 63
	s_add_i32 s21, s37, 0
	s_cmp_ge_u32 s21, 9
	s_cselect_b32 s38, 9, 0
	s_sub_i32 s21, s21, s38
	s_lshl_b32 s21, s21, 11
	s_add_i32 s21, s21, s20
	s_lshl_b32 s21, s21, 11
	s_add_u32 s10, s16, s21
	s_addc_u32 s11, s17, 0
	v_mov_b32_e32 v248, s0
	v_fmamk_f32 v248, v248, 0x3a800000, v143
	v_rsq_f32_e32 v248, v248
	s_nop 0
	v_pk_mul_f32 v[18:19], v[18:19], v[248:249] op_sel_hi:[1,0]
	v_pk_add_f32 v[50:51], v[50:51], 1.0 op_sel_hi:[1,0]
	v_pk_mul_f32 v[18:19], v[2:3], v[18:19]
	v_pk_fma_f32 v[18:19], v[50:51], v[18:19], v[34:35]
	v_pk_mul_f32 v[20:21], v[20:21], v[248:249] op_sel_hi:[1,0]
	v_pk_add_f32 v[52:53], v[52:53], 1.0 op_sel_hi:[1,0]
	v_pk_mul_f32 v[20:21], v[4:5], v[20:21]
	v_pk_fma_f32 v[20:21], v[52:53], v[20:21], v[36:37]
	v_cvt_pk_bf16_f32 v34, v18, v19
	v_cvt_pk_bf16_f32 v35, v20, v21
	global_store_dwordx2 v245, v[34:35], s[10:11]
	v_pk_mul_f32 v[22:23], v[22:23], v[248:249] op_sel_hi:[1,0]
	v_pk_add_f32 v[54:55], v[54:55], 1.0 op_sel_hi:[1,0]
	v_pk_mul_f32 v[22:23], v[6:7], v[22:23]
	v_pk_fma_f32 v[22:23], v[54:55], v[22:23], v[38:39]
	v_pk_mul_f32 v[24:25], v[24:25], v[248:249] op_sel_hi:[1,0]
	v_pk_add_f32 v[56:57], v[56:57], 1.0 op_sel_hi:[1,0]
	v_pk_mul_f32 v[24:25], v[8:9], v[24:25]
	v_pk_fma_f32 v[24:25], v[56:57], v[24:25], v[40:41]
	v_cvt_pk_bf16_f32 v38, v22, v23
	v_cvt_pk_bf16_f32 v39, v24, v25
	global_store_dwordx2 v245, v[38:39], s[10:11] offset:512
	v_pk_mul_f32 v[26:27], v[26:27], v[248:249] op_sel_hi:[1,0]
	v_pk_add_f32 v[58:59], v[58:59], 1.0 op_sel_hi:[1,0]
	v_pk_mul_f32 v[26:27], v[10:11], v[26:27]
	v_pk_fma_f32 v[26:27], v[58:59], v[26:27], v[42:43]
	v_pk_mul_f32 v[28:29], v[28:29], v[248:249] op_sel_hi:[1,0]
	v_pk_add_f32 v[60:61], v[60:61], 1.0 op_sel_hi:[1,0]
	v_pk_mul_f32 v[28:29], v[12:13], v[28:29]
	v_pk_fma_f32 v[28:29], v[60:61], v[28:29], v[44:45]
	v_cvt_pk_bf16_f32 v42, v26, v27
	v_cvt_pk_bf16_f32 v43, v28, v29
	global_store_dwordx2 v245, v[42:43], s[10:11] offset:1024
	v_pk_mul_f32 v[30:31], v[30:31], v[248:249] op_sel_hi:[1,0]
	v_pk_add_f32 v[62:63], v[62:63], 1.0 op_sel_hi:[1,0]
	v_pk_mul_f32 v[30:31], v[14:15], v[30:31]
	v_pk_fma_f32 v[30:31], v[62:63], v[30:31], v[46:47]
	v_pk_mul_f32 v[32:33], v[32:33], v[248:249] op_sel_hi:[1,0]
	v_pk_add_f32 v[64:65], v[64:65], 1.0 op_sel_hi:[1,0]
	v_pk_mul_f32 v[32:33], v[16:17], v[32:33]
	v_pk_fma_f32 v[32:33], v[64:65], v[32:33], v[48:49]
	v_cvt_pk_bf16_f32 v46, v30, v31
	v_cvt_pk_bf16_f32 v47, v32, v33
	global_store_dwordx2 v245, v[46:47], s[10:11] offset:1536
	s_waitcnt vmcnt(4)
	v_readfirstlane_b32 s6, v114
	s_cmp_ge_u32 s6, 8
	s_cbranch_scc1 .Ldep_norm2a_ok3
	s_add_i32 s6, s37, 3
	s_cmp_ge_u32 s6, 9
	s_cselect_b32 s38, 9, 0
	s_sub_i32 s6, s6, s38
	s_lshl_b32 s6, s6, 11
	s_add_i32 s6, s6, s20
	s_lshr_b32 s6, s6, 7
	s_lshl_b32 s6, s6, 2
	s_add_i32 s6, s6, 0x1c00
	v_mov_b32_e32 v110, s6

; DI unsigned pk_bf16(float lo, float hi) { f32x2 v = {lo, hi}; bf16v2 b = __builtin_convertvector(v, bf16v2); return __builtin_bit_cast(unsigned, b); }
; DI float red64(float x) { for (int o = 32; o > 0; o >>= 1) x += __shfl_xor(x, o); return x; }
; DI void modnorm_rows(const Params& p, int l, int which  , bool from_inputs, bool skip_ctx, int w0, int wstride, int lane) {
;     ...
;   for (; i < nrows; i += wstride) {
;     const int row = rowof(i); const int b = row / TB, s = row % TB;
;     f32x4 v[4];
; #pragma unroll
;     for (int q = 0; q < 4; ++q) v[q] = vn[q];
;     if (i + wstride < nrows) {
;       const int rn = rowof(i + wstride); const float* src = xsrc_row(p, from_inputs, rn / TB, rn % TB);
; #pragma unroll
;       for (int q = 0; q < 4; ++q) vn[q] = *(const f32x4*)(src + q * 256 + lane * 4);
;     }
;     const float* mod = p.MOD + (size_t)(l * 9 + (s < NCTX ? 8 : b)) * 6144 + (which ? 3 * 1024 : 0);
;     f32x4 sh[4], sc[4];
; #pragma unroll
;     for (int q = 0; q < 4; ++q) { sh[q] = *(const f32x4*)(mod + q * 256 + lane * 4); sc[q] = *(const f32x4*)(mod + 1024 + q * 256 + lane * 4); }
;     float ss = 0.f;
; #pragma unroll
;     for (int q = 0; q < 4; ++q) ss += v[q][0] * v[q][0] + v[q][1] * v[q][1] + v[q][2] * v[q][2] + v[q][3] * v[q][3];
;     ss = red64(ss);
;     const float rs = rsqrtf(ss * (1.f / 1024.f) + EPSF);
;     bf16_t* dst = p.HY + (size_t)row * DM;
; #pragma unroll
;     for (int q = 0; q < 4; ++q) {
;       float o[4];
; #pragma unroll
;       for (int j = 0; j < 4; ++j) o[j] = (v[q][j] * rs * gg[q][j]) * (1.f + sc[q][j]) + sh[q][j];
;       u32x2 w = {pk_bf16(o[0], o[1]), pk_bf16(o[2], o[3])};
;       *(u32x2*)(dst + q * 256 + lane * 4) = w;
;     }
.Ldep_norm2a_ok3:
	s_add_i32 s21, s37, 3
	s_cmp_ge_u32 s21, 9
	s_cselect_b32 s38, 9, 0
	s_sub_i32 s21, s21, s38
	s_lshl_b32 s21, s21, 11
	s_add_i32 s21, s21, s20
	s_mul_hi_u32 s7, s21, 0x38e38e39
	s_lshr_b32 s7, s7, 9
	s_mul_i32 s8, s7, 0x900
	s_sub_i32 s8, s21, s8
	s_lshl_b32 s9, s7, 11
	s_add_i32 s9, s9, s8
	s_add_i32 s9, s9, 0xffffff00
	s_lshl_b32 s10, s7, 8
	s_add_i32 s10, s10, s8
	s_cmpk_gt_i32 s8, 0xff
	s_cselect_b32 s9, s9, s10
	s_cselect_b32 s26, s12, s14
	s_cselect_b32 s27, s13, s15
	s_cselect_b32 s10, s7, 8
	s_lshl_b32 s9, s9, 12
	s_add_u32 s26, s26, s9
	s_addc_u32 s27, s27, 0
	s_add_i32 s10, s10, s82
	s_mul_i32 s10, s10, s24
	s_add_u32 s28, s58, s10
	s_addc_u32 s29, s59, 0
	s_add_u32 s28, s28, 0x3000
	s_addc_u32 s29, s29, 0
	s_add_u32 s0, s28, 0x1000
	s_addc_u32 s1, s29, 0
	global_load_dwordx4 v[18:21], v244, s[26:27] sc0 sc1
	global_load_dwordx4 v[22:25], v244, s[26:27] offset:1024 sc0 sc1
	global_load_dwordx4 v[26:29], v244, s[26:27] offset:2048 sc0 sc1
	global_load_dwordx4 v[30:33], v244, s[26:27] offset:3072 sc0 sc1
	global_load_dwordx4 v[34:37], v244, s[28:29]
	global_load_dwordx4 v[38:41], v244, s[28:29] offset:1024
	global_load_dwordx4 v[42:45], v244, s[28:29] offset:2048
	global_load_dwordx4 v[46:49], v244, s[28:29] offset:3072
	global_load_dwordx4 v[50:53], v244, s[0:1]
	global_load_dwordx4 v[54:57], v244, s[0:1] offset:1024
	global_load_dwordx4 v[58:61], v244, s[0:1] offset:2048
	global_load_dwordx4 v[62:65], v244, s[0:1] offset:3072
	s_add_i32 s6, s37, 4
	s_cmp_ge_u32 s6, 9
	s_cselect_b32 s38, 9, 0
	s_sub_i32 s6, s6, s38
	s_lshl_b32 s6, s6, 11
	s_add_i32 s6, s6, s20
	s_lshr_b32 s6, s6, 7
	s_lshl_b32 s6, s6, 2
	s_add_i32 s6, s6, 0x1c00
	v_mov_b32_e32 v110, s6
	global_load_dword v114, v110, s[70:71] sc1
	s_waitcnt vmcnt(30)
	v_pk_mul_f32 v[246:247], v[66:67], v[66:67]
	v_pk_fma_f32 v[246:247], v[68:69], v[68:69], v[246:247]
	v_pk_fma_f32 v[246:247], v[70:71], v[70:71], v[246:247]
	v_pk_fma_f32 v[246:247], v[72:73], v[72:73], v[246:247]
	v_pk_fma_f32 v[246:247], v[74:75], v[74:75], v[246:247]
	v_pk_fma_f32 v[246:247], v[76:77], v[76:77], v[246:247]
	v_pk_fma_f32 v[246:247], v[78:79], v[78:79], v[246:247]
	v_pk_fma_f32 v[246:247], v[80:81], v[80:81], v[246:247]
	s_nop 0
	v_add_f32_e32 v246, v246, v247
	s_nop 1
	v_add_f32_dpp v246, v246, v246 quad_perm:[1,0,3,2] row_mask:0xf bank_mask:0xf
	s_nop 1
	v_add_f32_dpp v246, v246, v246 quad_perm:[2,3,0,1] row_mask:0xf bank_mask:0xf
	s_nop 1
	v_add_f32_dpp v246, v246, v246 row_half_mirror row_mask:0xf bank_mask:0xf
	s_nop 1
	v_add_f32_dpp v246, v246, v246 row_mirror row_mask:0xf bank_mask:0xf
	s_nop 1
	v_add_f32_dpp v246, v246, v246 row_bcast:15 row_mask:0xa bank_mask:0xf
	s_nop 1
	v_add_f32_dpp v246, v246, v246 row_bcast:31 row_mask:0xc bank_mask:0xf
	s_nop 1
	v_readlane_b32 s0, v246, 63
	s_add_i32 s21, s37, 1
	s_cmp_ge_u32 s21, 9
	s_cselect_b32 s38, 9, 0
	s_sub_i32 s21, s21, s38
	s_lshl_b32 s21, s21, 11
	s_add_i32 s21, s21, s20
	s_lshl_b32 s21, s21, 11
	s_add_u32 s10, s16, s21
	s_addc_u32 s11, s17, 0
	v_mov_b32_e32 v248, s0
	v_fmamk_f32 v248, v248, 0x3a800000, v143
	v_rsq_f32_e32 v248, v248
	s_nop 0
	v_pk_mul_f32 v[66:67], v[66:67], v[248:249] op_sel_hi:[1,0]
	v_pk_add_f32 v[98:99], v[98:99], 1.0 op_sel_hi:[1,0]
	v_pk_mul_f32 v[66:67], v[2:3], v[66:67]
	v_pk_fma_f32 v[66:67], v[98:99], v[66:67], v[82:83]
	v_pk_mul_f32 v[68:69], v[68:69], v[248:249] op_sel_hi:[1,0]
	v_pk_add_f32 v[100:101], v[100:101], 1.0 op_sel_hi:[1,0]
	v_pk_mul_f32 v[68:69], v[4:5], v[68:69]
	v_pk_fma_f32 v[68:69], v[100:101], v[68:69], v[84:85]
	v_cvt_pk_bf16_f32 v82, v66, v67
	v_cvt_pk_bf16_f32 v83, v68, v69
	global_store_dwordx2 v245, v[82:83], s[10:11]
	v_pk_mul_f32 v[70:71], v[70:71], v[248:249] op_sel_hi:[1,0]
	v_pk_add_f32 v[102:103], v[102:103], 1.0 op_sel_hi:[1,0]
	v_pk_mul_f32 v[70:71], v[6:7], v[70:71]
	v_pk_fma_f32 v[70:71], v[102:103], v[70:71], v[86:87]
	v_pk_mul_f32 v[72:73], v[72:73], v[248:249] op_sel_hi:[1,0]
	v_pk_add_f32 v[104:105], v[104:105], 1.0 op_sel_hi:[1,0]
	v_pk_mul_f32 v[72:73], v[8:9], v[72:73]
	v_pk_fma_f32 v[72:73], v[104:105], v[72:73], v[88:89]
	v_cvt_pk_bf16_f32 v86, v70, v71
	v_cvt_pk_bf16_f32 v87, v72, v73
	global_store_dwordx2 v245, v[86:87], s[10:11] offset:512
	v_pk_mul_f32 v[74:75], v[74:75], v[248:249] op_sel_hi:[1,0]
	v_pk_add_f32 v[106:107], v[106:107], 1.0 op_sel_hi:[1,0]
	v_pk_mul_f32 v[74:75], v[10:11], v[74:75]
	v_pk_fma_f32 v[74:75], v[106:107], v[74:75], v[90:91]
	v_pk_mul_f32 v[76:77], v[76:77], v[248:249] op_sel_hi:[1,0]
	v_pk_add_f32 v[108:109], v[108:109], 1.0 op_sel_hi:[1,0]
	v_pk_mul_f32 v[76:77], v[12:13], v[76:77]
	v_pk_fma_f32 v[76:77], v[108:109], v[76:77], v[92:93]
	v_cvt_pk_bf16_f32 v90, v74, v75
	v_cvt_pk_bf16_f32 v91, v76, v77
	global_store_dwordx2 v245, v[90:91], s[10:11] offset:1024
	v_pk_mul_f32 v[78:79], v[78:79], v[248:249] op_sel_hi:[1,0]
	v_pk_add_f32 v[118:119], v[118:119], 1.0 op_sel_hi:[1,0]
	v_pk_mul_f32 v[78:79], v[14:15], v[78:79]
	v_pk_fma_f32 v[78:79], v[118:119], v[78:79], v[94:95]
	v_pk_mul_f32 v[80:81], v[80:81], v[248:249] op_sel_hi:[1,0]
	v_pk_add_f32 v[120:121], v[120:121], 1.0 op_sel_hi:[1,0]
	v_pk_mul_f32 v[80:81], v[16:17], v[80:81]
	v_pk_fma_f32 v[80:81], v[120:121], v[80:81], v[96:97]
	v_cvt_pk_bf16_f32 v94, v78, v79
	v_cvt_pk_bf16_f32 v95, v80, v81
	global_store_dwordx2 v245, v[94:95], s[10:11] offset:1536
	s_waitcnt vmcnt(4)
	v_readfirstlane_b32 s6, v114
	s_cmp_ge_u32 s6, 8
	s_cbranch_scc1 .Ldep_norm2a_ok4
	s_add_i32 s6, s37, 4
	s_cmp_ge_u32 s6, 9
	s_cselect_b32 s38, 9, 0
	s_sub_i32 s6, s6, s38
	s_lshl_b32 s6, s6, 11
	s_add_i32 s6, s6, s20
	s_lshr_b32 s6, s6, 7
	s_lshl_b32 s6, s6, 2
	s_add_i32 s6, s6, 0x1c00
	v_mov_b32_e32 v110, s6

; DI unsigned pk_bf16(float lo, float hi) { f32x2 v = {lo, hi}; bf16v2 b = __builtin_convertvector(v, bf16v2); return __builtin_bit_cast(unsigned, b); }
; DI float red64(float x) { for (int o = 32; o > 0; o >>= 1) x += __shfl_xor(x, o); return x; }
; DI void modnorm_rows(const Params& p, int l, int which  , bool from_inputs, bool skip_ctx, int w0, int wstride, int lane) {
;     ...
;   for (; i < nrows; i += wstride) {
;     const int row = rowof(i); const int b = row / TB, s = row % TB;
;     f32x4 v[4];
; #pragma unroll
;     for (int q = 0; q < 4; ++q) v[q] = vn[q];
;     if (i + wstride < nrows) {
;       const int rn = rowof(i + wstride); const float* src = xsrc_row(p, from_inputs, rn / TB, rn % TB);
; #pragma unroll
;       for (int q = 0; q < 4; ++q) vn[q] = *(const f32x4*)(src + q * 256 + lane * 4);
;     }
;     const float* mod = p.MOD + (size_t)(l * 9 + (s < NCTX ? 8 : b)) * 6144 + (which ? 3 * 1024 : 0);
;     f32x4 sh[4], sc[4];
; #pragma unroll
;     for (int q = 0; q < 4; ++q) { sh[q] = *(const f32x4*)(mod + q * 256 + lane * 4); sc[q] = *(const f32x4*)(mod + 1024 + q * 256 + lane * 4); }
;     float ss = 0.f;
; #pragma unroll
;     for (int q = 0; q < 4; ++q) ss += v[q][0] * v[q][0] + v[q][1] * v[q][1] + v[q][2] * v[q][2] + v[q][3] * v[q][3];
;     ss = red64(ss);
;     const float rs = rsqrtf(ss * (1.f / 1024.f) + EPSF);
;     bf16_t* dst = p.HY + (size_t)row * DM;
; #pragma unroll
;     for (int q = 0; q < 4; ++q) {
;       float o[4];
; #pragma unroll
;       for (int j = 0; j < 4; ++j) o[j] = (v[q][j] * rs * gg[q][j]) * (1.f + sc[q][j]) + sh[q][j];
;       u32x2 w = {pk_bf16(o[0], o[1]), pk_bf16(o[2], o[3])};
;       *(u32x2*)(dst + q * 256 + lane * 4) = w;
;     }
.Ldep_norm2a_ok4:
	s_add_i32 s21, s37, 4
	s_cmp_ge_u32 s21, 9
	s_cselect_b32 s38, 9, 0
	s_sub_i32 s21, s21, s38
	s_lshl_b32 s21, s21, 11
	s_add_i32 s21, s21, s20
	s_mul_hi_u32 s7, s21, 0x38e38e39
	s_lshr_b32 s7, s7, 9
	s_mul_i32 s8, s7, 0x900
	s_sub_i32 s8, s21, s8
	s_lshl_b32 s9, s7, 11
	s_add_i32 s9, s9, s8
	s_add_i32 s9, s9, 0xffffff00
	s_lshl_b32 s10, s7, 8
	s_add_i32 s10, s10, s8
	s_cmpk_gt_i32 s8, 0xff
	s_cselect_b32 s9, s9, s10
	s_cselect_b32 s26, s12, s14
	s_cselect_b32 s27, s13, s15
	s_cselect_b32 s10, s7, 8
	s_lshl_b32 s9, s9, 12
	s_add_u32 s26, s26, s9
	s_addc_u32 s27, s27, 0
	s_add_i32 s10, s10, s82
	s_mul_i32 s10, s10, s24
	s_add_u32 s28, s58, s10
	s_addc_u32 s29, s59, 0
	s_add_u32 s28, s28, 0x3000
	s_addc_u32 s29, s29, 0
	s_add_u32 s0, s28, 0x1000
	s_addc_u32 s1, s29, 0
	global_load_dwordx4 v[66:69], v244, s[26:27] sc0 sc1
	global_load_dwordx4 v[70:73], v244, s[26:27] offset:1024 sc0 sc1
	global_load_dwordx4 v[74:77], v244, s[26:27] offset:2048 sc0 sc1
	global_load_dwordx4 v[78:81], v244, s[26:27] offset:3072 sc0 sc1
	global_load_dwordx4 v[82:85], v244, s[28:29]
	global_load_dwordx4 v[86:89], v244, s[28:29] offset:1024
	global_load_dwordx4 v[90:93], v244, s[28:29] offset:2048
	global_load_dwordx4 v[94:97], v244, s[28:29] offset:3072
	global_load_dwordx4 v[98:101], v244, s[0:1]
	global_load_dwordx4 v[102:105], v244, s[0:1] offset:1024
	global_load_dwordx4 v[106:109], v244, s[0:1] offset:2048
	global_load_dwordx4 v[118:121], v244, s[0:1] offset:3072
	s_add_i32 s6, s37, 5
	s_cmp_ge_u32 s6, 9
	s_cselect_b32 s38, 9, 0
	s_sub_i32 s6, s6, s38
	s_lshl_b32 s6, s6, 11
	s_add_i32 s6, s6, s20
	s_lshr_b32 s6, s6, 7
	s_lshl_b32 s6, s6, 2
	s_add_i32 s6, s6, 0x1c00
	v_mov_b32_e32 v110, s6
	global_load_dword v114, v110, s[70:71] sc1
	s_waitcnt vmcnt(35)
	v_pk_mul_f32 v[246:247], v[122:123], v[122:123]
	v_pk_fma_f32 v[246:247], v[124:125], v[124:125], v[246:247]
	v_pk_fma_f32 v[246:247], v[126:127], v[126:127], v[246:247]
	v_pk_fma_f32 v[246:247], v[128:129], v[128:129], v[246:247]
	v_pk_fma_f32 v[246:247], v[130:131], v[130:131], v[246:247]
	v_pk_fma_f32 v[246:247], v[132:133], v[132:133], v[246:247]
	v_pk_fma_f32 v[246:247], v[134:135], v[134:135], v[246:247]
	v_pk_fma_f32 v[246:247], v[136:137], v[136:137], v[246:247]
	s_nop 0
	v_add_f32_e32 v246, v246, v247
	s_nop 1
	v_add_f32_dpp v246, v246, v246 quad_perm:[1,0,3,2] row_mask:0xf bank_mask:0xf
	s_nop 1
	v_add_f32_dpp v246, v246, v246 quad_perm:[2,3,0,1] row_mask:0xf bank_mask:0xf
	s_nop 1
	v_add_f32_dpp v246, v246, v246 row_half_mirror row_mask:0xf bank_mask:0xf
	s_nop 1
	v_add_f32_dpp v246, v246, v246 row_mirror row_mask:0xf bank_mask:0xf
	s_nop 1
	v_add_f32_dpp v246, v246, v246 row_bcast:15 row_mask:0xa bank_mask:0xf
	s_nop 1
	v_add_f32_dpp v246, v246, v246 row_bcast:31 row_mask:0xc bank_mask:0xf
	s_nop 1
	v_readlane_b32 s0, v246, 63
	s_add_i32 s21, s37, 2
	s_cmp_ge_u32 s21, 9
	s_cselect_b32 s38, 9, 0
	s_sub_i32 s21, s21, s38
	s_lshl_b32 s21, s21, 11
	s_add_i32 s21, s21, s20
	s_lshl_b32 s21, s21, 11
	s_add_u32 s10, s16, s21
	s_addc_u32 s11, s17, 0
	v_mov_b32_e32 v248, s0
	v_fmamk_f32 v248, v248, 0x3a800000, v143
	v_rsq_f32_e32 v248, v248
	s_nop 0
	v_pk_mul_f32 v[122:123], v[122:123], v[248:249] op_sel_hi:[1,0]
	v_pk_add_f32 v[176:177], v[176:177], 1.0 op_sel_hi:[1,0]
	v_pk_mul_f32 v[122:123], v[2:3], v[122:123]
	v_pk_fma_f32 v[122:123], v[176:177], v[122:123], v[160:161]
	v_pk_mul_f32 v[124:125], v[124:125], v[248:249] op_sel_hi:[1,0]
	v_pk_add_f32 v[178:179], v[178:179], 1.0 op_sel_hi:[1,0]
	v_pk_mul_f32 v[124:125], v[4:5], v[124:125]
	v_pk_fma_f32 v[124:125], v[178:179], v[124:125], v[162:163]
	v_cvt_pk_bf16_f32 v160, v122, v123
	v_cvt_pk_bf16_f32 v161, v124, v125
	global_store_dwordx2 v245, v[160:161], s[10:11]
	v_pk_mul_f32 v[126:127], v[126:127], v[248:249] op_sel_hi:[1,0]
	v_pk_add_f32 v[180:181], v[180:181], 1.0 op_sel_hi:[1,0]
	v_pk_mul_f32 v[126:127], v[6:7], v[126:127]
	v_pk_fma_f32 v[126:127], v[180:181], v[126:127], v[164:165]
	v_pk_mul_f32 v[128:129], v[128:129], v[248:249] op_sel_hi:[1,0]
	v_pk_add_f32 v[182:183], v[182:183], 1.0 op_sel_hi:[1,0]
	v_pk_mul_f32 v[128:129], v[8:9], v[128:129]
	v_pk_fma_f32 v[128:129], v[182:183], v[128:129], v[166:167]
	v_cvt_pk_bf16_f32 v164, v126, v127
	v_cvt_pk_bf16_f32 v165, v128, v129
	global_store_dwordx2 v245, v[164:165], s[10:11] offset:512
	v_pk_mul_f32 v[130:131], v[130:131], v[248:249] op_sel_hi:[1,0]
	v_pk_add_f32 v[184:185], v[184:185], 1.0 op_sel_hi:[1,0]
	v_pk_mul_f32 v[130:131], v[10:11], v[130:131]
	v_pk_fma_f32 v[130:131], v[184:185], v[130:131], v[168:169]
	v_pk_mul_f32 v[132:133], v[132:133], v[248:249] op_sel_hi:[1,0]
	v_pk_add_f32 v[186:187], v[186:187], 1.0 op_sel_hi:[1,0]
	v_pk_mul_f32 v[132:133], v[12:13], v[132:133]
	v_pk_fma_f32 v[132:133], v[186:187], v[132:133], v[170:171]
	v_cvt_pk_bf16_f32 v168, v130, v131
	v_cvt_pk_bf16_f32 v169, v132, v133
	global_store_dwordx2 v245, v[168:169], s[10:11] offset:1024
	v_pk_mul_f32 v[134:135], v[134:135], v[248:249] op_sel_hi:[1,0]
	v_pk_add_f32 v[188:189], v[188:189], 1.0 op_sel_hi:[1,0]
	v_pk_mul_f32 v[134:135], v[14:15], v[134:135]
	v_pk_fma_f32 v[134:135], v[188:189], v[134:135], v[172:173]
	v_pk_mul_f32 v[136:137], v[136:137], v[248:249] op_sel_hi:[1,0]
	v_pk_add_f32 v[190:191], v[190:191], 1.0 op_sel_hi:[1,0]
	v_pk_mul_f32 v[136:137], v[16:17], v[136:137]
	v_pk_fma_f32 v[136:137], v[190:191], v[136:137], v[174:175]
	v_cvt_pk_bf16_f32 v172, v134, v135
	v_cvt_pk_bf16_f32 v173, v136, v137
	global_store_dwordx2 v245, v[172:173], s[10:11] offset:1536
	s_waitcnt vmcnt(4)
	v_readfirstlane_b32 s6, v114
	s_cmp_ge_u32 s6, 8
	s_cbranch_scc1 .Ldep_norm2a_ok5
	s_add_i32 s6, s37, 5
	s_cmp_ge_u32 s6, 9
	s_cselect_b32 s38, 9, 0
	s_sub_i32 s6, s6, s38
	s_lshl_b32 s6, s6, 11
	s_add_i32 s6, s6, s20
	s_lshr_b32 s6, s6, 7
	s_lshl_b32 s6, s6, 2
	s_add_i32 s6, s6, 0x1c00
	v_mov_b32_e32 v110, s6

; DI unsigned pk_bf16(float lo, float hi) { f32x2 v = {lo, hi}; bf16v2 b = __builtin_convertvector(v, bf16v2); return __builtin_bit_cast(unsigned, b); }
; DI float red64(float x) { for (int o = 32; o > 0; o >>= 1) x += __shfl_xor(x, o); return x; }
; DI void modnorm_rows(const Params& p, int l, int which  , bool from_inputs, bool skip_ctx, int w0, int wstride, int lane) {
;     ...
;   for (; i < nrows; i += wstride) {
;     const int row = rowof(i); const int b = row / TB, s = row % TB;
;     f32x4 v[4];
; #pragma unroll
;     for (int q = 0; q < 4; ++q) v[q] = vn[q];
;     if (i + wstride < nrows) {
;       const int rn = rowof(i + wstride); const float* src = xsrc_row(p, from_inputs, rn / TB, rn % TB);
; #pragma unroll
;       for (int q = 0; q < 4; ++q) vn[q] = *(const f32x4*)(src + q * 256 + lane * 4);
;     }
;     const float* mod = p.MOD + (size_t)(l * 9 + (s < NCTX ? 8 : b)) * 6144 + (which ? 3 * 1024 : 0);
;     f32x4 sh[4], sc[4];
; #pragma unroll
;     for (int q = 0; q < 4; ++q) { sh[q] = *(const f32x4*)(mod + q * 256 + lane * 4); sc[q] = *(const f32x4*)(mod + 1024 + q * 256 + lane * 4); }
;     float ss = 0.f;
; #pragma unroll
;     for (int q = 0; q < 4; ++q) ss += v[q][0] * v[q][0] + v[q][1] * v[q][1] + v[q][2] * v[q][2] + v[q][3] * v[q][3];
;     ss = red64(ss);
;     const float rs = rsqrtf(ss * (1.f / 1024.f) + EPSF);
;     bf16_t* dst = p.HY + (size_t)row * DM;
; #pragma unroll
;     for (int q = 0; q < 4; ++q) {
;       float o[4];
; #pragma unroll
;       for (int j = 0; j < 4; ++j) o[j] = (v[q][j] * rs * gg[q][j]) * (1.f + sc[q][j]) + sh[q][j];
;       u32x2 w = {pk_bf16(o[0], o[1]), pk_bf16(o[2], o[3])};
;       *(u32x2*)(dst + q * 256 + lane * 4) = w;
;     }
.Ldep_norm2a_ok5:
	s_add_i32 s21, s37, 5
	s_cmp_ge_u32 s21, 9
	s_cselect_b32 s38, 9, 0
	s_sub_i32 s21, s21, s38
	s_lshl_b32 s21, s21, 11
	s_add_i32 s21, s21, s20
	s_mul_hi_u32 s7, s21, 0x38e38e39
	s_lshr_b32 s7, s7, 9
	s_mul_i32 s8, s7, 0x900
	s_sub_i32 s8, s21, s8
	s_lshl_b32 s9, s7, 11
	s_add_i32 s9, s9, s8
	s_add_i32 s9, s9, 0xffffff00
	s_lshl_b32 s10, s7, 8
	s_add_i32 s10, s10, s8
	s_cmpk_gt_i32 s8, 0xff
	s_cselect_b32 s9, s9, s10
	s_cselect_b32 s26, s12, s14
	s_cselect_b32 s27, s13, s15
	s_cselect_b32 s10, s7, 8
	s_lshl_b32 s9, s9, 12
	s_add_u32 s26, s26, s9
	s_addc_u32 s27, s27, 0
	s_add_i32 s10, s10, s82
	s_mul_i32 s10, s10, s24
	s_add_u32 s28, s58, s10
	s_addc_u32 s29, s59, 0
	s_add_u32 s28, s28, 0x3000
	s_addc_u32 s29, s29, 0
	s_add_u32 s0, s28, 0x1000
	s_addc_u32 s1, s29, 0
	global_load_dwordx4 v[122:125], v244, s[26:27] sc0 sc1
	global_load_dwordx4 v[126:129], v244, s[26:27] offset:1024 sc0 sc1
	global_load_dwordx4 v[130:133], v244, s[26:27] offset:2048 sc0 sc1
	global_load_dwordx4 v[134:137], v244, s[26:27] offset:3072 sc0 sc1
	global_load_dwordx4 v[160:163], v244, s[28:29]
	global_load_dwordx4 v[164:167], v244, s[28:29] offset:1024
	global_load_dwordx4 v[168:171], v244, s[28:29] offset:2048
	global_load_dwordx4 v[172:175], v244, s[28:29] offset:3072
	global_load_dwordx4 v[176:179], v244, s[0:1]
	global_load_dwordx4 v[180:183], v244, s[0:1] offset:1024
	global_load_dwordx4 v[184:187], v244, s[0:1] offset:2048
	global_load_dwordx4 v[188:191], v244, s[0:1] offset:3072
	s_add_i32 s6, s37, 6
	s_cmp_ge_u32 s6, 9
	s_cselect_b32 s38, 9, 0
	s_sub_i32 s6, s6, s38
	s_lshl_b32 s6, s6, 11
	s_add_i32 s6, s6, s20
	s_lshr_b32 s6, s6, 7
	s_lshl_b32 s6, s6, 2
	s_add_i32 s6, s6, 0x1c00
	v_mov_b32_e32 v110, s6
	global_load_dword v114, v110, s[70:71] sc1
	s_waitcnt vmcnt(35)
	v_pk_mul_f32 v[246:247], v[18:19], v[18:19]
	v_pk_fma_f32 v[246:247], v[20:21], v[20:21], v[246:247]
	v_pk_fma_f32 v[246:247], v[22:23], v[22:23], v[246:247]
	v_pk_fma_f32 v[246:247], v[24:25], v[24:25], v[246:247]
	v_pk_fma_f32 v[246:247], v[26:27], v[26:27], v[246:247]
	v_pk_fma_f32 v[246:247], v[28:29], v[28:29], v[246:247]
	v_pk_fma_f32 v[246:247], v[30:31], v[30:31], v[246:247]
	v_pk_fma_f32 v[246:247], v[32:33], v[32:33], v[246:247]
	s_nop 0
	v_add_f32_e32 v246, v246, v247
	s_nop 1
	v_add_f32_dpp v246, v246, v246 quad_perm:[1,0,3,2] row_mask:0xf bank_mask:0xf
	s_nop 1
	v_add_f32_dpp v246, v246, v246 quad_perm:[2,3,0,1] row_mask:0xf bank_mask:0xf
	s_nop 1
	v_add_f32_dpp v246, v246, v246 row_half_mirror row_mask:0xf bank_mask:0xf
	s_nop 1
	v_add_f32_dpp v246, v246, v246 row_mirror row_mask:0xf bank_mask:0xf
	s_nop 1
	v_add_f32_dpp v246, v246, v246 row_bcast:15 row_mask:0xa bank_mask:0xf
	s_nop 1
	v_add_f32_dpp v246, v246, v246 row_bcast:31 row_mask:0xc bank_mask:0xf
	s_nop 1
	v_readlane_b32 s0, v246, 63
	s_add_i32 s21, s37, 3
	s_cmp_ge_u32 s21, 9
	s_cselect_b32 s38, 9, 0
	s_sub_i32 s21, s21, s38
	s_lshl_b32 s21, s21, 11
	s_add_i32 s21, s21, s20
	s_lshl_b32 s21, s21, 11
	s_add_u32 s10, s16, s21
	s_addc_u32 s11, s17, 0
	v_mov_b32_e32 v248, s0
	v_fmamk_f32 v248, v248, 0x3a800000, v143
	v_rsq_f32_e32 v248, v248
	s_nop 0
	v_pk_mul_f32 v[18:19], v[18:19], v[248:249] op_sel_hi:[1,0]
	v_pk_add_f32 v[50:51], v[50:51], 1.0 op_sel_hi:[1,0]
	v_pk_mul_f32 v[18:19], v[2:3], v[18:19]
	v_pk_fma_f32 v[18:19], v[50:51], v[18:19], v[34:35]
	v_pk_mul_f32 v[20:21], v[20:21], v[248:249] op_sel_hi:[1,0]
	v_pk_add_f32 v[52:53], v[52:53], 1.0 op_sel_hi:[1,0]
	v_pk_mul_f32 v[20:21], v[4:5], v[20:21]
	v_pk_fma_f32 v[20:21], v[52:53], v[20:21], v[36:37]
	v_cvt_pk_bf16_f32 v34, v18, v19
	v_cvt_pk_bf16_f32 v35, v20, v21
	global_store_dwordx2 v245, v[34:35], s[10:11]
	v_pk_mul_f32 v[22:23], v[22:23], v[248:249] op_sel_hi:[1,0]
	v_pk_add_f32 v[54:55], v[54:55], 1.0 op_sel_hi:[1,0]
	v_pk_mul_f32 v[22:23], v[6:7], v[22:23]
	v_pk_fma_f32 v[22:23], v[54:55], v[22:23], v[38:39]
	v_pk_mul_f32 v[24:25], v[24:25], v[248:249] op_sel_hi:[1,0]
	v_pk_add_f32 v[56:57], v[56:57], 1.0 op_sel_hi:[1,0]
	v_pk_mul_f32 v[24:25], v[8:9], v[24:25]
	v_pk_fma_f32 v[24:25], v[56:57], v[24:25], v[40:41]
	v_cvt_pk_bf16_f32 v38, v22, v23
	v_cvt_pk_bf16_f32 v39, v24, v25
	global_store_dwordx2 v245, v[38:39], s[10:11] offset:512
	v_pk_mul_f32 v[26:27], v[26:27], v[248:249] op_sel_hi:[1,0]
	v_pk_add_f32 v[58:59], v[58:59], 1.0 op_sel_hi:[1,0]
	v_pk_mul_f32 v[26:27], v[10:11], v[26:27]
	v_pk_fma_f32 v[26:27], v[58:59], v[26:27], v[42:43]
	v_pk_mul_f32 v[28:29], v[28:29], v[248:249] op_sel_hi:[1,0]
	v_pk_add_f32 v[60:61], v[60:61], 1.0 op_sel_hi:[1,0]
	v_pk_mul_f32 v[28:29], v[12:13], v[28:29]
	v_pk_fma_f32 v[28:29], v[60:61], v[28:29], v[44:45]
	v_cvt_pk_bf16_f32 v42, v26, v27
	v_cvt_pk_bf16_f32 v43, v28, v29
	global_store_dwordx2 v245, v[42:43], s[10:11] offset:1024
	v_pk_mul_f32 v[30:31], v[30:31], v[248:249] op_sel_hi:[1,0]
	v_pk_add_f32 v[62:63], v[62:63], 1.0 op_sel_hi:[1,0]
	v_pk_mul_f32 v[30:31], v[14:15], v[30:31]
	v_pk_fma_f32 v[30:31], v[62:63], v[30:31], v[46:47]
	v_pk_mul_f32 v[32:33], v[32:33], v[248:249] op_sel_hi:[1,0]
	v_pk_add_f32 v[64:65], v[64:65], 1.0 op_sel_hi:[1,0]
	v_pk_mul_f32 v[32:33], v[16:17], v[32:33]
	v_pk_fma_f32 v[32:33], v[64:65], v[32:33], v[48:49]
	v_cvt_pk_bf16_f32 v46, v30, v31
	v_cvt_pk_bf16_f32 v47, v32, v33
	global_store_dwordx2 v245, v[46:47], s[10:11] offset:1536
	s_waitcnt vmcnt(4)
	v_readfirstlane_b32 s6, v114
	s_cmp_ge_u32 s6, 8
	s_cbranch_scc1 .Ldep_norm2a_ok6
	s_add_i32 s6, s37, 6
	s_cmp_ge_u32 s6, 9
	s_cselect_b32 s38, 9, 0
	s_sub_i32 s6, s6, s38
	s_lshl_b32 s6, s6, 11
	s_add_i32 s6, s6, s20
	s_lshr_b32 s6, s6, 7
	s_lshl_b32 s6, s6, 2
	s_add_i32 s6, s6, 0x1c00
	v_mov_b32_e32 v110, s6

; DI unsigned pk_bf16(float lo, float hi) { f32x2 v = {lo, hi}; bf16v2 b = __builtin_convertvector(v, bf16v2); return __builtin_bit_cast(unsigned, b); }
; DI float red64(float x) { for (int o = 32; o > 0; o >>= 1) x += __shfl_xor(x, o); return x; }
; DI void modnorm_rows(const Params& p, int l, int which  , bool from_inputs, bool skip_ctx, int w0, int wstride, int lane) {
;     ...
;   for (; i < nrows; i += wstride) {
;     const int row = rowof(i); const int b = row / TB, s = row % TB;
;     f32x4 v[4];
; #pragma unroll
;     for (int q = 0; q < 4; ++q) v[q] = vn[q];
;     if (i + wstride < nrows) {
;       const int rn = rowof(i + wstride); const float* src = xsrc_row(p, from_inputs, rn / TB, rn % TB);
; #pragma unroll
;       for (int q = 0; q < 4; ++q) vn[q] = *(const f32x4*)(src + q * 256 + lane * 4);
;     }
;     const float* mod = p.MOD + (size_t)(l * 9 + (s < NCTX ? 8 : b)) * 6144 + (which ? 3 * 1024 : 0);
;     f32x4 sh[4], sc[4];
; #pragma unroll
;     for (int q = 0; q < 4; ++q) { sh[q] = *(const f32x4*)(mod + q * 256 + lane * 4); sc[q] = *(const f32x4*)(mod + 1024 + q * 256 + lane * 4); }
;     float ss = 0.f;
; #pragma unroll
;     for (int q = 0; q < 4; ++q) ss += v[q][0] * v[q][0] + v[q][1] * v[q][1] + v[q][2] * v[q][2] + v[q][3] * v[q][3];
;     ss = red64(ss);
;     const float rs = rsqrtf(ss * (1.f / 1024.f) + EPSF);
;     bf16_t* dst = p.HY + (size_t)row * DM;
; #pragma unroll
;     for (int q = 0; q < 4; ++q) {
;       float o[4];
; #pragma unroll
;       for (int j = 0; j < 4; ++j) o[j] = (v[q][j] * rs * gg[q][j]) * (1.f + sc[q][j]) + sh[q][j];
;       u32x2 w = {pk_bf16(o[0], o[1]), pk_bf16(o[2], o[3])};
;       *(u32x2*)(dst + q * 256 + lane * 4) = w;
;     }
.Ldep_norm2a_ok6:
	s_add_i32 s21, s37, 6
	s_cmp_ge_u32 s21, 9
	s_cselect_b32 s38, 9, 0
	s_sub_i32 s21, s21, s38
	s_lshl_b32 s21, s21, 11
	s_add_i32 s21, s21, s20
	s_mul_hi_u32 s7, s21, 0x38e38e39
	s_lshr_b32 s7, s7, 9
	s_mul_i32 s8, s7, 0x900
	s_sub_i32 s8, s21, s8
	s_lshl_b32 s9, s7, 11
	s_add_i32 s9, s9, s8
	s_add_i32 s9, s9, 0xffffff00
	s_lshl_b32 s10, s7, 8
	s_add_i32 s10, s10, s8
	s_cmpk_gt_i32 s8, 0xff
	s_cselect_b32 s9, s9, s10
	s_cselect_b32 s26, s12, s14
	s_cselect_b32 s27, s13, s15
	s_cselect_b32 s10, s7, 8
	s_lshl_b32 s9, s9, 12
	s_add_u32 s26, s26, s9
	s_addc_u32 s27, s27, 0
	s_add_i32 s10, s10, s82
	s_mul_i32 s10, s10, s24
	s_add_u32 s28, s58, s10
	s_addc_u32 s29, s59, 0
	s_add_u32 s28, s28, 0x3000
	s_addc_u32 s29, s29, 0
	s_add_u32 s0, s28, 0x1000
	s_addc_u32 s1, s29, 0
	global_load_dwordx4 v[18:21], v244, s[26:27] sc0 sc1
	global_load_dwordx4 v[22:25], v244, s[26:27] offset:1024 sc0 sc1
	global_load_dwordx4 v[26:29], v244, s[26:27] offset:2048 sc0 sc1
	global_load_dwordx4 v[30:33], v244, s[26:27] offset:3072 sc0 sc1
	global_load_dwordx4 v[34:37], v244, s[28:29]
	global_load_dwordx4 v[38:41], v244, s[28:29] offset:1024
	global_load_dwordx4 v[42:45], v244, s[28:29] offset:2048
	global_load_dwordx4 v[46:49], v244, s[28:29] offset:3072
	global_load_dwordx4 v[50:53], v244, s[0:1]
	global_load_dwordx4 v[54:57], v244, s[0:1] offset:1024
	global_load_dwordx4 v[58:61], v244, s[0:1] offset:2048
	global_load_dwordx4 v[62:65], v244, s[0:1] offset:3072
	s_add_i32 s6, s37, 7
	s_cmp_ge_u32 s6, 9
	s_cselect_b32 s38, 9, 0
	s_sub_i32 s6, s6, s38
	s_lshl_b32 s6, s6, 11
	s_add_i32 s6, s6, s20
	s_lshr_b32 s6, s6, 7
	s_lshl_b32 s6, s6, 2
	s_add_i32 s6, s6, 0x1c00
	v_mov_b32_e32 v110, s6
	global_load_dword v114, v110, s[70:71] sc1
	s_waitcnt vmcnt(35)
	v_pk_mul_f32 v[246:247], v[66:67], v[66:67]
	v_pk_fma_f32 v[246:247], v[68:69], v[68:69], v[246:247]
	v_pk_fma_f32 v[246:247], v[70:71], v[70:71], v[246:247]
	v_pk_fma_f32 v[246:247], v[72:73], v[72:73], v[246:247]
	v_pk_fma_f32 v[246:247], v[74:75], v[74:75], v[246:247]
	v_pk_fma_f32 v[246:247], v[76:77], v[76:77], v[246:247]
	v_pk_fma_f32 v[246:247], v[78:79], v[78:79], v[246:247]
	v_pk_fma_f32 v[246:247], v[80:81], v[80:81], v[246:247]
	s_nop 0
	v_add_f32_e32 v246, v246, v247
	s_nop 1
	v_add_f32_dpp v246, v246, v246 quad_perm:[1,0,3,2] row_mask:0xf bank_mask:0xf
	s_nop 1
	v_add_f32_dpp v246, v246, v246 quad_perm:[2,3,0,1] row_mask:0xf bank_mask:0xf
	s_nop 1
	v_add_f32_dpp v246, v246, v246 row_half_mirror row_mask:0xf bank_mask:0xf
	s_nop 1
	v_add_f32_dpp v246, v246, v246 row_mirror row_mask:0xf bank_mask:0xf
	s_nop 1
	v_add_f32_dpp v246, v246, v246 row_bcast:15 row_mask:0xa bank_mask:0xf
	s_nop 1
	v_add_f32_dpp v246, v246, v246 row_bcast:31 row_mask:0xc bank_mask:0xf
	s_nop 1
	v_readlane_b32 s0, v246, 63
	s_add_i32 s21, s37, 4
	s_cmp_ge_u32 s21, 9
	s_cselect_b32 s38, 9, 0
	s_sub_i32 s21, s21, s38
	s_lshl_b32 s21, s21, 11
	s_add_i32 s21, s21, s20
	s_lshl_b32 s21, s21, 11
	s_add_u32 s10, s16, s21
	s_addc_u32 s11, s17, 0
	v_mov_b32_e32 v248, s0
	v_fmamk_f32 v248, v248, 0x3a800000, v143
	v_rsq_f32_e32 v248, v248
	s_nop 0
	v_pk_mul_f32 v[66:67], v[66:67], v[248:249] op_sel_hi:[1,0]
	v_pk_add_f32 v[98:99], v[98:99], 1.0 op_sel_hi:[1,0]
	v_pk_mul_f32 v[66:67], v[2:3], v[66:67]
	v_pk_fma_f32 v[66:67], v[98:99], v[66:67], v[82:83]
	v_pk_mul_f32 v[68:69], v[68:69], v[248:249] op_sel_hi:[1,0]
	v_pk_add_f32 v[100:101], v[100:101], 1.0 op_sel_hi:[1,0]
	v_pk_mul_f32 v[68:69], v[4:5], v[68:69]
	v_pk_fma_f32 v[68:69], v[100:101], v[68:69], v[84:85]
	v_cvt_pk_bf16_f32 v82, v66, v67
	v_cvt_pk_bf16_f32 v83, v68, v69
	global_store_dwordx2 v245, v[82:83], s[10:11]
	v_pk_mul_f32 v[70:71], v[70:71], v[248:249] op_sel_hi:[1,0]
	v_pk_add_f32 v[102:103], v[102:103], 1.0 op_sel_hi:[1,0]
	v_pk_mul_f32 v[70:71], v[6:7], v[70:71]
	v_pk_fma_f32 v[70:71], v[102:103], v[70:71], v[86:87]
	v_pk_mul_f32 v[72:73], v[72:73], v[248:249] op_sel_hi:[1,0]
	v_pk_add_f32 v[104:105], v[104:105], 1.0 op_sel_hi:[1,0]
	v_pk_mul_f32 v[72:73], v[8:9], v[72:73]
	v_pk_fma_f32 v[72:73], v[104:105], v[72:73], v[88:89]
	v_cvt_pk_bf16_f32 v86, v70, v71
	v_cvt_pk_bf16_f32 v87, v72, v73
	global_store_dwordx2 v245, v[86:87], s[10:11] offset:512
	v_pk_mul_f32 v[74:75], v[74:75], v[248:249] op_sel_hi:[1,0]
	v_pk_add_f32 v[106:107], v[106:107], 1.0 op_sel_hi:[1,0]
	v_pk_mul_f32 v[74:75], v[10:11], v[74:75]
	v_pk_fma_f32 v[74:75], v[106:107], v[74:75], v[90:91]
	v_pk_mul_f32 v[76:77], v[76:77], v[248:249] op_sel_hi:[1,0]
	v_pk_add_f32 v[108:109], v[108:109], 1.0 op_sel_hi:[1,0]
	v_pk_mul_f32 v[76:77], v[12:13], v[76:77]
	v_pk_fma_f32 v[76:77], v[108:109], v[76:77], v[92:93]
	v_cvt_pk_bf16_f32 v90, v74, v75
	v_cvt_pk_bf16_f32 v91, v76, v77
	global_store_dwordx2 v245, v[90:91], s[10:11] offset:1024
	v_pk_mul_f32 v[78:79], v[78:79], v[248:249] op_sel_hi:[1,0]
	v_pk_add_f32 v[118:119], v[118:119], 1.0 op_sel_hi:[1,0]
	v_pk_mul_f32 v[78:79], v[14:15], v[78:79]
	v_pk_fma_f32 v[78:79], v[118:119], v[78:79], v[94:95]
	v_pk_mul_f32 v[80:81], v[80:81], v[248:249] op_sel_hi:[1,0]
	v_pk_add_f32 v[120:121], v[120:121], 1.0 op_sel_hi:[1,0]
	v_pk_mul_f32 v[80:81], v[16:17], v[80:81]
	v_pk_fma_f32 v[80:81], v[120:121], v[80:81], v[96:97]
	v_cvt_pk_bf16_f32 v94, v78, v79
	v_cvt_pk_bf16_f32 v95, v80, v81
	global_store_dwordx2 v245, v[94:95], s[10:11] offset:1536
	s_waitcnt vmcnt(4)
	v_readfirstlane_b32 s6, v114
	s_cmp_ge_u32 s6, 8
	s_cbranch_scc1 .Ldep_norm2a_ok7
	s_add_i32 s6, s37, 7
	s_cmp_ge_u32 s6, 9
	s_cselect_b32 s38, 9, 0
	s_sub_i32 s6, s6, s38
	s_lshl_b32 s6, s6, 11
	s_add_i32 s6, s6, s20
	s_lshr_b32 s6, s6, 7
	s_lshl_b32 s6, s6, 2
	s_add_i32 s6, s6, 0x1c00
	v_mov_b32_e32 v110, s6

; DI unsigned pk_bf16(float lo, float hi) { f32x2 v = {lo, hi}; bf16v2 b = __builtin_convertvector(v, bf16v2); return __builtin_bit_cast(unsigned, b); }
; DI float red64(float x) { for (int o = 32; o > 0; o >>= 1) x += __shfl_xor(x, o); return x; }
; DI void modnorm_rows(const Params& p, int l, int which  , bool from_inputs, bool skip_ctx, int w0, int wstride, int lane) {
;     ...
;   for (; i < nrows; i += wstride) {
;     const int row = rowof(i); const int b = row / TB, s = row % TB;
;     f32x4 v[4];
; #pragma unroll
;     for (int q = 0; q < 4; ++q) v[q] = vn[q];
;     if (i + wstride < nrows) {
;       const int rn = rowof(i + wstride); const float* src = xsrc_row(p, from_inputs, rn / TB, rn % TB);
; #pragma unroll
;       for (int q = 0; q < 4; ++q) vn[q] = *(const f32x4*)(src + q * 256 + lane * 4);
;     }
;     const float* mod = p.MOD + (size_t)(l * 9 + (s < NCTX ? 8 : b)) * 6144 + (which ? 3 * 1024 : 0);
;     f32x4 sh[4], sc[4];
; #pragma unroll
;     for (int q = 0; q < 4; ++q) { sh[q] = *(const f32x4*)(mod + q * 256 + lane * 4); sc[q] = *(const f32x4*)(mod + 1024 + q * 256 + lane * 4); }
;     float ss = 0.f;
; #pragma unroll
;     for (int q = 0; q < 4; ++q) ss += v[q][0] * v[q][0] + v[q][1] * v[q][1] + v[q][2] * v[q][2] + v[q][3] * v[q][3];
;     ss = red64(ss);
;     const float rs = rsqrtf(ss * (1.f / 1024.f) + EPSF);
;     bf16_t* dst = p.HY + (size_t)row * DM;
; #pragma unroll
;     for (int q = 0; q < 4; ++q) {
;       float o[4];
; #pragma unroll
;       for (int j = 0; j < 4; ++j) o[j] = (v[q][j] * rs * gg[q][j]) * (1.f + sc[q][j]) + sh[q][j];
;       u32x2 w = {pk_bf16(o[0], o[1]), pk_bf16(o[2], o[3])};
;       *(u32x2*)(dst + q * 256 + lane * 4) = w;
;     }
;   }
.Ldep_norm2a_ok7:
	s_add_i32 s21, s37, 7
	s_cmp_ge_u32 s21, 9
	s_cselect_b32 s38, 9, 0
	s_sub_i32 s21, s21, s38
	s_lshl_b32 s21, s21, 11
	s_add_i32 s21, s21, s20
	s_mul_hi_u32 s7, s21, 0x38e38e39
	s_lshr_b32 s7, s7, 9
	s_mul_i32 s8, s7, 0x900
	s_sub_i32 s8, s21, s8
	s_lshl_b32 s9, s7, 11
	s_add_i32 s9, s9, s8
	s_add_i32 s9, s9, 0xffffff00
	s_lshl_b32 s10, s7, 8
	s_add_i32 s10, s10, s8
	s_cmpk_gt_i32 s8, 0xff
	s_cselect_b32 s9, s9, s10
	s_cselect_b32 s26, s12, s14
	s_cselect_b32 s27, s13, s15
	s_cselect_b32 s10, s7, 8
	s_lshl_b32 s9, s9, 12
	s_add_u32 s26, s26, s9
	s_addc_u32 s27, s27, 0
	s_add_i32 s10, s10, s82
	s_mul_i32 s10, s10, s24
	s_add_u32 s28, s58, s10
	s_addc_u32 s29, s59, 0
	s_add_u32 s28, s28, 0x3000
	s_addc_u32 s29, s29, 0
	s_add_u32 s0, s28, 0x1000
	s_addc_u32 s1, s29, 0
	global_load_dwordx4 v[66:69], v244, s[26:27] sc0 sc1
	global_load_dwordx4 v[70:73], v244, s[26:27] offset:1024 sc0 sc1
	global_load_dwordx4 v[74:77], v244, s[26:27] offset:2048 sc0 sc1
	global_load_dwordx4 v[78:81], v244, s[26:27] offset:3072 sc0 sc1
	global_load_dwordx4 v[82:85], v244, s[28:29]
	global_load_dwordx4 v[86:89], v244, s[28:29] offset:1024
	global_load_dwordx4 v[90:93], v244, s[28:29] offset:2048
	global_load_dwordx4 v[94:97], v244, s[28:29] offset:3072
	global_load_dwordx4 v[98:101], v244, s[0:1]
	global_load_dwordx4 v[102:105], v244, s[0:1] offset:1024
	global_load_dwordx4 v[106:109], v244, s[0:1] offset:2048
	global_load_dwordx4 v[118:121], v244, s[0:1] offset:3072
	s_add_i32 s6, s37, 8
	s_cmp_ge_u32 s6, 9
	s_cselect_b32 s38, 9, 0
	s_sub_i32 s6, s6, s38
	s_lshl_b32 s6, s6, 11
	s_add_i32 s6, s6, s20
	s_lshr_b32 s6, s6, 7
	s_lshl_b32 s6, s6, 2
	s_add_i32 s6, s6, 0x1c00
	v_mov_b32_e32 v110, s6
	global_load_dword v114, v110, s[70:71] sc1
	s_waitcnt vmcnt(35)
	v_pk_mul_f32 v[246:247], v[122:123], v[122:123]
	v_pk_fma_f32 v[246:247], v[124:125], v[124:125], v[246:247]
	v_pk_fma_f32 v[246:247], v[126:127], v[126:127], v[246:247]
	v_pk_fma_f32 v[246:247], v[128:129], v[128:129], v[246:247]
	v_pk_fma_f32 v[246:247], v[130:131], v[130:131], v[246:247]
	v_pk_fma_f32 v[246:247], v[132:133], v[132:133], v[246:247]
	v_pk_fma_f32 v[246:247], v[134:135], v[134:135], v[246:247]
	v_pk_fma_f32 v[246:247], v[136:137], v[136:137], v[246:247]
	s_nop 0
	v_add_f32_e32 v246, v246, v247
	s_nop 1
	v_add_f32_dpp v246, v246, v246 quad_perm:[1,0,3,2] row_mask:0xf bank_mask:0xf
	s_nop 1
	v_add_f32_dpp v246, v246, v246 quad_perm:[2,3,0,1] row_mask:0xf bank_mask:0xf
	s_nop 1
	v_add_f32_dpp v246, v246, v246 row_half_mirror row_mask:0xf bank_mask:0xf
	s_nop 1
	v_add_f32_dpp v246, v246, v246 row_mirror row_mask:0xf bank_mask:0xf
	s_nop 1
	v_add_f32_dpp v246, v246, v246 row_bcast:15 row_mask:0xa bank_mask:0xf
	s_nop 1
	v_add_f32_dpp v246, v246, v246 row_bcast:31 row_mask:0xc bank_mask:0xf
	s_nop 1
	v_readlane_b32 s0, v246, 63
	s_add_i32 s21, s37, 5
	s_cmp_ge_u32 s21, 9
	s_cselect_b32 s38, 9, 0
	s_sub_i32 s21, s21, s38
	s_lshl_b32 s21, s21, 11
	s_add_i32 s21, s21, s20
	s_lshl_b32 s21, s21, 11
	s_add_u32 s10, s16, s21
	s_addc_u32 s11, s17, 0
	v_mov_b32_e32 v248, s0
	v_fmamk_f32 v248, v248, 0x3a800000, v143
	v_rsq_f32_e32 v248, v248
	s_nop 0
	v_pk_mul_f32 v[122:123], v[122:123], v[248:249] op_sel_hi:[1,0]
	v_pk_add_f32 v[176:177], v[176:177], 1.0 op_sel_hi:[1,0]
	v_pk_mul_f32 v[122:123], v[2:3], v[122:123]
	v_pk_fma_f32 v[122:123], v[176:177], v[122:123], v[160:161]
	v_pk_mul_f32 v[124:125], v[124:125], v[248:249] op_sel_hi:[1,0]
	v_pk_add_f32 v[178:179], v[178:179], 1.0 op_sel_hi:[1,0]
	v_pk_mul_f32 v[124:125], v[4:5], v[124:125]
	v_pk_fma_f32 v[124:125], v[178:179], v[124:125], v[162:163]
	v_cvt_pk_bf16_f32 v160, v122, v123
	v_cvt_pk_bf16_f32 v161, v124, v125
	global_store_dwordx2 v245, v[160:161], s[10:11]
	v_pk_mul_f32 v[126:127], v[126:127], v[248:249] op_sel_hi:[1,0]
	v_pk_add_f32 v[180:181], v[180:181], 1.0 op_sel_hi:[1,0]
	v_pk_mul_f32 v[126:127], v[6:7], v[126:127]
	v_pk_fma_f32 v[126:127], v[180:181], v[126:127], v[164:165]
	v_pk_mul_f32 v[128:129], v[128:129], v[248:249] op_sel_hi:[1,0]
	v_pk_add_f32 v[182:183], v[182:183], 1.0 op_sel_hi:[1,0]
	v_pk_mul_f32 v[128:129], v[8:9], v[128:129]
	v_pk_fma_f32 v[128:129], v[182:183], v[128:129], v[166:167]
	v_cvt_pk_bf16_f32 v164, v126, v127
	v_cvt_pk_bf16_f32 v165, v128, v129
	global_store_dwordx2 v245, v[164:165], s[10:11] offset:512
	v_pk_mul_f32 v[130:131], v[130:131], v[248:249] op_sel_hi:[1,0]
	v_pk_add_f32 v[184:185], v[184:185], 1.0 op_sel_hi:[1,0]
	v_pk_mul_f32 v[130:131], v[10:11], v[130:131]
	v_pk_fma_f32 v[130:131], v[184:185], v[130:131], v[168:169]
	v_pk_mul_f32 v[132:133], v[132:133], v[248:249] op_sel_hi:[1,0]
	v_pk_add_f32 v[186:187], v[186:187], 1.0 op_sel_hi:[1,0]
	v_pk_mul_f32 v[132:133], v[12:13], v[132:133]
	v_pk_fma_f32 v[132:133], v[186:187], v[132:133], v[170:171]
	v_cvt_pk_bf16_f32 v168, v130, v131
	v_cvt_pk_bf16_f32 v169, v132, v133
	global_store_dwordx2 v245, v[168:169], s[10:11] offset:1024
	v_pk_mul_f32 v[134:135], v[134:135], v[248:249] op_sel_hi:[1,0]
	v_pk_add_f32 v[188:189], v[188:189], 1.0 op_sel_hi:[1,0]
	v_pk_mul_f32 v[134:135], v[14:15], v[134:135]
	v_pk_fma_f32 v[134:135], v[188:189], v[134:135], v[172:173]
	v_pk_mul_f32 v[136:137], v[136:137], v[248:249] op_sel_hi:[1,0]
	v_pk_add_f32 v[190:191], v[190:191], 1.0 op_sel_hi:[1,0]
	v_pk_mul_f32 v[136:137], v[16:17], v[136:137]
	v_pk_fma_f32 v[136:137], v[190:191], v[136:137], v[174:175]
	v_cvt_pk_bf16_f32 v172, v134, v135
	v_cvt_pk_bf16_f32 v173, v136, v137
	global_store_dwordx2 v245, v[172:173], s[10:11] offset:1536
	s_waitcnt vmcnt(4)
	v_readfirstlane_b32 s6, v114
	s_cmp_ge_u32 s6, 8
	s_cbranch_scc1 .Ldep_norm2a_ok8
	s_add_i32 s6, s37, 8
	s_cmp_ge_u32 s6, 9
	s_cselect_b32 s38, 9, 0
	s_sub_i32 s6, s6, s38
	s_lshl_b32 s6, s6, 11
	s_add_i32 s6, s6, s20
	s_lshr_b32 s6, s6, 7
	s_lshl_b32 s6, s6, 2
	s_add_i32 s6, s6, 0x1c00
	v_mov_b32_e32 v110, s6

; DI unsigned pk_bf16(float lo, float hi) { f32x2 v = {lo, hi}; bf16v2 b = __builtin_convertvector(v, bf16v2); return __builtin_bit_cast(unsigned, b); }
; DI float red64(float x) { for (int o = 32; o > 0; o >>= 1) x += __shfl_xor(x, o); return x; }
; DI void modnorm_rows(const Params& p, int l, int which  , bool from_inputs, bool skip_ctx, int w0, int wstride, int lane) {
;     ...
;   for (; i < nrows; i += wstride) {
;     const int row = rowof(i); const int b = row / TB, s = row % TB;
;     f32x4 v[4];
; #pragma unroll
;     for (int q = 0; q < 4; ++q) v[q] = vn[q];
;     if (i + wstride < nrows) {
;       const int rn = rowof(i + wstride); const float* src = xsrc_row(p, from_inputs, rn / TB, rn % TB);
; #pragma unroll
;       for (int q = 0; q < 4; ++q) vn[q] = *(const f32x4*)(src + q * 256 + lane * 4);
;     }
;     const float* mod = p.MOD + (size_t)(l * 9 + (s < NCTX ? 8 : b)) * 6144 + (which ? 3 * 1024 : 0);
;     f32x4 sh[4], sc[4];
; #pragma unroll
;     for (int q = 0; q < 4; ++q) { sh[q] = *(const f32x4*)(mod + q * 256 + lane * 4); sc[q] = *(const f32x4*)(mod + 1024 + q * 256 + lane * 4); }
;     float ss = 0.f;
; #pragma unroll
;     for (int q = 0; q < 4; ++q) ss += v[q][0] * v[q][0] + v[q][1] * v[q][1] + v[q][2] * v[q][2] + v[q][3] * v[q][3];
;     ss = red64(ss);
;     const float rs = rsqrtf(ss * (1.f / 1024.f) + EPSF);
;     bf16_t* dst = p.HY + (size_t)row * DM;
; #pragma unroll
;     for (int q = 0; q < 4; ++q) {
;       float o[4];
; #pragma unroll
;       for (int j = 0; j < 4; ++j) o[j] = (v[q][j] * rs * gg[q][j]) * (1.f + sc[q][j]) + sh[q][j];
;       u32x2 w = {pk_bf16(o[0], o[1]), pk_bf16(o[2], o[3])};
;       *(u32x2*)(dst + q * 256 + lane * 4) = w;
;     }
;   }
.Ldep_norm2a_ok8:
	s_add_i32 s21, s37, 8
	s_cmp_ge_u32 s21, 9
	s_cselect_b32 s38, 9, 0
	s_sub_i32 s21, s21, s38
	s_lshl_b32 s21, s21, 11
	s_add_i32 s21, s21, s20
	s_mul_hi_u32 s7, s21, 0x38e38e39
	s_lshr_b32 s7, s7, 9
	s_mul_i32 s8, s7, 0x900
	s_sub_i32 s8, s21, s8
	s_lshl_b32 s9, s7, 11
	s_add_i32 s9, s9, s8
	s_add_i32 s9, s9, 0xffffff00
	s_lshl_b32 s10, s7, 8
	s_add_i32 s10, s10, s8
	s_cmpk_gt_i32 s8, 0xff
	s_cselect_b32 s9, s9, s10
	s_cselect_b32 s26, s12, s14
	s_cselect_b32 s27, s13, s15
	s_cselect_b32 s10, s7, 8
	s_lshl_b32 s9, s9, 12
	s_add_u32 s26, s26, s9
	s_addc_u32 s27, s27, 0
	s_add_i32 s10, s10, s82
	s_mul_i32 s10, s10, s24
	s_add_u32 s28, s58, s10
	s_addc_u32 s29, s59, 0
	s_add_u32 s28, s28, 0x3000
	s_addc_u32 s29, s29, 0
	s_add_u32 s0, s28, 0x1000
	s_addc_u32 s1, s29, 0
	global_load_dwordx4 v[122:125], v244, s[26:27] sc0 sc1
	global_load_dwordx4 v[126:129], v244, s[26:27] offset:1024 sc0 sc1
	global_load_dwordx4 v[130:133], v244, s[26:27] offset:2048 sc0 sc1
	global_load_dwordx4 v[134:137], v244, s[26:27] offset:3072 sc0 sc1
	global_load_dwordx4 v[160:163], v244, s[28:29]
	global_load_dwordx4 v[164:167], v244, s[28:29] offset:1024
	global_load_dwordx4 v[168:171], v244, s[28:29] offset:2048
	global_load_dwordx4 v[172:175], v244, s[28:29] offset:3072
	global_load_dwordx4 v[176:179], v244, s[0:1]
	global_load_dwordx4 v[180:183], v244, s[0:1] offset:1024
	global_load_dwordx4 v[184:187], v244, s[0:1] offset:2048
	global_load_dwordx4 v[188:191], v244, s[0:1] offset:3072
	s_waitcnt vmcnt(34)
	v_pk_mul_f32 v[246:247], v[18:19], v[18:19]
	v_pk_fma_f32 v[246:247], v[20:21], v[20:21], v[246:247]
	v_pk_fma_f32 v[246:247], v[22:23], v[22:23], v[246:247]
	v_pk_fma_f32 v[246:247], v[24:25], v[24:25], v[246:247]
	v_pk_fma_f32 v[246:247], v[26:27], v[26:27], v[246:247]
	v_pk_fma_f32 v[246:247], v[28:29], v[28:29], v[246:247]
	v_pk_fma_f32 v[246:247], v[30:31], v[30:31], v[246:247]
	v_pk_fma_f32 v[246:247], v[32:33], v[32:33], v[246:247]
	s_nop 0
	v_add_f32_e32 v246, v246, v247
	s_nop 1
	v_add_f32_dpp v246, v246, v246 quad_perm:[1,0,3,2] row_mask:0xf bank_mask:0xf
	s_nop 1
	v_add_f32_dpp v246, v246, v246 quad_perm:[2,3,0,1] row_mask:0xf bank_mask:0xf
	s_nop 1
	v_add_f32_dpp v246, v246, v246 row_half_mirror row_mask:0xf bank_mask:0xf
	s_nop 1
	v_add_f32_dpp v246, v246, v246 row_mirror row_mask:0xf bank_mask:0xf
	s_nop 1
	v_add_f32_dpp v246, v246, v246 row_bcast:15 row_mask:0xa bank_mask:0xf
	s_nop 1
	v_add_f32_dpp v246, v246, v246 row_bcast:31 row_mask:0xc bank_mask:0xf
	s_nop 1
	v_readlane_b32 s0, v246, 63
	s_add_i32 s21, s37, 6
	s_cmp_ge_u32 s21, 9
	s_cselect_b32 s38, 9, 0
	s_sub_i32 s21, s21, s38
	s_lshl_b32 s21, s21, 11
	s_add_i32 s21, s21, s20
	s_lshl_b32 s21, s21, 11
	s_add_u32 s10, s16, s21
	s_addc_u32 s11, s17, 0
	v_mov_b32_e32 v248, s0
	v_fmamk_f32 v248, v248, 0x3a800000, v143
	v_rsq_f32_e32 v248, v248
	s_nop 0
	v_pk_mul_f32 v[18:19], v[18:19], v[248:249] op_sel_hi:[1,0]
	v_pk_add_f32 v[50:51], v[50:51], 1.0 op_sel_hi:[1,0]
	v_pk_mul_f32 v[18:19], v[2:3], v[18:19]
	v_pk_fma_f32 v[18:19], v[50:51], v[18:19], v[34:35]
	v_pk_mul_f32 v[20:21], v[20:21], v[248:249] op_sel_hi:[1,0]
	v_pk_add_f32 v[52:53], v[52:53], 1.0 op_sel_hi:[1,0]
	v_pk_mul_f32 v[20:21], v[4:5], v[20:21]
	v_pk_fma_f32 v[20:21], v[52:53], v[20:21], v[36:37]
	v_cvt_pk_bf16_f32 v34, v18, v19
	v_cvt_pk_bf16_f32 v35, v20, v21
	global_store_dwordx2 v245, v[34:35], s[10:11]
	v_pk_mul_f32 v[22:23], v[22:23], v[248:249] op_sel_hi:[1,0]
	v_pk_add_f32 v[54:55], v[54:55], 1.0 op_sel_hi:[1,0]
	v_pk_mul_f32 v[22:23], v[6:7], v[22:23]
	v_pk_fma_f32 v[22:23], v[54:55], v[22:23], v[38:39]
	v_pk_mul_f32 v[24:25], v[24:25], v[248:249] op_sel_hi:[1,0]
	v_pk_add_f32 v[56:57], v[56:57], 1.0 op_sel_hi:[1,0]
	v_pk_mul_f32 v[24:25], v[8:9], v[24:25]
	v_pk_fma_f32 v[24:25], v[56:57], v[24:25], v[40:41]
	v_cvt_pk_bf16_f32 v38, v22, v23
	v_cvt_pk_bf16_f32 v39, v24, v25
	global_store_dwordx2 v245, v[38:39], s[10:11] offset:512
	v_pk_mul_f32 v[26:27], v[26:27], v[248:249] op_sel_hi:[1,0]
	v_pk_add_f32 v[58:59], v[58:59], 1.0 op_sel_hi:[1,0]
	v_pk_mul_f32 v[26:27], v[10:11], v[26:27]
	v_pk_fma_f32 v[26:27], v[58:59], v[26:27], v[42:43]
	v_pk_mul_f32 v[28:29], v[28:29], v[248:249] op_sel_hi:[1,0]
	v_pk_add_f32 v[60:61], v[60:61], 1.0 op_sel_hi:[1,0]
	v_pk_mul_f32 v[28:29], v[12:13], v[28:29]
	v_pk_fma_f32 v[28:29], v[60:61], v[28:29], v[44:45]
	v_cvt_pk_bf16_f32 v42, v26, v27
	v_cvt_pk_bf16_f32 v43, v28, v29
	global_store_dwordx2 v245, v[42:43], s[10:11] offset:1024
	v_pk_mul_f32 v[30:31], v[30:31], v[248:249] op_sel_hi:[1,0]
	v_pk_add_f32 v[62:63], v[62:63], 1.0 op_sel_hi:[1,0]
	v_pk_mul_f32 v[30:31], v[14:15], v[30:31]
	v_pk_fma_f32 v[30:31], v[62:63], v[30:31], v[46:47]
	v_pk_mul_f32 v[32:33], v[32:33], v[248:249] op_sel_hi:[1,0]
	v_pk_add_f32 v[64:65], v[64:65], 1.0 op_sel_hi:[1,0]
	v_pk_mul_f32 v[32:33], v[16:17], v[32:33]
	v_pk_fma_f32 v[32:33], v[64:65], v[32:33], v[48:49]
	v_cvt_pk_bf16_f32 v46, v30, v31
	v_cvt_pk_bf16_f32 v47, v32, v33
	global_store_dwordx2 v245, v[46:47], s[10:11] offset:1536
	s_waitcnt vmcnt(21)
; DI unsigned pk_bf16(float lo, float hi) { f32x2 v = {lo, hi}; bf16v2 b = __builtin_convertvector(v, bf16v2); return __builtin_bit_cast(unsigned, b); }
; DI float red64(float x) { for (int o = 32; o > 0; o >>= 1) x += __shfl_xor(x, o); return x; }
; DI void modnorm_rows(const Params& p, int l, int which  , bool from_inputs, bool skip_ctx, int w0, int wstride, int lane) {
;     ...
;     for (int q = 0; q < 4; ++q) { sh[q] = *(const f32x4*)(mod + q * 256 + lane * 4); sc[q] = *(const f32x4*)(mod + 1024 + q * 256 + lane * 4); }
;     float ss = 0.f;
; #pragma unroll
;     for (int q = 0; q < 4; ++q) ss += v[q][0] * v[q][0] + v[q][1] * v[q][1] + v[q][2] * v[q][2] + v[q][3] * v[q][3];
;     ss = red64(ss);
;     const float rs = rsqrtf(ss * (1.f / 1024.f) + EPSF);
;     bf16_t* dst = p.HY + (size_t)row * DM;
; #pragma unroll
;     for (int q = 0; q < 4; ++q) {
;       float o[4];
; #pragma unroll
;       for (int j = 0; j < 4; ++j) o[j] = (v[q][j] * rs * gg[q][j]) * (1.f + sc[q][j]) + sh[q][j];
;       u32x2 w = {pk_bf16(o[0], o[1]), pk_bf16(o[2], o[3])};
;       *(u32x2*)(dst + q * 256 + lane * 4) = w;
;     }
;   }
	v_pk_mul_f32 v[246:247], v[66:67], v[66:67]
	v_pk_fma_f32 v[246:247], v[68:69], v[68:69], v[246:247]
	v_pk_fma_f32 v[246:247], v[70:71], v[70:71], v[246:247]
	v_pk_fma_f32 v[246:247], v[72:73], v[72:73], v[246:247]
	v_pk_fma_f32 v[246:247], v[74:75], v[74:75], v[246:247]
	v_pk_fma_f32 v[246:247], v[76:77], v[76:77], v[246:247]
	v_pk_fma_f32 v[246:247], v[78:79], v[78:79], v[246:247]
	v_pk_fma_f32 v[246:247], v[80:81], v[80:81], v[246:247]
	s_nop 0
	v_add_f32_e32 v246, v246, v247
	s_nop 1
	v_add_f32_dpp v246, v246, v246 quad_perm:[1,0,3,2] row_mask:0xf bank_mask:0xf
	s_nop 1
	v_add_f32_dpp v246, v246, v246 quad_perm:[2,3,0,1] row_mask:0xf bank_mask:0xf
	s_nop 1
	v_add_f32_dpp v246, v246, v246 row_half_mirror row_mask:0xf bank_mask:0xf
	s_nop 1
	v_add_f32_dpp v246, v246, v246 row_mirror row_mask:0xf bank_mask:0xf
	s_nop 1
	v_add_f32_dpp v246, v246, v246 row_bcast:15 row_mask:0xa bank_mask:0xf
	s_nop 1
	v_add_f32_dpp v246, v246, v246 row_bcast:31 row_mask:0xc bank_mask:0xf
	s_nop 1
	v_readlane_b32 s0, v246, 63
	s_add_i32 s21, s37, 7
	s_cmp_ge_u32 s21, 9
	s_cselect_b32 s38, 9, 0
	s_sub_i32 s21, s21, s38
	s_lshl_b32 s21, s21, 11
	s_add_i32 s21, s21, s20
	s_lshl_b32 s21, s21, 11
	s_add_u32 s10, s16, s21
	s_addc_u32 s11, s17, 0
	v_mov_b32_e32 v248, s0
	v_fmamk_f32 v248, v248, 0x3a800000, v143
	v_rsq_f32_e32 v248, v248
	s_nop 0
	v_pk_mul_f32 v[66:67], v[66:67], v[248:249] op_sel_hi:[1,0]
	v_pk_add_f32 v[98:99], v[98:99], 1.0 op_sel_hi:[1,0]
	v_pk_mul_f32 v[66:67], v[2:3], v[66:67]
	v_pk_fma_f32 v[66:67], v[98:99], v[66:67], v[82:83]
	v_pk_mul_f32 v[68:69], v[68:69], v[248:249] op_sel_hi:[1,0]
	v_pk_add_f32 v[100:101], v[100:101], 1.0 op_sel_hi:[1,0]
	v_pk_mul_f32 v[68:69], v[4:5], v[68:69]
	v_pk_fma_f32 v[68:69], v[100:101], v[68:69], v[84:85]
	v_cvt_pk_bf16_f32 v82, v66, v67
	v_cvt_pk_bf16_f32 v83, v68, v69
	global_store_dwordx2 v245, v[82:83], s[10:11]
	v_pk_mul_f32 v[70:71], v[70:71], v[248:249] op_sel_hi:[1,0]
	v_pk_add_f32 v[102:103], v[102:103], 1.0 op_sel_hi:[1,0]
	v_pk_mul_f32 v[70:71], v[6:7], v[70:71]
	v_pk_fma_f32 v[70:71], v[102:103], v[70:71], v[86:87]
	v_pk_mul_f32 v[72:73], v[72:73], v[248:249] op_sel_hi:[1,0]
	v_pk_add_f32 v[104:105], v[104:105], 1.0 op_sel_hi:[1,0]
	v_pk_mul_f32 v[72:73], v[8:9], v[72:73]
	v_pk_fma_f32 v[72:73], v[104:105], v[72:73], v[88:89]
	v_cvt_pk_bf16_f32 v86, v70, v71
	v_cvt_pk_bf16_f32 v87, v72, v73
	global_store_dwordx2 v245, v[86:87], s[10:11] offset:512
	v_pk_mul_f32 v[74:75], v[74:75], v[248:249] op_sel_hi:[1,0]
	v_pk_add_f32 v[106:107], v[106:107], 1.0 op_sel_hi:[1,0]
	v_pk_mul_f32 v[74:75], v[10:11], v[74:75]
	v_pk_fma_f32 v[74:75], v[106:107], v[74:75], v[90:91]
	v_pk_mul_f32 v[76:77], v[76:77], v[248:249] op_sel_hi:[1,0]
	v_pk_add_f32 v[108:109], v[108:109], 1.0 op_sel_hi:[1,0]
	v_pk_mul_f32 v[76:77], v[12:13], v[76:77]
	v_pk_fma_f32 v[76:77], v[108:109], v[76:77], v[92:93]
	v_cvt_pk_bf16_f32 v90, v74, v75
	v_cvt_pk_bf16_f32 v91, v76, v77
	global_store_dwordx2 v245, v[90:91], s[10:11] offset:1024
	v_pk_mul_f32 v[78:79], v[78:79], v[248:249] op_sel_hi:[1,0]
	v_pk_add_f32 v[118:119], v[118:119], 1.0 op_sel_hi:[1,0]
	v_pk_mul_f32 v[78:79], v[14:15], v[78:79]
	v_pk_fma_f32 v[78:79], v[118:119], v[78:79], v[94:95]
	v_pk_mul_f32 v[80:81], v[80:81], v[248:249] op_sel_hi:[1,0]
	v_pk_add_f32 v[120:121], v[120:121], 1.0 op_sel_hi:[1,0]
	v_pk_mul_f32 v[80:81], v[16:17], v[80:81]
	v_pk_fma_f32 v[80:81], v[120:121], v[80:81], v[96:97]
	v_cvt_pk_bf16_f32 v94, v78, v79
	v_cvt_pk_bf16_f32 v95, v80, v81
	global_store_dwordx2 v245, v[94:95], s[10:11] offset:1536
	s_waitcnt vmcnt(8)
; DI unsigned pk_bf16(float lo, float hi) { f32x2 v = {lo, hi}; bf16v2 b = __builtin_convertvector(v, bf16v2); return __builtin_bit_cast(unsigned, b); }
; DI float red64(float x) { for (int o = 32; o > 0; o >>= 1) x += __shfl_xor(x, o); return x; }
; DI void modnorm_rows(const Params& p, int l, int which  , bool from_inputs, bool skip_ctx, int w0, int wstride, int lane) {
;     ...
;     for (int q = 0; q < 4; ++q) { sh[q] = *(const f32x4*)(mod + q * 256 + lane * 4); sc[q] = *(const f32x4*)(mod + 1024 + q * 256 + lane * 4); }
;     float ss = 0.f;
; #pragma unroll
;     for (int q = 0; q < 4; ++q) ss += v[q][0] * v[q][0] + v[q][1] * v[q][1] + v[q][2] * v[q][2] + v[q][3] * v[q][3];
;     ss = red64(ss);
;     const float rs = rsqrtf(ss * (1.f / 1024.f) + EPSF);
;     bf16_t* dst = p.HY + (size_t)row * DM;
; #pragma unroll
;     for (int q = 0; q < 4; ++q) {
;       float o[4];
; #pragma unroll
;       for (int j = 0; j < 4; ++j) o[j] = (v[q][j] * rs * gg[q][j]) * (1.f + sc[q][j]) + sh[q][j];
;       u32x2 w = {pk_bf16(o[0], o[1]), pk_bf16(o[2], o[3])};
;       *(u32x2*)(dst + q * 256 + lane * 4) = w;
;     }
;   }
	v_pk_mul_f32 v[246:247], v[122:123], v[122:123]
	v_pk_fma_f32 v[246:247], v[124:125], v[124:125], v[246:247]
	v_pk_fma_f32 v[246:247], v[126:127], v[126:127], v[246:247]
	v_pk_fma_f32 v[246:247], v[128:129], v[128:129], v[246:247]
	v_pk_fma_f32 v[246:247], v[130:131], v[130:131], v[246:247]
	v_pk_fma_f32 v[246:247], v[132:133], v[132:133], v[246:247]
	v_pk_fma_f32 v[246:247], v[134:135], v[134:135], v[246:247]
	v_pk_fma_f32 v[246:247], v[136:137], v[136:137], v[246:247]
	s_nop 0
	v_add_f32_e32 v246, v246, v247
	s_nop 1
	v_add_f32_dpp v246, v246, v246 quad_perm:[1,0,3,2] row_mask:0xf bank_mask:0xf
	s_nop 1
	v_add_f32_dpp v246, v246, v246 quad_perm:[2,3,0,1] row_mask:0xf bank_mask:0xf
	s_nop 1
	v_add_f32_dpp v246, v246, v246 row_half_mirror row_mask:0xf bank_mask:0xf
	s_nop 1
	v_add_f32_dpp v246, v246, v246 row_mirror row_mask:0xf bank_mask:0xf
	s_nop 1
	v_add_f32_dpp v246, v246, v246 row_bcast:15 row_mask:0xa bank_mask:0xf
	s_nop 1
	v_add_f32_dpp v246, v246, v246 row_bcast:31 row_mask:0xc bank_mask:0xf
	s_nop 1
	v_readlane_b32 s0, v246, 63
	s_add_i32 s21, s37, 8
	s_cmp_ge_u32 s21, 9
	s_cselect_b32 s38, 9, 0
	s_sub_i32 s21, s21, s38
	s_lshl_b32 s21, s21, 11
	s_add_i32 s21, s21, s20
	s_lshl_b32 s21, s21, 11
	s_add_u32 s10, s16, s21
	s_addc_u32 s11, s17, 0
	v_mov_b32_e32 v248, s0
	v_fmamk_f32 v248, v248, 0x3a800000, v143
	v_rsq_f32_e32 v248, v248
	s_nop 0
	v_pk_mul_f32 v[122:123], v[122:123], v[248:249] op_sel_hi:[1,0]
	v_pk_add_f32 v[176:177], v[176:177], 1.0 op_sel_hi:[1,0]
	v_pk_mul_f32 v[122:123], v[2:3], v[122:123]
	v_pk_fma_f32 v[122:123], v[176:177], v[122:123], v[160:161]
	v_pk_mul_f32 v[124:125], v[124:125], v[248:249] op_sel_hi:[1,0]
	v_pk_add_f32 v[178:179], v[178:179], 1.0 op_sel_hi:[1,0]
	v_pk_mul_f32 v[124:125], v[4:5], v[124:125]
	v_pk_fma_f32 v[124:125], v[178:179], v[124:125], v[162:163]
	v_cvt_pk_bf16_f32 v160, v122, v123
	v_cvt_pk_bf16_f32 v161, v124, v125
	global_store_dwordx2 v245, v[160:161], s[10:11]
	v_pk_mul_f32 v[126:127], v[126:127], v[248:249] op_sel_hi:[1,0]
	v_pk_add_f32 v[180:181], v[180:181], 1.0 op_sel_hi:[1,0]
	v_pk_mul_f32 v[126:127], v[6:7], v[126:127]
	v_pk_fma_f32 v[126:127], v[180:181], v[126:127], v[164:165]
	v_pk_mul_f32 v[128:129], v[128:129], v[248:249] op_sel_hi:[1,0]
	v_pk_add_f32 v[182:183], v[182:183], 1.0 op_sel_hi:[1,0]
	v_pk_mul_f32 v[128:129], v[8:9], v[128:129]
	v_pk_fma_f32 v[128:129], v[182:183], v[128:129], v[166:167]
	v_cvt_pk_bf16_f32 v164, v126, v127
	v_cvt_pk_bf16_f32 v165, v128, v129
	global_store_dwordx2 v245, v[164:165], s[10:11] offset:512
	v_pk_mul_f32 v[130:131], v[130:131], v[248:249] op_sel_hi:[1,0]
	v_pk_add_f32 v[184:185], v[184:185], 1.0 op_sel_hi:[1,0]
	v_pk_mul_f32 v[130:131], v[10:11], v[130:131]
	v_pk_fma_f32 v[130:131], v[184:185], v[130:131], v[168:169]
	v_pk_mul_f32 v[132:133], v[132:133], v[248:249] op_sel_hi:[1,0]
	v_pk_add_f32 v[186:187], v[186:187], 1.0 op_sel_hi:[1,0]
	v_pk_mul_f32 v[132:133], v[12:13], v[132:133]
	v_pk_fma_f32 v[132:133], v[186:187], v[132:133], v[170:171]
	v_cvt_pk_bf16_f32 v168, v130, v131
	v_cvt_pk_bf16_f32 v169, v132, v133
	global_store_dwordx2 v245, v[168:169], s[10:11] offset:1024
	v_pk_mul_f32 v[134:135], v[134:135], v[248:249] op_sel_hi:[1,0]
	v_pk_add_f32 v[188:189], v[188:189], 1.0 op_sel_hi:[1,0]
	v_pk_mul_f32 v[134:135], v[14:15], v[134:135]
	v_pk_fma_f32 v[134:135], v[188:189], v[134:135], v[172:173]
	v_pk_mul_f32 v[136:137], v[136:137], v[248:249] op_sel_hi:[1,0]
	v_pk_add_f32 v[190:191], v[190:191], 1.0 op_sel_hi:[1,0]
	v_pk_mul_f32 v[136:137], v[16:17], v[136:137]
	v_pk_fma_f32 v[136:137], v[190:191], v[136:137], v[174:175]
	v_cvt_pk_bf16_f32 v172, v134, v135
	v_cvt_pk_bf16_f32 v173, v136, v137
	global_store_dwordx2 v245, v[172:173], s[10:11] offset:1536
	s_branch .Lnorm2_done

; template <class Epi>
; DI void gemm_tile(const bf16_t* __restrict__ A, int lda, const bf16_t* __restrict__ Bt, int ldb, int K, int row0, int col0, char* lds, const Epi& epi) {
;     ...
;   for (int kt = 0; kt < KT; ++kt) {
;     asm volatile("s_waitcnt vmcnt(0)" ::: "memory");
;     __syncthreads();
;     const char* sa = lds + (kt & 1) * 32768 + (wr * 64 + fr) * 128;
;     const char* sb = lds + (kt & 1) * 32768 + 16384 + (wc * 64 + fr) * 128;
; #pragma unroll
;     for (int kk = 0; kk < 2; ++kk) {
;       if (kt + 1 < KT) { if (kk == 0) stage_a(kt + 1, (kt + 1) & 1); else stage_b(kt + 1, (kt + 1) & 1); }
;       bf16x8 a[4], b[4];
;       const int co = ((kk * 4 + fq) ^ swz) * 16;
; #pragma unroll
;       for (int m = 0; m < 4; ++m) a[m] = *(const bf16x8*)(sa + m * 2048 + co);
; #pragma unroll
;       for (int n = 0; n < 4; ++n) b[n] = *(const bf16x8*)(sb + n * 2048 + co);
; #pragma unroll
;       for (int m = 0; m < 4; ++m)
; #pragma unroll
;         for (int n = 0; n < 4; ++n) acc[m][n] = __builtin_amdgcn_mfma_f32_16x16x32_bf16(b[n], a[m], acc[m][n], 0, 0, 0);
;     }
;   }
.LBB0_267:
	s_add_i32 s20, s3, 0xffff8000
	s_and_b32 s29, s3, 0x8000
	s_and_b32 s20, s20, 0x8000
	v_add_u32_e32 v102, s29, v90
	v_add_u32_e32 v110, s20, v91
	v_or_b32_e32 v136, s20, v93
	v_add_u32_e32 v103, 0x1000, v102
	v_readfirstlane_b32 s20, v102
	v_lshl_add_u64 v[94:95], v[74:75], 0, s[0:1]
	v_add_u32_e32 v104, 0x2000, v102
	s_mov_b32 m0, s20
	v_readfirstlane_b32 s20, v103
	s_waitcnt vmcnt(0)
	s_waitcnt vmcnt(0) lgkmcnt(0)
	s_barrier
	v_lshl_add_u64 v[96:97], v[76:77], 0, s[0:1]
	v_add_u32_e32 v105, 0x3000, v102
	global_load_lds_dwordx4 v[94:95], off
	s_mov_b32 m0, s20
	v_readfirstlane_b32 s20, v104
	v_add_u32_e32 v137, 0x4000, v102
	v_lshl_add_u64 v[98:99], v[78:79], 0, s[0:1]
	global_load_lds_dwordx4 v[96:97], off
	s_mov_b32 m0, s20
	v_readfirstlane_b32 s20, v105
	v_add_u32_e32 v159, 0x5000, v102
	v_lshl_add_u64 v[100:101], v[80:81], 0, s[0:1]
	global_load_lds_dwordx4 v[98:99], off
	s_mov_b32 m0, s20
	v_readfirstlane_b32 s20, v137
	v_lshl_add_u64 v[132:133], v[66:67], 0, s[0:1]
	v_add_u32_e32 v160, 0x6000, v102
	global_load_lds_dwordx4 v[100:101], off
	v_add_u32_e32 v106, v110, v92
	v_add_u32_e32 v128, v136, v92
	s_mov_b32 m0, s20
	v_readfirstlane_b32 s20, v159
	v_lshl_add_u64 v[134:135], v[68:69], 0, s[0:1]
	v_add_u32_e32 v161, 0x7000, v102
	ds_read_b128 v[94:97], v106
	ds_read_b128 v[98:101], v106 offset:2048
	ds_read_b128 v[102:105], v106 offset:4096
	ds_read_b128 v[106:109], v106 offset:6144
	ds_read_b128 v[116:119], v128 offset:16384
	ds_read_b128 v[120:123], v128 offset:18432
	ds_read_b128 v[124:127], v128 offset:20480
	ds_read_b128 v[128:131], v128 offset:22528
	global_load_lds_dwordx4 v[132:133], off
	s_mov_b32 m0, s20
	v_readfirstlane_b32 s20, v160
	v_lshl_add_u64 v[84:85], v[70:71], 0, s[0:1]
	global_load_lds_dwordx4 v[134:135], off
	s_mov_b32 m0, s20
	v_readfirstlane_b32 s20, v161
	v_lshl_add_u64 v[82:83], v[72:73], 0, s[0:1]
	global_load_lds_dwordx4 v[84:85], off
	s_mov_b32 m0, s20
	s_waitcnt lgkmcnt(0)
	v_mfma_f32_16x16x32_bf16 v[30:33], v[116:119], v[102:105], v[30:33]
	global_load_lds_dwordx4 v[82:83], off
	s_add_u32 s0, s0, 0x80
	v_mfma_f32_16x16x32_bf16 v[26:29], v[120:123], v[102:105], v[26:29]
	s_addc_u32 s1, s1, 0
	s_add_i32 s3, s3, 0x8000
	s_cmpk_eq_i32 s0, 0x780
	v_mfma_f32_16x16x32_bf16 v[22:25], v[124:127], v[102:105], v[22:25]
	v_mfma_f32_16x16x32_bf16 v[18:21], v[128:131], v[102:105], v[18:21]
	v_add_u32_e32 v102, v110, v89
	v_add_u32_e32 v110, v136, v89
	v_mfma_f32_16x16x32_bf16 v[62:65], v[116:119], v[94:97], v[62:65]
	v_mfma_f32_16x16x32_bf16 v[58:61], v[120:123], v[94:97], v[58:61]
	v_mfma_f32_16x16x32_bf16 v[54:57], v[124:127], v[94:97], v[54:57]
	v_mfma_f32_16x16x32_bf16 v[50:53], v[128:131], v[94:97], v[50:53]
	v_mfma_f32_16x16x32_bf16 v[46:49], v[116:119], v[98:101], v[46:49]
	v_mfma_f32_16x16x32_bf16 v[42:45], v[120:123], v[98:101], v[42:45]
	v_mfma_f32_16x16x32_bf16 v[38:41], v[124:127], v[98:101], v[38:41]
	v_mfma_f32_16x16x32_bf16 v[34:37], v[128:131], v[98:101], v[34:37]
	ds_read_b128 v[82:85], v102
	ds_read_b128 v[94:97], v102 offset:2048
	ds_read_b128 v[98:101], v102 offset:4096
	ds_read_b128 v[102:105], v102 offset:6144
	v_mfma_f32_16x16x32_bf16 v[14:17], v[116:119], v[106:109], v[14:17]
	v_mfma_f32_16x16x32_bf16 v[10:13], v[120:123], v[106:109], v[10:13]
	v_mfma_f32_16x16x32_bf16 v[6:9], v[124:127], v[106:109], v[6:9]
	v_mfma_f32_16x16x32_bf16 v[2:5], v[128:131], v[106:109], v[2:5]
	ds_read_b128 v[106:109], v110 offset:16384
	ds_read_b128 v[116:119], v110 offset:18432
	ds_read_b128 v[120:123], v110 offset:20480
	ds_read_b128 v[124:127], v110 offset:22528
	s_waitcnt lgkmcnt(0)
	v_mfma_f32_16x16x32_bf16 v[62:65], v[106:109], v[82:85], v[62:65]
	v_mfma_f32_16x16x32_bf16 v[58:61], v[116:119], v[82:85], v[58:61]
	v_mfma_f32_16x16x32_bf16 v[54:57], v[120:123], v[82:85], v[54:57]
	v_mfma_f32_16x16x32_bf16 v[50:53], v[124:127], v[82:85], v[50:53]
	v_mfma_f32_16x16x32_bf16 v[46:49], v[106:109], v[94:97], v[46:49]
	v_mfma_f32_16x16x32_bf16 v[42:45], v[116:119], v[94:97], v[42:45]
	v_mfma_f32_16x16x32_bf16 v[38:41], v[120:123], v[94:97], v[38:41]
	v_mfma_f32_16x16x32_bf16 v[34:37], v[124:127], v[94:97], v[34:37]
	v_mfma_f32_16x16x32_bf16 v[30:33], v[106:109], v[98:101], v[30:33]
	v_mfma_f32_16x16x32_bf16 v[26:29], v[116:119], v[98:101], v[26:29]
	v_mfma_f32_16x16x32_bf16 v[22:25], v[120:123], v[98:101], v[22:25]
	v_mfma_f32_16x16x32_bf16 v[18:21], v[124:127], v[98:101], v[18:21]
	v_mfma_f32_16x16x32_bf16 v[14:17], v[106:109], v[102:105], v[14:17]
	v_mfma_f32_16x16x32_bf16 v[10:13], v[116:119], v[102:105], v[10:13]
	v_mfma_f32_16x16x32_bf16 v[6:9], v[120:123], v[102:105], v[6:9]
	v_mfma_f32_16x16x32_bf16 v[2:5], v[124:127], v[102:105], v[2:5]
	s_cbranch_scc0 .LBB0_267
	v_add_u32_e32 v90, s29, v93
	v_add_u32_e32 v91, s29, v91
	v_add_u32_e32 v82, v90, v92
	v_add_u32_e32 v92, v91, v92
	s_waitcnt vmcnt(0)
	s_waitcnt vmcnt(0)
	s_barrier
; template <class Epi>
; DI void gemm_tile(const bf16_t* __restrict__ A, int lda, const bf16_t* __restrict__ Bt, int ldb, int K, int row0, int col0, char* lds, const Epi& epi) {
;     ...
;     for (int kk = 0; kk < 2; ++kk) {
;       if (kt + 1 < KT) { if (kk == 0) stage_a(kt + 1, (kt + 1) & 1); else stage_b(kt + 1, (kt + 1) & 1); }
;       bf16x8 a[4], b[4];
;       const int co = ((kk * 4 + fq) ^ swz) * 16;
; #pragma unroll
;       for (int m = 0; m < 4; ++m) a[m] = *(const bf16x8*)(sa + m * 2048 + co);
; #pragma unroll
;       for (int n = 0; n < 4; ++n) b[n] = *(const bf16x8*)(sb + n * 2048 + co);
; #pragma unroll
;       for (int m = 0; m < 4; ++m)
; #pragma unroll
;         for (int n = 0; n < 4; ++n) acc[m][n] = __builtin_amdgcn_mfma_f32_16x16x32_bf16(b[n], a[m], acc[m][n], 0, 0, 0);
;     }
;   }
;   DI void operator()(const f32x4 (&acc)[4][4], int r0, int c0, int fr, int fq) const {
; #pragma unroll
;     for (int m = 0; m < 4; ++m) {
;       const int row = r0 + m * 16 + fr; const int b = row / TB, s = row % TB;
;       const float* src = xsrc_row(*p, from_inputs, b, s);
;       float* dst = xdst_row(*p, b, s);
;       const float* gate = p->MOD + (size_t)(l * 9 + (s < NCTX ? 8 : b)) * 6144 + gate_off;
; #pragma unroll
;       for (int n = 0; n < 4; ++n) {
;         const int col = c0 + n * 16 + fq * 4;
;         f32x4 g = *(const f32x4*)(gate + col), xv = *(const f32x4*)(src + col);
	ds_read_b128 v[66:69], v82 offset:16384
	ds_read_b128 v[74:77], v82 offset:18432
	ds_read_b128 v[70:73], v92
	ds_read_b128 v[78:81], v82 offset:20480
	ds_read_b128 v[82:85], v82 offset:22528
	s_waitcnt lgkmcnt(2)
	v_mfma_f32_16x16x32_bf16 v[62:65], v[66:69], v[70:73], v[62:65]
	s_and_b64 vcc, exec, s[38:39]
	v_mfma_f32_16x16x32_bf16 v[58:61], v[74:77], v[70:73], v[58:61]
	s_waitcnt lgkmcnt(1)
	v_mfma_f32_16x16x32_bf16 v[54:57], v[78:81], v[70:73], v[54:57]
	s_waitcnt lgkmcnt(0)
	v_mfma_f32_16x16x32_bf16 v[50:53], v[82:85], v[70:73], v[50:53]
	ds_read_b128 v[70:73], v92 offset:2048
	s_waitcnt lgkmcnt(0)
	v_mfma_f32_16x16x32_bf16 v[46:49], v[66:69], v[70:73], v[46:49]
	v_mfma_f32_16x16x32_bf16 v[42:45], v[74:77], v[70:73], v[42:45]
	v_mfma_f32_16x16x32_bf16 v[38:41], v[78:81], v[70:73], v[38:41]
	v_mfma_f32_16x16x32_bf16 v[34:37], v[82:85], v[70:73], v[34:37]
	ds_read_b128 v[70:73], v92 offset:4096
	s_waitcnt lgkmcnt(0)
	v_mfma_f32_16x16x32_bf16 v[30:33], v[66:69], v[70:73], v[30:33]
	v_mfma_f32_16x16x32_bf16 v[26:29], v[74:77], v[70:73], v[26:29]
	v_mfma_f32_16x16x32_bf16 v[22:25], v[78:81], v[70:73], v[22:25]
	v_mfma_f32_16x16x32_bf16 v[18:21], v[82:85], v[70:73], v[18:21]
	ds_read_b128 v[70:73], v92 offset:6144
	s_waitcnt lgkmcnt(0)
	v_mfma_f32_16x16x32_bf16 v[10:13], v[74:77], v[70:73], v[10:13]
	v_add_u32_e32 v74, v90, v89
	v_add_u32_e32 v75, v91, v89
	ds_read_b128 v[90:93], v74 offset:22528
	v_mfma_f32_16x16x32_bf16 v[14:17], v[66:69], v[70:73], v[14:17]
	ds_read_b128 v[66:69], v74 offset:16384
	v_mfma_f32_16x16x32_bf16 v[6:9], v[78:81], v[70:73], v[6:9]
	ds_read_b128 v[76:79], v74 offset:18432
	v_mfma_f32_16x16x32_bf16 v[2:5], v[82:85], v[70:73], v[2:5]
	ds_read_b128 v[80:83], v74 offset:20480
	ds_read_b128 v[70:73], v75
	v_or_b32_e32 v74, s2, v87
	s_waitcnt lgkmcnt(0)
	v_mfma_f32_16x16x32_bf16 v[62:65], v[66:69], v[70:73], v[62:65]
	v_lshl_add_u32 v74, v88, 6, v74
	s_mov_b64 s[2:3], -1
	v_mfma_f32_16x16x32_bf16 v[58:61], v[76:79], v[70:73], v[58:61]
	v_mfma_f32_16x16x32_bf16 v[54:57], v[80:83], v[70:73], v[54:57]
	v_mfma_f32_16x16x32_bf16 v[50:53], v[90:93], v[70:73], v[50:53]
	ds_read_b128 v[70:73], v75 offset:2048
	s_waitcnt lgkmcnt(0)
	v_mfma_f32_16x16x32_bf16 v[46:49], v[66:69], v[70:73], v[46:49]
	v_mfma_f32_16x16x32_bf16 v[42:45], v[76:79], v[70:73], v[42:45]
	v_mfma_f32_16x16x32_bf16 v[38:41], v[80:83], v[70:73], v[38:41]
	v_mfma_f32_16x16x32_bf16 v[34:37], v[90:93], v[70:73], v[34:37]
	ds_read_b128 v[70:73], v75 offset:4096
	s_waitcnt lgkmcnt(0)
	v_mfma_f32_16x16x32_bf16 v[30:33], v[66:69], v[70:73], v[30:33]
	v_mfma_f32_16x16x32_bf16 v[26:29], v[76:79], v[70:73], v[26:29]
	v_mfma_f32_16x16x32_bf16 v[22:25], v[80:83], v[70:73], v[22:25]
	v_mfma_f32_16x16x32_bf16 v[18:21], v[90:93], v[70:73], v[18:21]
	ds_read_b128 v[70:73], v75 offset:6144
	s_waitcnt lgkmcnt(0)
	v_mfma_f32_16x16x32_bf16 v[14:17], v[66:69], v[70:73], v[14:17]
	v_mul_hi_i32 v66, v74, s47
	v_lshrrev_b32_e32 v67, 31, v66
	v_ashrrev_i32_e32 v66, 9, v66
	v_mfma_f32_16x16x32_bf16 v[10:13], v[76:79], v[70:73], v[10:13]
	v_add_u32_e32 v75, v66, v67
	v_mul_i32_i24_e32 v66, 0x900, v75
	v_sub_u32_e32 v67, v74, v66
	v_mfma_f32_16x16x32_bf16 v[6:9], v[80:83], v[70:73], v[6:9]
	v_cmp_lt_i32_e64 s[0:1], s33, v67
	v_mfma_f32_16x16x32_bf16 v[2:5], v[90:93], v[70:73], v[2:5]
	v_readlane_b32 s4, v254, 28
	v_readlane_b32 s5, v254, 29
	v_readlane_b32 s8, v254, 32
	v_readlane_b32 s9, v254, 33
	s_nop 3
	s_cmp_lg_u64 s[38:39], 0
	s_cselect_b32 s4, s56, s4
	s_cselect_b32 s5, s57, s5
	s_cselect_b32 s8, s64, s8
	s_cselect_b32 s9, s65, s9
	v_lshlrev_b32_e32 v1, 6, v1
	v_lshlrev_b32_e32 v67, 2, v86
	v_or3_b32 v80, v1, v67, s28
	v_lshlrev_b32_e32 v66, 2, v80
	v_mov_b32_e32 v67, 0
	v_mov_b32_e32 v100, s8
	v_mov_b32_e32 v101, s9
	v_mov_b32_e32 v102, s4
	v_mov_b32_e32 v103, s5
	v_mov_b32_e32 v104, s64
	v_mov_b32_e32 v105, s65
	v_mov_b32_e32 v106, s56
	v_mov_b32_e32 v107, s57
	s_add_u32 s0, s58, 0x2000
	s_addc_u32 s1, s59, 0
	v_mov_b32_e32 v108, s0
	v_mov_b32_e32 v109, s1
	v_mov_b32_e32 v110, 8
	v_mov_b32_e32 v88, v74
	v_mul_hi_i32 v89, v88, s47
	v_lshrrev_b32_e32 v90, 31, v89
	v_ashrrev_i32_e32 v89, 9, v89
	v_add_u32_e32 v91, v89, v90
	v_mul_i32_i24_e32 v89, 0x900, v91
	v_sub_u32_e32 v92, v88, v89
	v_cmp_lt_i32_e32 vcc, s33, v92
	v_lshlrev_b32_e32 v89, 11, v91
	v_add3_u32 v89, v92, v89, s75
	v_lshl_add_u32 v90, v91, 8, v92
	v_cndmask_b32_e32 v94, v90, v89, vcc
	v_ashrrev_i32_e32 v95, 31, v94
	v_lshlrev_b64 v[96:97], 12, v[94:95]
	v_lshl_add_u64 v[96:97], v[96:97], 0, v[66:67]
	v_cndmask_b32_e32 v98, v100, v102, vcc
	v_cndmask_b32_e32 v99, v101, v103, vcc
	v_lshl_add_u64 v[224:225], v[98:99], 0, v[96:97]
	v_cndmask_b32_e32 v98, v104, v106, vcc
	v_cndmask_b32_e32 v99, v105, v107, vcc
	v_lshl_add_u64 v[232:233], v[98:99], 0, v[96:97]
	v_cndmask_b32_e32 v93, v110, v91, vcc
	v_add_u32_e32 v93, s82, v93
	v_mad_i64_i32 v[240:241], s[0:1], v93, s24, v[108:109]
	s_nop 0
	v_lshl_add_u64 v[240:241], v[240:241], 0, v[66:67]
	global_load_dwordx4 v[116:119], v[240:241], off
	global_load_dwordx4 v[120:123], v[240:241], off offset:64
	global_load_dwordx4 v[124:127], v[240:241], off offset:128
	global_load_dwordx4 v[128:131], v[240:241], off offset:192
	global_load_dwordx4 v[160:163], v[224:225], off
	global_load_dwordx4 v[164:167], v[224:225], off offset:64
	global_load_dwordx4 v[168:171], v[224:225], off offset:128
	global_load_dwordx4 v[172:175], v[224:225], off offset:192
	v_or_b32_e32 v88, 16, v74
	v_mul_hi_i32 v89, v88, s47
	v_lshrrev_b32_e32 v90, 31, v89
	v_ashrrev_i32_e32 v89, 9, v89
	v_add_u32_e32 v91, v89, v90
	v_mul_i32_i24_e32 v89, 0x900, v91
	v_sub_u32_e32 v92, v88, v89
	v_cmp_lt_i32_e32 vcc, s33, v92
;   DI void operator()(const f32x4 (&acc)[4][4], int r0, int c0, int fr, int fq) const {
; #pragma unroll
;     for (int m = 0; m < 4; ++m) {
;       const int row = r0 + m * 16 + fr; const int b = row / TB, s = row % TB;
;       const float* src = xsrc_row(*p, from_inputs, b, s);
;       float* dst = xdst_row(*p, b, s);
;       const float* gate = p->MOD + (size_t)(l * 9 + (s < NCTX ? 8 : b)) * 6144 + gate_off;
; #pragma unroll
;       for (int n = 0; n < 4; ++n) {
;         const int col = c0 + n * 16 + fq * 4;
;         f32x4 g = *(const f32x4*)(gate + col), xv = *(const f32x4*)(src + col);
;         *(f32x4*)(dst + col) = xv + g * acc[m][n];
;       }
;     }
;   }
	v_lshlrev_b32_e32 v89, 11, v91
	v_add3_u32 v89, v92, v89, s75
	v_lshl_add_u32 v90, v91, 8, v92
	v_cndmask_b32_e32 v94, v90, v89, vcc
	v_ashrrev_i32_e32 v95, 31, v94
	v_lshlrev_b64 v[96:97], 12, v[94:95]
	v_lshl_add_u64 v[96:97], v[96:97], 0, v[66:67]
	v_cndmask_b32_e32 v98, v100, v102, vcc
	v_cndmask_b32_e32 v99, v101, v103, vcc
	v_lshl_add_u64 v[226:227], v[98:99], 0, v[96:97]
	v_cndmask_b32_e32 v98, v104, v106, vcc
	v_cndmask_b32_e32 v99, v105, v107, vcc
	v_lshl_add_u64 v[234:235], v[98:99], 0, v[96:97]
	global_load_dwordx4 v[176:179], v[226:227], off
	global_load_dwordx4 v[180:183], v[226:227], off offset:64
	global_load_dwordx4 v[184:187], v[226:227], off offset:128
	global_load_dwordx4 v[188:191], v[226:227], off offset:192
	v_or_b32_e32 v88, 32, v74
	v_mul_hi_i32 v89, v88, s47
	v_lshrrev_b32_e32 v90, 31, v89
	v_ashrrev_i32_e32 v89, 9, v89
	v_add_u32_e32 v91, v89, v90
	v_mul_i32_i24_e32 v89, 0x900, v91
	v_sub_u32_e32 v92, v88, v89
	v_cmp_lt_i32_e32 vcc, s33, v92
	v_lshlrev_b32_e32 v89, 11, v91
	v_add3_u32 v89, v92, v89, s75
	v_lshl_add_u32 v90, v91, 8, v92
	v_cndmask_b32_e32 v94, v90, v89, vcc
	v_ashrrev_i32_e32 v95, 31, v94
	v_lshlrev_b64 v[96:97], 12, v[94:95]
	v_lshl_add_u64 v[96:97], v[96:97], 0, v[66:67]
	v_cndmask_b32_e32 v98, v100, v102, vcc
	v_cndmask_b32_e32 v99, v101, v103, vcc
	v_lshl_add_u64 v[228:229], v[98:99], 0, v[96:97]
	v_cndmask_b32_e32 v98, v104, v106, vcc
	v_cndmask_b32_e32 v99, v105, v107, vcc
	v_lshl_add_u64 v[236:237], v[98:99], 0, v[96:97]
	global_load_dwordx4 v[192:195], v[228:229], off
	global_load_dwordx4 v[196:199], v[228:229], off offset:64
	global_load_dwordx4 v[200:203], v[228:229], off offset:128
	global_load_dwordx4 v[204:207], v[228:229], off offset:192
	v_or_b32_e32 v88, 48, v74
	v_mul_hi_i32 v89, v88, s47
	v_lshrrev_b32_e32 v90, 31, v89
	v_ashrrev_i32_e32 v89, 9, v89
	v_add_u32_e32 v91, v89, v90
	v_mul_i32_i24_e32 v89, 0x900, v91
	v_sub_u32_e32 v92, v88, v89
	v_cmp_lt_i32_e32 vcc, s33, v92
	v_lshlrev_b32_e32 v89, 11, v91
	v_add3_u32 v89, v92, v89, s75
	v_lshl_add_u32 v90, v91, 8, v92
	v_cndmask_b32_e32 v94, v90, v89, vcc
	v_ashrrev_i32_e32 v95, 31, v94
	v_lshlrev_b64 v[96:97], 12, v[94:95]
	v_lshl_add_u64 v[96:97], v[96:97], 0, v[66:67]
	v_cndmask_b32_e32 v98, v100, v102, vcc
	v_cndmask_b32_e32 v99, v101, v103, vcc
	v_lshl_add_u64 v[230:231], v[98:99], 0, v[96:97]
	v_cndmask_b32_e32 v98, v104, v106, vcc
	v_cndmask_b32_e32 v99, v105, v107, vcc
	v_lshl_add_u64 v[238:239], v[98:99], 0, v[96:97]
	global_load_dwordx4 v[208:211], v[230:231], off
	global_load_dwordx4 v[212:215], v[230:231], off offset:64
	global_load_dwordx4 v[216:219], v[230:231], off offset:128
	global_load_dwordx4 v[220:223], v[230:231], off offset:192
	s_waitcnt vmcnt(15)
	v_pk_fma_f32 v[64:65], v[64:65], v[118:119], v[162:163]
	v_pk_fma_f32 v[62:63], v[62:63], v[116:117], v[160:161]
	global_store_dwordx4 v[232:233], v[62:65], off sc0 sc1
	s_waitcnt vmcnt(15)
	v_pk_fma_f32 v[60:61], v[60:61], v[122:123], v[166:167]
	v_pk_fma_f32 v[58:59], v[58:59], v[120:121], v[164:165]
	global_store_dwordx4 v[232:233], v[58:61], off offset:64 sc0 sc1
	s_waitcnt vmcnt(15)
	v_pk_fma_f32 v[56:57], v[56:57], v[126:127], v[170:171]
	v_pk_fma_f32 v[54:55], v[54:55], v[124:125], v[168:169]
	global_store_dwordx4 v[232:233], v[54:57], off offset:128 sc0 sc1
	s_waitcnt vmcnt(15)
	v_pk_fma_f32 v[52:53], v[52:53], v[130:131], v[174:175]
	v_pk_fma_f32 v[50:51], v[50:51], v[128:129], v[172:173]
	global_store_dwordx4 v[232:233], v[50:53], off offset:192 sc0 sc1
	s_waitcnt vmcnt(15)
	v_pk_fma_f32 v[48:49], v[48:49], v[118:119], v[178:179]
	v_pk_fma_f32 v[46:47], v[46:47], v[116:117], v[176:177]
	global_store_dwordx4 v[234:235], v[46:49], off sc0 sc1
	s_waitcnt vmcnt(15)
	v_pk_fma_f32 v[44:45], v[44:45], v[122:123], v[182:183]
	v_pk_fma_f32 v[42:43], v[42:43], v[120:121], v[180:181]
	global_store_dwordx4 v[234:235], v[42:45], off offset:64 sc0 sc1
	s_waitcnt vmcnt(15)
	v_pk_fma_f32 v[40:41], v[40:41], v[126:127], v[186:187]
	v_pk_fma_f32 v[38:39], v[38:39], v[124:125], v[184:185]
	global_store_dwordx4 v[234:235], v[38:41], off offset:128 sc0 sc1
	s_waitcnt vmcnt(15)
	v_pk_fma_f32 v[36:37], v[36:37], v[130:131], v[190:191]
	v_pk_fma_f32 v[34:35], v[34:35], v[128:129], v[188:189]
	global_store_dwordx4 v[234:235], v[34:37], off offset:192 sc0 sc1
	s_waitcnt vmcnt(15)
	v_pk_fma_f32 v[32:33], v[32:33], v[118:119], v[194:195]
	v_pk_fma_f32 v[30:31], v[30:31], v[116:117], v[192:193]
	global_store_dwordx4 v[236:237], v[30:33], off sc0 sc1
	s_waitcnt vmcnt(15)
	v_pk_fma_f32 v[28:29], v[28:29], v[122:123], v[198:199]
	v_pk_fma_f32 v[26:27], v[26:27], v[120:121], v[196:197]
	global_store_dwordx4 v[236:237], v[26:29], off offset:64 sc0 sc1
	s_waitcnt vmcnt(15)
	v_pk_fma_f32 v[24:25], v[24:25], v[126:127], v[202:203]
	v_pk_fma_f32 v[22:23], v[22:23], v[124:125], v[200:201]
	global_store_dwordx4 v[236:237], v[22:25], off offset:128 sc0 sc1
	s_waitcnt vmcnt(15)
	v_pk_fma_f32 v[20:21], v[20:21], v[130:131], v[206:207]
	v_pk_fma_f32 v[18:19], v[18:19], v[128:129], v[204:205]
	global_store_dwordx4 v[236:237], v[18:21], off offset:192 sc0 sc1
	s_waitcnt vmcnt(15)
	v_pk_fma_f32 v[16:17], v[16:17], v[118:119], v[210:211]
	v_pk_fma_f32 v[14:15], v[14:15], v[116:117], v[208:209]
	global_store_dwordx4 v[238:239], v[14:17], off sc0 sc1
	s_waitcnt vmcnt(15)
	v_pk_fma_f32 v[12:13], v[12:13], v[122:123], v[214:215]
	v_pk_fma_f32 v[10:11], v[10:11], v[120:121], v[212:213]
	global_store_dwordx4 v[238:239], v[10:13], off offset:64 sc0 sc1
	s_waitcnt vmcnt(15)
	v_pk_fma_f32 v[8:9], v[8:9], v[126:127], v[218:219]
	v_pk_fma_f32 v[6:7], v[6:7], v[124:125], v[216:217]
	global_store_dwordx4 v[238:239], v[6:9], off offset:128 sc0 sc1
	s_waitcnt vmcnt(15)
	v_pk_fma_f32 v[4:5], v[4:5], v[130:131], v[222:223]
	v_pk_fma_f32 v[2:3], v[2:3], v[128:129], v[220:221]
	global_store_dwordx4 v[238:239], v[2:5], off offset:192 sc0 sc1
	s_cmp_lg_u32 s77, 6
	s_cbranch_scc1 .Ldep_nosig_k6
	s_waitcnt vmcnt(0)
	s_barrier
	v_readfirstlane_b32 s0, v74
	s_lshr_b32 s0, s0, 7
	s_lshl_b32 s0, s0, 2
	s_add_i32 s0, s0, 0x1c00
	v_mov_b32_e32 v88, s0
	v_mov_b32_e32 v89, 1
	v_cmp_eq_u32_e32 vcc, 0, v138
	s_and_saveexec_b64 s[0:1], vcc
	global_atomic_add v88, v89, s[70:71]
	s_or_b64 exec, exec, s[0:1]
.Ldep_nosig_k6:
	s_add_i32 s41, s41, 1
	s_mov_b64 s[0:1], 0
	s_branch .LBB0_254

; DI void modnorm_rows(const Params& p, int l, int which  , bool from_inputs, bool skip_ctx, int w0, int wstride, int lane) {
;   const float* g = (which ? p.norm2_g : p.norm1_g) + l * DM;
;   f32x4 gg[4];
; #pragma unroll
;   for (int i = 0; i < 4; ++i) gg[i] = *(const f32x4*)(g + i * 256 + lane * 4);
;   const int nrows = skip_ctx ? 8 * NLAT : T_TOK;
;   auto rowof = [&](int i) -> int { return skip_ctx ? (i / NLAT) * TB + NCTX + (i % NLAT) : i; };
;   int i = w0;
;   if (i >= nrows) return;
;   f32x4 vn[4];
;   {
;     const int row = rowof(i); const float* src = xsrc_row(p, from_inputs, row / TB, row % TB);
; #pragma unroll
;     for (int q = 0; q < 4; ++q) vn[q] = *(const f32x4*)(src + q * 256 + lane * 4);
;   }
;   for (; i < nrows; i += wstride) {
;     const int row = rowof(i); const int b = row / TB, s = row % TB;
;     f32x4 v[4];
; #pragma unroll
;     for (int q = 0; q < 4; ++q) v[q] = vn[q];
;     if (i + wstride < nrows) {
;       const int rn = rowof(i + wstride); const float* src = xsrc_row(p, from_inputs, rn / TB, rn % TB);
; #pragma unroll
;       for (int q = 0; q < 4; ++q) vn[q] = *(const f32x4*)(src + q * 256 + lane * 4);
.LBB0_823:
	s_or_b64 exec, exec, s[0:1]
	v_readlane_b32 s0, v252, 9
	s_nop 1
	v_add_u32_e32 v50, s0, v158
	s_movk_i32 s0, 0x4800
	v_cmp_gt_i32_e32 vcc, s0, v50
	s_and_saveexec_b64 s[2:3], vcc
	s_cbranch_execz .LBB0_852
	v_readlane_b32 s0, v252, 9
	v_lshlrev_b32_e32 v244, 4, v115
	v_lshlrev_b32_e32 v245, 3, v115
	v_add_u32_e32 v1, s0, v158
	s_nop 1
	v_readfirstlane_b32 s20, v1
	v_readlane_b32 s4, v254, 40
	v_readlane_b32 s5, v254, 41
	v_readlane_b32 s12, v254, 28
	v_readlane_b32 s13, v254, 29
	v_readlane_b32 s14, v254, 32
	v_readlane_b32 s15, v254, 33
	v_readlane_b32 s16, v253, 40
	v_readlane_b32 s17, v253, 41
	v_readlane_b32 s18, v250, 4
	v_readlane_b32 s19, v250, 5
	s_nop 3
	s_lshl_b32 s0, s49, 12
	s_add_u32 s4, s4, s0
	s_addc_u32 s5, s5, 0
	global_load_dwordx4 v[2:5], v244, s[4:5]
	global_load_dwordx4 v[6:9], v244, s[4:5] offset:1024
	global_load_dwordx4 v[10:13], v244, s[4:5] offset:2048
	global_load_dwordx4 v[14:17], v244, s[4:5] offset:3072
	s_add_i32 s0, s77, 7
	s_cmp_gt_u32 s0, 16
	s_cselect_b32 s12, s56, s12
	s_cselect_b32 s13, s57, s13
	s_cselect_b32 s14, s64, s14
	s_cselect_b32 s15, s65, s15
	s_cmp_gt_u32 s77, 9
	s_cbranch_scc1 .Lnorm1_l1
	s_add_i32 s21, s20, 0
	s_mul_hi_u32 s7, s21, 0x38e38e39
	s_lshr_b32 s7, s7, 9
	s_mul_i32 s8, s7, 0x900
	s_sub_i32 s8, s21, s8
	s_lshl_b32 s9, s7, 11
	s_add_i32 s9, s9, s8
	s_add_i32 s9, s9, 0xffffff00
	s_lshl_b32 s10, s7, 8
	s_add_i32 s10, s10, s8
	s_cmpk_gt_i32 s8, 0xff
	s_cselect_b32 s9, s9, s10
	s_cselect_b32 s26, s12, s14
	s_cselect_b32 s27, s13, s15
	s_cselect_b32 s10, s7, 8
	s_lshl_b32 s9, s9, 12
	s_add_u32 s26, s26, s9
	s_addc_u32 s27, s27, 0
	s_add_i32 s10, s10, s82
	s_mul_i32 s10, s10, s24
	s_add_u32 s28, s58, s10
	s_addc_u32 s29, s59, 0
	s_add_u32 s28, s28, 0x0
	s_addc_u32 s29, s29, 0
	s_add_u32 s0, s28, 0x1000
	s_addc_u32 s1, s29, 0
	global_load_dwordx4 v[18:21], v244, s[26:27]
	global_load_dwordx4 v[22:25], v244, s[26:27] offset:1024
	global_load_dwordx4 v[26:29], v244, s[26:27] offset:2048
	global_load_dwordx4 v[30:33], v244, s[26:27] offset:3072
	global_load_dwordx4 v[34:37], v244, s[28:29]
	global_load_dwordx4 v[38:41], v244, s[28:29] offset:1024
	global_load_dwordx4 v[42:45], v244, s[28:29] offset:2048
	global_load_dwordx4 v[46:49], v244, s[28:29] offset:3072
	global_load_dwordx4 v[50:53], v244, s[0:1]
	global_load_dwordx4 v[54:57], v244, s[0:1] offset:1024
	global_load_dwordx4 v[58:61], v244, s[0:1] offset:2048
	global_load_dwordx4 v[62:65], v244, s[0:1] offset:3072
	s_add_i32 s21, s20, 2048
	s_mul_hi_u32 s7, s21, 0x38e38e39
	s_lshr_b32 s7, s7, 9
	s_mul_i32 s8, s7, 0x900
	s_sub_i32 s8, s21, s8
	s_lshl_b32 s9, s7, 11
	s_add_i32 s9, s9, s8
	s_add_i32 s9, s9, 0xffffff00
	s_lshl_b32 s10, s7, 8
	s_add_i32 s10, s10, s8
	s_cmpk_gt_i32 s8, 0xff
	s_cselect_b32 s9, s9, s10
	s_cselect_b32 s26, s12, s14
	s_cselect_b32 s27, s13, s15
	s_cselect_b32 s10, s7, 8
	s_lshl_b32 s9, s9, 12
	s_add_u32 s26, s26, s9
	s_addc_u32 s27, s27, 0
	s_add_i32 s10, s10, s82
	s_mul_i32 s10, s10, s24
	s_add_u32 s28, s58, s10
	s_addc_u32 s29, s59, 0
	s_add_u32 s28, s28, 0x0
	s_addc_u32 s29, s29, 0
	s_add_u32 s0, s28, 0x1000
	s_addc_u32 s1, s29, 0
	global_load_dwordx4 v[66:69], v244, s[26:27]
	global_load_dwordx4 v[70:73], v244, s[26:27] offset:1024
	global_load_dwordx4 v[74:77], v244, s[26:27] offset:2048
	global_load_dwordx4 v[78:81], v244, s[26:27] offset:3072
	global_load_dwordx4 v[82:85], v244, s[28:29]
	global_load_dwordx4 v[86:89], v244, s[28:29] offset:1024
	global_load_dwordx4 v[90:93], v244, s[28:29] offset:2048
	global_load_dwordx4 v[94:97], v244, s[28:29] offset:3072
	global_load_dwordx4 v[98:101], v244, s[0:1]
	global_load_dwordx4 v[102:105], v244, s[0:1] offset:1024
	global_load_dwordx4 v[106:109], v244, s[0:1] offset:2048
	global_load_dwordx4 v[118:121], v244, s[0:1] offset:3072
	s_add_i32 s21, s20, 4096
	s_mul_hi_u32 s7, s21, 0x38e38e39
	s_lshr_b32 s7, s7, 9
	s_mul_i32 s8, s7, 0x900
	s_sub_i32 s8, s21, s8
	s_lshl_b32 s9, s7, 11
	s_add_i32 s9, s9, s8
	s_add_i32 s9, s9, 0xffffff00
	s_lshl_b32 s10, s7, 8
	s_add_i32 s10, s10, s8
	s_cmpk_gt_i32 s8, 0xff
	s_cselect_b32 s9, s9, s10
	s_cselect_b32 s26, s12, s14
	s_cselect_b32 s27, s13, s15
	s_cselect_b32 s10, s7, 8
	s_lshl_b32 s9, s9, 12
	s_add_u32 s26, s26, s9
	s_addc_u32 s27, s27, 0
	s_add_i32 s10, s10, s82
	s_mul_i32 s10, s10, s24
	s_add_u32 s28, s58, s10
	s_addc_u32 s29, s59, 0
	s_add_u32 s28, s28, 0x0
	s_addc_u32 s29, s29, 0
	s_add_u32 s0, s28, 0x1000
	s_addc_u32 s1, s29, 0
	global_load_dwordx4 v[122:125], v244, s[26:27]
	global_load_dwordx4 v[126:129], v244, s[26:27] offset:1024
	global_load_dwordx4 v[130:133], v244, s[26:27] offset:2048
	global_load_dwordx4 v[134:137], v244, s[26:27] offset:3072
	global_load_dwordx4 v[160:163], v244, s[28:29]
	global_load_dwordx4 v[164:167], v244, s[28:29] offset:1024
	global_load_dwordx4 v[168:171], v244, s[28:29] offset:2048
	global_load_dwordx4 v[172:175], v244, s[28:29] offset:3072
	global_load_dwordx4 v[176:179], v244, s[0:1]
	global_load_dwordx4 v[180:183], v244, s[0:1] offset:1024
	global_load_dwordx4 v[184:187], v244, s[0:1] offset:2048
	global_load_dwordx4 v[188:191], v244, s[0:1] offset:3072
	s_waitcnt vmcnt(24)
; DI unsigned pk_bf16(float lo, float hi) { f32x2 v = {lo, hi}; bf16v2 b = __builtin_convertvector(v, bf16v2); return __builtin_bit_cast(unsigned, b); }
; DI float red64(float x) { for (int o = 32; o > 0; o >>= 1) x += __shfl_xor(x, o); return x; }
; DI void modnorm_rows(const Params& p, int l, int which  , bool from_inputs, bool skip_ctx, int w0, int wstride, int lane) {
;     ...
;     if (i + wstride < nrows) {
;       const int rn = rowof(i + wstride); const float* src = xsrc_row(p, from_inputs, rn / TB, rn % TB);
; #pragma unroll
;       for (int q = 0; q < 4; ++q) vn[q] = *(const f32x4*)(src + q * 256 + lane * 4);
;     }
;     ...
;     for (int q = 0; q < 4; ++q) { sh[q] = *(const f32x4*)(mod + q * 256 + lane * 4); sc[q] = *(const f32x4*)(mod + 1024 + q * 256 + lane * 4); }
;     float ss = 0.f;
; #pragma unroll
;     for (int q = 0; q < 4; ++q) ss += v[q][0] * v[q][0] + v[q][1] * v[q][1] + v[q][2] * v[q][2] + v[q][3] * v[q][3];
;     ss = red64(ss);
;     const float rs = rsqrtf(ss * (1.f / 1024.f) + EPSF);
;     bf16_t* dst = p.HY + (size_t)row * DM;
; #pragma unroll
;     for (int q = 0; q < 4; ++q) {
;       float o[4];
; #pragma unroll
;       for (int j = 0; j < 4; ++j) o[j] = (v[q][j] * rs * gg[q][j]) * (1.f + sc[q][j]) + sh[q][j];
;       u32x2 w = {pk_bf16(o[0], o[1]), pk_bf16(o[2], o[3])};
;       *(u32x2*)(dst + q * 256 + lane * 4) = w;
;     }
;   }
	v_pk_mul_f32 v[246:247], v[18:19], v[18:19]
	v_pk_fma_f32 v[246:247], v[20:21], v[20:21], v[246:247]
	v_pk_fma_f32 v[246:247], v[22:23], v[22:23], v[246:247]
	v_pk_fma_f32 v[246:247], v[24:25], v[24:25], v[246:247]
	v_pk_fma_f32 v[246:247], v[26:27], v[26:27], v[246:247]
	v_pk_fma_f32 v[246:247], v[28:29], v[28:29], v[246:247]
	v_pk_fma_f32 v[246:247], v[30:31], v[30:31], v[246:247]
	v_pk_fma_f32 v[246:247], v[32:33], v[32:33], v[246:247]
	s_nop 0
	v_add_f32_e32 v246, v246, v247
	s_nop 1
	v_add_f32_dpp v246, v246, v246 quad_perm:[1,0,3,2] row_mask:0xf bank_mask:0xf
	s_nop 1
	v_add_f32_dpp v246, v246, v246 quad_perm:[2,3,0,1] row_mask:0xf bank_mask:0xf
	s_nop 1
	v_add_f32_dpp v246, v246, v246 row_half_mirror row_mask:0xf bank_mask:0xf
	s_nop 1
	v_add_f32_dpp v246, v246, v246 row_mirror row_mask:0xf bank_mask:0xf
	s_nop 1
	v_add_f32_dpp v246, v246, v246 row_bcast:15 row_mask:0xa bank_mask:0xf
	s_nop 1
	v_add_f32_dpp v246, v246, v246 row_bcast:31 row_mask:0xc bank_mask:0xf
	s_nop 1
	v_readlane_b32 s0, v246, 63
	s_add_i32 s21, s20, 0
	s_lshl_b32 s21, s21, 11
	s_add_u32 s10, s16, s21
	s_addc_u32 s11, s17, 0
	v_mov_b32_e32 v248, s0
	v_fmamk_f32 v248, v248, 0x3a800000, v143
	v_rsq_f32_e32 v248, v248
	s_nop 0
	v_pk_mul_f32 v[18:19], v[18:19], v[248:249] op_sel_hi:[1,0]
	v_pk_add_f32 v[50:51], v[50:51], 1.0 op_sel_hi:[1,0]
	v_pk_mul_f32 v[18:19], v[2:3], v[18:19]
	v_pk_fma_f32 v[18:19], v[50:51], v[18:19], v[34:35]
	v_pk_mul_f32 v[20:21], v[20:21], v[248:249] op_sel_hi:[1,0]
	v_pk_add_f32 v[52:53], v[52:53], 1.0 op_sel_hi:[1,0]
	v_pk_mul_f32 v[20:21], v[4:5], v[20:21]
	v_pk_fma_f32 v[20:21], v[52:53], v[20:21], v[36:37]
	v_cvt_pk_bf16_f32 v34, v18, v19
	v_cvt_pk_bf16_f32 v35, v20, v21
	global_store_dwordx2 v245, v[34:35], s[10:11]
	v_pk_mul_f32 v[22:23], v[22:23], v[248:249] op_sel_hi:[1,0]
	v_pk_add_f32 v[54:55], v[54:55], 1.0 op_sel_hi:[1,0]
	v_pk_mul_f32 v[22:23], v[6:7], v[22:23]
	v_pk_fma_f32 v[22:23], v[54:55], v[22:23], v[38:39]
	v_pk_mul_f32 v[24:25], v[24:25], v[248:249] op_sel_hi:[1,0]
	v_pk_add_f32 v[56:57], v[56:57], 1.0 op_sel_hi:[1,0]
	v_pk_mul_f32 v[24:25], v[8:9], v[24:25]
	v_pk_fma_f32 v[24:25], v[56:57], v[24:25], v[40:41]
	v_cvt_pk_bf16_f32 v38, v22, v23
	v_cvt_pk_bf16_f32 v39, v24, v25
	global_store_dwordx2 v245, v[38:39], s[10:11] offset:512
	v_pk_mul_f32 v[26:27], v[26:27], v[248:249] op_sel_hi:[1,0]
	v_pk_add_f32 v[58:59], v[58:59], 1.0 op_sel_hi:[1,0]
	v_pk_mul_f32 v[26:27], v[10:11], v[26:27]
	v_pk_fma_f32 v[26:27], v[58:59], v[26:27], v[42:43]
	v_pk_mul_f32 v[28:29], v[28:29], v[248:249] op_sel_hi:[1,0]
	v_pk_add_f32 v[60:61], v[60:61], 1.0 op_sel_hi:[1,0]
	v_pk_mul_f32 v[28:29], v[12:13], v[28:29]
	v_pk_fma_f32 v[28:29], v[60:61], v[28:29], v[44:45]
	v_cvt_pk_bf16_f32 v42, v26, v27
	v_cvt_pk_bf16_f32 v43, v28, v29
	global_store_dwordx2 v245, v[42:43], s[10:11] offset:1024
	v_pk_mul_f32 v[30:31], v[30:31], v[248:249] op_sel_hi:[1,0]
	v_pk_add_f32 v[62:63], v[62:63], 1.0 op_sel_hi:[1,0]
	v_pk_mul_f32 v[30:31], v[14:15], v[30:31]
	v_pk_fma_f32 v[30:31], v[62:63], v[30:31], v[46:47]
	v_pk_mul_f32 v[32:33], v[32:33], v[248:249] op_sel_hi:[1,0]
	v_pk_add_f32 v[64:65], v[64:65], 1.0 op_sel_hi:[1,0]
	v_pk_mul_f32 v[32:33], v[16:17], v[32:33]
	v_pk_fma_f32 v[32:33], v[64:65], v[32:33], v[48:49]
	v_cvt_pk_bf16_f32 v46, v30, v31
	v_cvt_pk_bf16_f32 v47, v32, v33
	global_store_dwordx2 v245, v[46:47], s[10:11] offset:1536
	s_add_i32 s21, s20, 6144
	s_mul_hi_u32 s7, s21, 0x38e38e39
	s_lshr_b32 s7, s7, 9
	s_mul_i32 s8, s7, 0x900
	s_sub_i32 s8, s21, s8
	s_lshl_b32 s9, s7, 11
	s_add_i32 s9, s9, s8
	s_add_i32 s9, s9, 0xffffff00
	s_lshl_b32 s10, s7, 8
	s_add_i32 s10, s10, s8
	s_cmpk_gt_i32 s8, 0xff
	s_cselect_b32 s9, s9, s10
	s_cselect_b32 s26, s12, s14
	s_cselect_b32 s27, s13, s15
	s_cselect_b32 s10, s7, 8
	s_lshl_b32 s9, s9, 12
	s_add_u32 s26, s26, s9
	s_addc_u32 s27, s27, 0
	s_add_i32 s10, s10, s82
	s_mul_i32 s10, s10, s24
	s_add_u32 s28, s58, s10
	s_addc_u32 s29, s59, 0
	s_add_u32 s28, s28, 0x0
	s_addc_u32 s29, s29, 0
	s_add_u32 s0, s28, 0x1000
	s_addc_u32 s1, s29, 0
	global_load_dwordx4 v[18:21], v244, s[26:27]
	global_load_dwordx4 v[22:25], v244, s[26:27] offset:1024
	global_load_dwordx4 v[26:29], v244, s[26:27] offset:2048
	global_load_dwordx4 v[30:33], v244, s[26:27] offset:3072
	global_load_dwordx4 v[34:37], v244, s[28:29]
	global_load_dwordx4 v[38:41], v244, s[28:29] offset:1024
	global_load_dwordx4 v[42:45], v244, s[28:29] offset:2048
	global_load_dwordx4 v[46:49], v244, s[28:29] offset:3072
	global_load_dwordx4 v[50:53], v244, s[0:1]
	global_load_dwordx4 v[54:57], v244, s[0:1] offset:1024
	global_load_dwordx4 v[58:61], v244, s[0:1] offset:2048
	global_load_dwordx4 v[62:65], v244, s[0:1] offset:3072
	s_waitcnt vmcnt(28)
; DI unsigned pk_bf16(float lo, float hi) { f32x2 v = {lo, hi}; bf16v2 b = __builtin_convertvector(v, bf16v2); return __builtin_bit_cast(unsigned, b); }
; DI float red64(float x) { for (int o = 32; o > 0; o >>= 1) x += __shfl_xor(x, o); return x; }
; DI void modnorm_rows(const Params& p, int l, int which  , bool from_inputs, bool skip_ctx, int w0, int wstride, int lane) {
;     ...
;     if (i + wstride < nrows) {
;       const int rn = rowof(i + wstride); const float* src = xsrc_row(p, from_inputs, rn / TB, rn % TB);
; #pragma unroll
;       for (int q = 0; q < 4; ++q) vn[q] = *(const f32x4*)(src + q * 256 + lane * 4);
;     }
;     const float* mod = p.MOD + (size_t)(l * 9 + (s < NCTX ? 8 : b)) * 6144 + (which ? 3 * 1024 : 0);
;     f32x4 sh[4], sc[4];
; #pragma unroll
;     for (int q = 0; q < 4; ++q) { sh[q] = *(const f32x4*)(mod + q * 256 + lane * 4); sc[q] = *(const f32x4*)(mod + 1024 + q * 256 + lane * 4); }
;     float ss = 0.f;
; #pragma unroll
;     for (int q = 0; q < 4; ++q) ss += v[q][0] * v[q][0] + v[q][1] * v[q][1] + v[q][2] * v[q][2] + v[q][3] * v[q][3];
;     ss = red64(ss);
;     const float rs = rsqrtf(ss * (1.f / 1024.f) + EPSF);
;     bf16_t* dst = p.HY + (size_t)row * DM;
; #pragma unroll
;     for (int q = 0; q < 4; ++q) {
;       float o[4];
; #pragma unroll
;       for (int j = 0; j < 4; ++j) o[j] = (v[q][j] * rs * gg[q][j]) * (1.f + sc[q][j]) + sh[q][j];
;       u32x2 w = {pk_bf16(o[0], o[1]), pk_bf16(o[2], o[3])};
;       *(u32x2*)(dst + q * 256 + lane * 4) = w;
;     }
;   }
	v_pk_mul_f32 v[246:247], v[66:67], v[66:67]
	v_pk_fma_f32 v[246:247], v[68:69], v[68:69], v[246:247]
	v_pk_fma_f32 v[246:247], v[70:71], v[70:71], v[246:247]
	v_pk_fma_f32 v[246:247], v[72:73], v[72:73], v[246:247]
	v_pk_fma_f32 v[246:247], v[74:75], v[74:75], v[246:247]
	v_pk_fma_f32 v[246:247], v[76:77], v[76:77], v[246:247]
	v_pk_fma_f32 v[246:247], v[78:79], v[78:79], v[246:247]
	v_pk_fma_f32 v[246:247], v[80:81], v[80:81], v[246:247]
	s_nop 0
	v_add_f32_e32 v246, v246, v247
	s_nop 1
	v_add_f32_dpp v246, v246, v246 quad_perm:[1,0,3,2] row_mask:0xf bank_mask:0xf
	s_nop 1
	v_add_f32_dpp v246, v246, v246 quad_perm:[2,3,0,1] row_mask:0xf bank_mask:0xf
	s_nop 1
	v_add_f32_dpp v246, v246, v246 row_half_mirror row_mask:0xf bank_mask:0xf
	s_nop 1
	v_add_f32_dpp v246, v246, v246 row_mirror row_mask:0xf bank_mask:0xf
	s_nop 1
	v_add_f32_dpp v246, v246, v246 row_bcast:15 row_mask:0xa bank_mask:0xf
	s_nop 1
	v_add_f32_dpp v246, v246, v246 row_bcast:31 row_mask:0xc bank_mask:0xf
	s_nop 1
	v_readlane_b32 s0, v246, 63
	s_add_i32 s21, s20, 2048
	s_lshl_b32 s21, s21, 11
	s_add_u32 s10, s16, s21
	s_addc_u32 s11, s17, 0
	v_mov_b32_e32 v248, s0
	v_fmamk_f32 v248, v248, 0x3a800000, v143
	v_rsq_f32_e32 v248, v248
	s_nop 0
	v_pk_mul_f32 v[66:67], v[66:67], v[248:249] op_sel_hi:[1,0]
	v_pk_add_f32 v[98:99], v[98:99], 1.0 op_sel_hi:[1,0]
	v_pk_mul_f32 v[66:67], v[2:3], v[66:67]
	v_pk_fma_f32 v[66:67], v[98:99], v[66:67], v[82:83]
	v_pk_mul_f32 v[68:69], v[68:69], v[248:249] op_sel_hi:[1,0]
	v_pk_add_f32 v[100:101], v[100:101], 1.0 op_sel_hi:[1,0]
	v_pk_mul_f32 v[68:69], v[4:5], v[68:69]
	v_pk_fma_f32 v[68:69], v[100:101], v[68:69], v[84:85]
	v_cvt_pk_bf16_f32 v82, v66, v67
	v_cvt_pk_bf16_f32 v83, v68, v69
	global_store_dwordx2 v245, v[82:83], s[10:11]
	v_pk_mul_f32 v[70:71], v[70:71], v[248:249] op_sel_hi:[1,0]
	v_pk_add_f32 v[102:103], v[102:103], 1.0 op_sel_hi:[1,0]
	v_pk_mul_f32 v[70:71], v[6:7], v[70:71]
	v_pk_fma_f32 v[70:71], v[102:103], v[70:71], v[86:87]
	v_pk_mul_f32 v[72:73], v[72:73], v[248:249] op_sel_hi:[1,0]
	v_pk_add_f32 v[104:105], v[104:105], 1.0 op_sel_hi:[1,0]
	v_pk_mul_f32 v[72:73], v[8:9], v[72:73]
	v_pk_fma_f32 v[72:73], v[104:105], v[72:73], v[88:89]
	v_cvt_pk_bf16_f32 v86, v70, v71
	v_cvt_pk_bf16_f32 v87, v72, v73
	global_store_dwordx2 v245, v[86:87], s[10:11] offset:512
	v_pk_mul_f32 v[74:75], v[74:75], v[248:249] op_sel_hi:[1,0]
	v_pk_add_f32 v[106:107], v[106:107], 1.0 op_sel_hi:[1,0]
	v_pk_mul_f32 v[74:75], v[10:11], v[74:75]
	v_pk_fma_f32 v[74:75], v[106:107], v[74:75], v[90:91]
	v_pk_mul_f32 v[76:77], v[76:77], v[248:249] op_sel_hi:[1,0]
	v_pk_add_f32 v[108:109], v[108:109], 1.0 op_sel_hi:[1,0]
	v_pk_mul_f32 v[76:77], v[12:13], v[76:77]
	v_pk_fma_f32 v[76:77], v[108:109], v[76:77], v[92:93]
	v_cvt_pk_bf16_f32 v90, v74, v75
	v_cvt_pk_bf16_f32 v91, v76, v77
	global_store_dwordx2 v245, v[90:91], s[10:11] offset:1024
	v_pk_mul_f32 v[78:79], v[78:79], v[248:249] op_sel_hi:[1,0]
	v_pk_add_f32 v[118:119], v[118:119], 1.0 op_sel_hi:[1,0]
	v_pk_mul_f32 v[78:79], v[14:15], v[78:79]
	v_pk_fma_f32 v[78:79], v[118:119], v[78:79], v[94:95]
	v_pk_mul_f32 v[80:81], v[80:81], v[248:249] op_sel_hi:[1,0]
	v_pk_add_f32 v[120:121], v[120:121], 1.0 op_sel_hi:[1,0]
	v_pk_mul_f32 v[80:81], v[16:17], v[80:81]
	v_pk_fma_f32 v[80:81], v[120:121], v[80:81], v[96:97]
	v_cvt_pk_bf16_f32 v94, v78, v79
	v_cvt_pk_bf16_f32 v95, v80, v81
	global_store_dwordx2 v245, v[94:95], s[10:11] offset:1536
	s_add_i32 s21, s20, 8192
	s_mul_hi_u32 s7, s21, 0x38e38e39
	s_lshr_b32 s7, s7, 9
	s_mul_i32 s8, s7, 0x900
	s_sub_i32 s8, s21, s8
	s_lshl_b32 s9, s7, 11
	s_add_i32 s9, s9, s8
	s_add_i32 s9, s9, 0xffffff00
	s_lshl_b32 s10, s7, 8
	s_add_i32 s10, s10, s8
	s_cmpk_gt_i32 s8, 0xff
	s_cselect_b32 s9, s9, s10
	s_cselect_b32 s26, s12, s14
	s_cselect_b32 s27, s13, s15
	s_cselect_b32 s10, s7, 8
	s_lshl_b32 s9, s9, 12
	s_add_u32 s26, s26, s9
	s_addc_u32 s27, s27, 0
	s_add_i32 s10, s10, s82
	s_mul_i32 s10, s10, s24
	s_add_u32 s28, s58, s10
	s_addc_u32 s29, s59, 0
	s_add_u32 s28, s28, 0x0
	s_addc_u32 s29, s29, 0
	s_add_u32 s0, s28, 0x1000
	s_addc_u32 s1, s29, 0
	global_load_dwordx4 v[66:69], v244, s[26:27]
	global_load_dwordx4 v[70:73], v244, s[26:27] offset:1024
	global_load_dwordx4 v[74:77], v244, s[26:27] offset:2048
	global_load_dwordx4 v[78:81], v244, s[26:27] offset:3072
	global_load_dwordx4 v[82:85], v244, s[28:29]
	global_load_dwordx4 v[86:89], v244, s[28:29] offset:1024
	global_load_dwordx4 v[90:93], v244, s[28:29] offset:2048
	global_load_dwordx4 v[94:97], v244, s[28:29] offset:3072
	global_load_dwordx4 v[98:101], v244, s[0:1]
	global_load_dwordx4 v[102:105], v244, s[0:1] offset:1024
	global_load_dwordx4 v[106:109], v244, s[0:1] offset:2048
	global_load_dwordx4 v[118:121], v244, s[0:1] offset:3072
	s_waitcnt vmcnt(32)
; DI unsigned pk_bf16(float lo, float hi) { f32x2 v = {lo, hi}; bf16v2 b = __builtin_convertvector(v, bf16v2); return __builtin_bit_cast(unsigned, b); }
; DI float red64(float x) { for (int o = 32; o > 0; o >>= 1) x += __shfl_xor(x, o); return x; }
; DI void modnorm_rows(const Params& p, int l, int which  , bool from_inputs, bool skip_ctx, int w0, int wstride, int lane) {
;     ...
;     if (i + wstride < nrows) {
;       const int rn = rowof(i + wstride); const float* src = xsrc_row(p, from_inputs, rn / TB, rn % TB);
; #pragma unroll
;       for (int q = 0; q < 4; ++q) vn[q] = *(const f32x4*)(src + q * 256 + lane * 4);
;     }
;     const float* mod = p.MOD + (size_t)(l * 9 + (s < NCTX ? 8 : b)) * 6144 + (which ? 3 * 1024 : 0);
;     f32x4 sh[4], sc[4];
; #pragma unroll
;     for (int q = 0; q < 4; ++q) { sh[q] = *(const f32x4*)(mod + q * 256 + lane * 4); sc[q] = *(const f32x4*)(mod + 1024 + q * 256 + lane * 4); }
;     float ss = 0.f;
; #pragma unroll
;     for (int q = 0; q < 4; ++q) ss += v[q][0] * v[q][0] + v[q][1] * v[q][1] + v[q][2] * v[q][2] + v[q][3] * v[q][3];
;     ss = red64(ss);
;     const float rs = rsqrtf(ss * (1.f / 1024.f) + EPSF);
;     bf16_t* dst = p.HY + (size_t)row * DM;
; #pragma unroll
;     for (int q = 0; q < 4; ++q) {
;       float o[4];
; #pragma unroll
;       for (int j = 0; j < 4; ++j) o[j] = (v[q][j] * rs * gg[q][j]) * (1.f + sc[q][j]) + sh[q][j];
;       u32x2 w = {pk_bf16(o[0], o[1]), pk_bf16(o[2], o[3])};
;       *(u32x2*)(dst + q * 256 + lane * 4) = w;
;     }
;   }
	v_pk_mul_f32 v[246:247], v[122:123], v[122:123]
	v_pk_fma_f32 v[246:247], v[124:125], v[124:125], v[246:247]
	v_pk_fma_f32 v[246:247], v[126:127], v[126:127], v[246:247]
	v_pk_fma_f32 v[246:247], v[128:129], v[128:129], v[246:247]
	v_pk_fma_f32 v[246:247], v[130:131], v[130:131], v[246:247]
	v_pk_fma_f32 v[246:247], v[132:133], v[132:133], v[246:247]
	v_pk_fma_f32 v[246:247], v[134:135], v[134:135], v[246:247]
	v_pk_fma_f32 v[246:247], v[136:137], v[136:137], v[246:247]
	s_nop 0
	v_add_f32_e32 v246, v246, v247
	s_nop 1
	v_add_f32_dpp v246, v246, v246 quad_perm:[1,0,3,2] row_mask:0xf bank_mask:0xf
	s_nop 1
	v_add_f32_dpp v246, v246, v246 quad_perm:[2,3,0,1] row_mask:0xf bank_mask:0xf
	s_nop 1
	v_add_f32_dpp v246, v246, v246 row_half_mirror row_mask:0xf bank_mask:0xf
	s_nop 1
	v_add_f32_dpp v246, v246, v246 row_mirror row_mask:0xf bank_mask:0xf
	s_nop 1
	v_add_f32_dpp v246, v246, v246 row_bcast:15 row_mask:0xa bank_mask:0xf
	s_nop 1
	v_add_f32_dpp v246, v246, v246 row_bcast:31 row_mask:0xc bank_mask:0xf
	s_nop 1
	v_readlane_b32 s0, v246, 63
	s_add_i32 s21, s20, 4096
	s_lshl_b32 s21, s21, 11
	s_add_u32 s10, s16, s21
	s_addc_u32 s11, s17, 0
	v_mov_b32_e32 v248, s0
	v_fmamk_f32 v248, v248, 0x3a800000, v143
	v_rsq_f32_e32 v248, v248
	s_nop 0
	v_pk_mul_f32 v[122:123], v[122:123], v[248:249] op_sel_hi:[1,0]
	v_pk_add_f32 v[176:177], v[176:177], 1.0 op_sel_hi:[1,0]
	v_pk_mul_f32 v[122:123], v[2:3], v[122:123]
	v_pk_fma_f32 v[122:123], v[176:177], v[122:123], v[160:161]
	v_pk_mul_f32 v[124:125], v[124:125], v[248:249] op_sel_hi:[1,0]
	v_pk_add_f32 v[178:179], v[178:179], 1.0 op_sel_hi:[1,0]
	v_pk_mul_f32 v[124:125], v[4:5], v[124:125]
	v_pk_fma_f32 v[124:125], v[178:179], v[124:125], v[162:163]
	v_cvt_pk_bf16_f32 v160, v122, v123
	v_cvt_pk_bf16_f32 v161, v124, v125
	global_store_dwordx2 v245, v[160:161], s[10:11]
	v_pk_mul_f32 v[126:127], v[126:127], v[248:249] op_sel_hi:[1,0]
	v_pk_add_f32 v[180:181], v[180:181], 1.0 op_sel_hi:[1,0]
	v_pk_mul_f32 v[126:127], v[6:7], v[126:127]
	v_pk_fma_f32 v[126:127], v[180:181], v[126:127], v[164:165]
	v_pk_mul_f32 v[128:129], v[128:129], v[248:249] op_sel_hi:[1,0]
	v_pk_add_f32 v[182:183], v[182:183], 1.0 op_sel_hi:[1,0]
	v_pk_mul_f32 v[128:129], v[8:9], v[128:129]
	v_pk_fma_f32 v[128:129], v[182:183], v[128:129], v[166:167]
	v_cvt_pk_bf16_f32 v164, v126, v127
	v_cvt_pk_bf16_f32 v165, v128, v129
	global_store_dwordx2 v245, v[164:165], s[10:11] offset:512
	v_pk_mul_f32 v[130:131], v[130:131], v[248:249] op_sel_hi:[1,0]
	v_pk_add_f32 v[184:185], v[184:185], 1.0 op_sel_hi:[1,0]
	v_pk_mul_f32 v[130:131], v[10:11], v[130:131]
	v_pk_fma_f32 v[130:131], v[184:185], v[130:131], v[168:169]
	v_pk_mul_f32 v[132:133], v[132:133], v[248:249] op_sel_hi:[1,0]
	v_pk_add_f32 v[186:187], v[186:187], 1.0 op_sel_hi:[1,0]
	v_pk_mul_f32 v[132:133], v[12:13], v[132:133]
	v_pk_fma_f32 v[132:133], v[186:187], v[132:133], v[170:171]
	v_cvt_pk_bf16_f32 v168, v130, v131
	v_cvt_pk_bf16_f32 v169, v132, v133
	global_store_dwordx2 v245, v[168:169], s[10:11] offset:1024
	v_pk_mul_f32 v[134:135], v[134:135], v[248:249] op_sel_hi:[1,0]
	v_pk_add_f32 v[188:189], v[188:189], 1.0 op_sel_hi:[1,0]
	v_pk_mul_f32 v[134:135], v[14:15], v[134:135]
	v_pk_fma_f32 v[134:135], v[188:189], v[134:135], v[172:173]
	v_pk_mul_f32 v[136:137], v[136:137], v[248:249] op_sel_hi:[1,0]
	v_pk_add_f32 v[190:191], v[190:191], 1.0 op_sel_hi:[1,0]
	v_pk_mul_f32 v[136:137], v[16:17], v[136:137]
	v_pk_fma_f32 v[136:137], v[190:191], v[136:137], v[174:175]
	v_cvt_pk_bf16_f32 v172, v134, v135
	v_cvt_pk_bf16_f32 v173, v136, v137
	global_store_dwordx2 v245, v[172:173], s[10:11] offset:1536
	s_add_i32 s21, s20, 10240
	s_mul_hi_u32 s7, s21, 0x38e38e39
	s_lshr_b32 s7, s7, 9
	s_mul_i32 s8, s7, 0x900
	s_sub_i32 s8, s21, s8
	s_lshl_b32 s9, s7, 11
	s_add_i32 s9, s9, s8
	s_add_i32 s9, s9, 0xffffff00
	s_lshl_b32 s10, s7, 8
	s_add_i32 s10, s10, s8
	s_cmpk_gt_i32 s8, 0xff
	s_cselect_b32 s9, s9, s10
	s_cselect_b32 s26, s12, s14
	s_cselect_b32 s27, s13, s15
	s_cselect_b32 s10, s7, 8
	s_lshl_b32 s9, s9, 12
	s_add_u32 s26, s26, s9
	s_addc_u32 s27, s27, 0
	s_add_i32 s10, s10, s82
	s_mul_i32 s10, s10, s24
	s_add_u32 s28, s58, s10
	s_addc_u32 s29, s59, 0
	s_add_u32 s28, s28, 0x0
	s_addc_u32 s29, s29, 0
	s_add_u32 s0, s28, 0x1000
	s_addc_u32 s1, s29, 0
	global_load_dwordx4 v[122:125], v244, s[26:27]
	global_load_dwordx4 v[126:129], v244, s[26:27] offset:1024
	global_load_dwordx4 v[130:133], v244, s[26:27] offset:2048
	global_load_dwordx4 v[134:137], v244, s[26:27] offset:3072
	global_load_dwordx4 v[160:163], v244, s[28:29]
	global_load_dwordx4 v[164:167], v244, s[28:29] offset:1024
	global_load_dwordx4 v[168:171], v244, s[28:29] offset:2048
	global_load_dwordx4 v[172:175], v244, s[28:29] offset:3072
	global_load_dwordx4 v[176:179], v244, s[0:1]
	global_load_dwordx4 v[180:183], v244, s[0:1] offset:1024
	global_load_dwordx4 v[184:187], v244, s[0:1] offset:2048
	global_load_dwordx4 v[188:191], v244, s[0:1] offset:3072
	s_waitcnt vmcnt(32)
; DI unsigned pk_bf16(float lo, float hi) { f32x2 v = {lo, hi}; bf16v2 b = __builtin_convertvector(v, bf16v2); return __builtin_bit_cast(unsigned, b); }
; DI float red64(float x) { for (int o = 32; o > 0; o >>= 1) x += __shfl_xor(x, o); return x; }
; DI void modnorm_rows(const Params& p, int l, int which  , bool from_inputs, bool skip_ctx, int w0, int wstride, int lane) {
;     ...
;     if (i + wstride < nrows) {
;       const int rn = rowof(i + wstride); const float* src = xsrc_row(p, from_inputs, rn / TB, rn % TB);
; #pragma unroll
;       for (int q = 0; q < 4; ++q) vn[q] = *(const f32x4*)(src + q * 256 + lane * 4);
;     }
;     const float* mod = p.MOD + (size_t)(l * 9 + (s < NCTX ? 8 : b)) * 6144 + (which ? 3 * 1024 : 0);
;     f32x4 sh[4], sc[4];
; #pragma unroll
;     for (int q = 0; q < 4; ++q) { sh[q] = *(const f32x4*)(mod + q * 256 + lane * 4); sc[q] = *(const f32x4*)(mod + 1024 + q * 256 + lane * 4); }
;     float ss = 0.f;
; #pragma unroll
;     for (int q = 0; q < 4; ++q) ss += v[q][0] * v[q][0] + v[q][1] * v[q][1] + v[q][2] * v[q][2] + v[q][3] * v[q][3];
;     ss = red64(ss);
;     const float rs = rsqrtf(ss * (1.f / 1024.f) + EPSF);
;     bf16_t* dst = p.HY + (size_t)row * DM;
; #pragma unroll
;     for (int q = 0; q < 4; ++q) {
;       float o[4];
; #pragma unroll
;       for (int j = 0; j < 4; ++j) o[j] = (v[q][j] * rs * gg[q][j]) * (1.f + sc[q][j]) + sh[q][j];
;       u32x2 w = {pk_bf16(o[0], o[1]), pk_bf16(o[2], o[3])};
;       *(u32x2*)(dst + q * 256 + lane * 4) = w;
;     }
;   }
	v_pk_mul_f32 v[246:247], v[18:19], v[18:19]
	v_pk_fma_f32 v[246:247], v[20:21], v[20:21], v[246:247]
	v_pk_fma_f32 v[246:247], v[22:23], v[22:23], v[246:247]
	v_pk_fma_f32 v[246:247], v[24:25], v[24:25], v[246:247]
	v_pk_fma_f32 v[246:247], v[26:27], v[26:27], v[246:247]
	v_pk_fma_f32 v[246:247], v[28:29], v[28:29], v[246:247]
	v_pk_fma_f32 v[246:247], v[30:31], v[30:31], v[246:247]
	v_pk_fma_f32 v[246:247], v[32:33], v[32:33], v[246:247]
	s_nop 0
	v_add_f32_e32 v246, v246, v247
	s_nop 1
	v_add_f32_dpp v246, v246, v246 quad_perm:[1,0,3,2] row_mask:0xf bank_mask:0xf
	s_nop 1
	v_add_f32_dpp v246, v246, v246 quad_perm:[2,3,0,1] row_mask:0xf bank_mask:0xf
	s_nop 1
	v_add_f32_dpp v246, v246, v246 row_half_mirror row_mask:0xf bank_mask:0xf
	s_nop 1
	v_add_f32_dpp v246, v246, v246 row_mirror row_mask:0xf bank_mask:0xf
	s_nop 1
	v_add_f32_dpp v246, v246, v246 row_bcast:15 row_mask:0xa bank_mask:0xf
	s_nop 1
	v_add_f32_dpp v246, v246, v246 row_bcast:31 row_mask:0xc bank_mask:0xf
	s_nop 1
	v_readlane_b32 s0, v246, 63
	s_add_i32 s21, s20, 6144
	s_lshl_b32 s21, s21, 11
	s_add_u32 s10, s16, s21
	s_addc_u32 s11, s17, 0
	v_mov_b32_e32 v248, s0
	v_fmamk_f32 v248, v248, 0x3a800000, v143
	v_rsq_f32_e32 v248, v248
	s_nop 0
	v_pk_mul_f32 v[18:19], v[18:19], v[248:249] op_sel_hi:[1,0]
	v_pk_add_f32 v[50:51], v[50:51], 1.0 op_sel_hi:[1,0]
	v_pk_mul_f32 v[18:19], v[2:3], v[18:19]
	v_pk_fma_f32 v[18:19], v[50:51], v[18:19], v[34:35]
	v_pk_mul_f32 v[20:21], v[20:21], v[248:249] op_sel_hi:[1,0]
	v_pk_add_f32 v[52:53], v[52:53], 1.0 op_sel_hi:[1,0]
	v_pk_mul_f32 v[20:21], v[4:5], v[20:21]
	v_pk_fma_f32 v[20:21], v[52:53], v[20:21], v[36:37]
	v_cvt_pk_bf16_f32 v34, v18, v19
	v_cvt_pk_bf16_f32 v35, v20, v21
	global_store_dwordx2 v245, v[34:35], s[10:11]
	v_pk_mul_f32 v[22:23], v[22:23], v[248:249] op_sel_hi:[1,0]
	v_pk_add_f32 v[54:55], v[54:55], 1.0 op_sel_hi:[1,0]
	v_pk_mul_f32 v[22:23], v[6:7], v[22:23]
	v_pk_fma_f32 v[22:23], v[54:55], v[22:23], v[38:39]
	v_pk_mul_f32 v[24:25], v[24:25], v[248:249] op_sel_hi:[1,0]
	v_pk_add_f32 v[56:57], v[56:57], 1.0 op_sel_hi:[1,0]
	v_pk_mul_f32 v[24:25], v[8:9], v[24:25]
	v_pk_fma_f32 v[24:25], v[56:57], v[24:25], v[40:41]
	v_cvt_pk_bf16_f32 v38, v22, v23
	v_cvt_pk_bf16_f32 v39, v24, v25
	global_store_dwordx2 v245, v[38:39], s[10:11] offset:512
	v_pk_mul_f32 v[26:27], v[26:27], v[248:249] op_sel_hi:[1,0]
	v_pk_add_f32 v[58:59], v[58:59], 1.0 op_sel_hi:[1,0]
	v_pk_mul_f32 v[26:27], v[10:11], v[26:27]
	v_pk_fma_f32 v[26:27], v[58:59], v[26:27], v[42:43]
	v_pk_mul_f32 v[28:29], v[28:29], v[248:249] op_sel_hi:[1,0]
	v_pk_add_f32 v[60:61], v[60:61], 1.0 op_sel_hi:[1,0]
	v_pk_mul_f32 v[28:29], v[12:13], v[28:29]
	v_pk_fma_f32 v[28:29], v[60:61], v[28:29], v[44:45]
	v_cvt_pk_bf16_f32 v42, v26, v27
	v_cvt_pk_bf16_f32 v43, v28, v29
	global_store_dwordx2 v245, v[42:43], s[10:11] offset:1024
	v_pk_mul_f32 v[30:31], v[30:31], v[248:249] op_sel_hi:[1,0]
	v_pk_add_f32 v[62:63], v[62:63], 1.0 op_sel_hi:[1,0]
	v_pk_mul_f32 v[30:31], v[14:15], v[30:31]
	v_pk_fma_f32 v[30:31], v[62:63], v[30:31], v[46:47]
	v_pk_mul_f32 v[32:33], v[32:33], v[248:249] op_sel_hi:[1,0]
	v_pk_add_f32 v[64:65], v[64:65], 1.0 op_sel_hi:[1,0]
	v_pk_mul_f32 v[32:33], v[16:17], v[32:33]
	v_pk_fma_f32 v[32:33], v[64:65], v[32:33], v[48:49]
	v_cvt_pk_bf16_f32 v46, v30, v31
	v_cvt_pk_bf16_f32 v47, v32, v33
	global_store_dwordx2 v245, v[46:47], s[10:11] offset:1536
	s_add_i32 s21, s20, 12288
	s_mul_hi_u32 s7, s21, 0x38e38e39
	s_lshr_b32 s7, s7, 9
	s_mul_i32 s8, s7, 0x900
	s_sub_i32 s8, s21, s8
	s_lshl_b32 s9, s7, 11
	s_add_i32 s9, s9, s8
	s_add_i32 s9, s9, 0xffffff00
	s_lshl_b32 s10, s7, 8
	s_add_i32 s10, s10, s8
	s_cmpk_gt_i32 s8, 0xff
	s_cselect_b32 s9, s9, s10
	s_cselect_b32 s26, s12, s14
	s_cselect_b32 s27, s13, s15
	s_cselect_b32 s10, s7, 8
	s_lshl_b32 s9, s9, 12
	s_add_u32 s26, s26, s9
	s_addc_u32 s27, s27, 0
	s_add_i32 s10, s10, s82
	s_mul_i32 s10, s10, s24
	s_add_u32 s28, s58, s10
	s_addc_u32 s29, s59, 0
	s_add_u32 s28, s28, 0x0
	s_addc_u32 s29, s29, 0
	s_add_u32 s0, s28, 0x1000
	s_addc_u32 s1, s29, 0
	global_load_dwordx4 v[18:21], v244, s[26:27]
	global_load_dwordx4 v[22:25], v244, s[26:27] offset:1024
	global_load_dwordx4 v[26:29], v244, s[26:27] offset:2048
	global_load_dwordx4 v[30:33], v244, s[26:27] offset:3072
	global_load_dwordx4 v[34:37], v244, s[28:29]
	global_load_dwordx4 v[38:41], v244, s[28:29] offset:1024
	global_load_dwordx4 v[42:45], v244, s[28:29] offset:2048
	global_load_dwordx4 v[46:49], v244, s[28:29] offset:3072
	global_load_dwordx4 v[50:53], v244, s[0:1]
	global_load_dwordx4 v[54:57], v244, s[0:1] offset:1024
	global_load_dwordx4 v[58:61], v244, s[0:1] offset:2048
	global_load_dwordx4 v[62:65], v244, s[0:1] offset:3072
	s_waitcnt vmcnt(32)
; DI unsigned pk_bf16(float lo, float hi) { f32x2 v = {lo, hi}; bf16v2 b = __builtin_convertvector(v, bf16v2); return __builtin_bit_cast(unsigned, b); }
; DI float red64(float x) { for (int o = 32; o > 0; o >>= 1) x += __shfl_xor(x, o); return x; }
; DI void modnorm_rows(const Params& p, int l, int which  , bool from_inputs, bool skip_ctx, int w0, int wstride, int lane) {
;     ...
;     if (i + wstride < nrows) {
;       const int rn = rowof(i + wstride); const float* src = xsrc_row(p, from_inputs, rn / TB, rn % TB);
; #pragma unroll
;       for (int q = 0; q < 4; ++q) vn[q] = *(const f32x4*)(src + q * 256 + lane * 4);
;     }
;     const float* mod = p.MOD + (size_t)(l * 9 + (s < NCTX ? 8 : b)) * 6144 + (which ? 3 * 1024 : 0);
;     f32x4 sh[4], sc[4];
; #pragma unroll
;     for (int q = 0; q < 4; ++q) { sh[q] = *(const f32x4*)(mod + q * 256 + lane * 4); sc[q] = *(const f32x4*)(mod + 1024 + q * 256 + lane * 4); }
;     float ss = 0.f;
; #pragma unroll
;     for (int q = 0; q < 4; ++q) ss += v[q][0] * v[q][0] + v[q][1] * v[q][1] + v[q][2] * v[q][2] + v[q][3] * v[q][3];
;     ss = red64(ss);
;     const float rs = rsqrtf(ss * (1.f / 1024.f) + EPSF);
;     bf16_t* dst = p.HY + (size_t)row * DM;
; #pragma unroll
;     for (int q = 0; q < 4; ++q) {
;       float o[4];
; #pragma unroll
;       for (int j = 0; j < 4; ++j) o[j] = (v[q][j] * rs * gg[q][j]) * (1.f + sc[q][j]) + sh[q][j];
;       u32x2 w = {pk_bf16(o[0], o[1]), pk_bf16(o[2], o[3])};
;       *(u32x2*)(dst + q * 256 + lane * 4) = w;
;     }
;   }
	v_pk_mul_f32 v[246:247], v[66:67], v[66:67]
	v_pk_fma_f32 v[246:247], v[68:69], v[68:69], v[246:247]
	v_pk_fma_f32 v[246:247], v[70:71], v[70:71], v[246:247]
	v_pk_fma_f32 v[246:247], v[72:73], v[72:73], v[246:247]
	v_pk_fma_f32 v[246:247], v[74:75], v[74:75], v[246:247]
	v_pk_fma_f32 v[246:247], v[76:77], v[76:77], v[246:247]
	v_pk_fma_f32 v[246:247], v[78:79], v[78:79], v[246:247]
	v_pk_fma_f32 v[246:247], v[80:81], v[80:81], v[246:247]
	s_nop 0
	v_add_f32_e32 v246, v246, v247
	s_nop 1
	v_add_f32_dpp v246, v246, v246 quad_perm:[1,0,3,2] row_mask:0xf bank_mask:0xf
	s_nop 1
	v_add_f32_dpp v246, v246, v246 quad_perm:[2,3,0,1] row_mask:0xf bank_mask:0xf
	s_nop 1
	v_add_f32_dpp v246, v246, v246 row_half_mirror row_mask:0xf bank_mask:0xf
	s_nop 1
	v_add_f32_dpp v246, v246, v246 row_mirror row_mask:0xf bank_mask:0xf
	s_nop 1
	v_add_f32_dpp v246, v246, v246 row_bcast:15 row_mask:0xa bank_mask:0xf
	s_nop 1
	v_add_f32_dpp v246, v246, v246 row_bcast:31 row_mask:0xc bank_mask:0xf
	s_nop 1
	v_readlane_b32 s0, v246, 63
	s_add_i32 s21, s20, 8192
	s_lshl_b32 s21, s21, 11
	s_add_u32 s10, s16, s21
	s_addc_u32 s11, s17, 0
	v_mov_b32_e32 v248, s0
	v_fmamk_f32 v248, v248, 0x3a800000, v143
	v_rsq_f32_e32 v248, v248
	s_nop 0
	v_pk_mul_f32 v[66:67], v[66:67], v[248:249] op_sel_hi:[1,0]
	v_pk_add_f32 v[98:99], v[98:99], 1.0 op_sel_hi:[1,0]
	v_pk_mul_f32 v[66:67], v[2:3], v[66:67]
	v_pk_fma_f32 v[66:67], v[98:99], v[66:67], v[82:83]
	v_pk_mul_f32 v[68:69], v[68:69], v[248:249] op_sel_hi:[1,0]
	v_pk_add_f32 v[100:101], v[100:101], 1.0 op_sel_hi:[1,0]
	v_pk_mul_f32 v[68:69], v[4:5], v[68:69]
	v_pk_fma_f32 v[68:69], v[100:101], v[68:69], v[84:85]
	v_cvt_pk_bf16_f32 v82, v66, v67
	v_cvt_pk_bf16_f32 v83, v68, v69
	global_store_dwordx2 v245, v[82:83], s[10:11]
	v_pk_mul_f32 v[70:71], v[70:71], v[248:249] op_sel_hi:[1,0]
	v_pk_add_f32 v[102:103], v[102:103], 1.0 op_sel_hi:[1,0]
	v_pk_mul_f32 v[70:71], v[6:7], v[70:71]
	v_pk_fma_f32 v[70:71], v[102:103], v[70:71], v[86:87]
	v_pk_mul_f32 v[72:73], v[72:73], v[248:249] op_sel_hi:[1,0]
	v_pk_add_f32 v[104:105], v[104:105], 1.0 op_sel_hi:[1,0]
	v_pk_mul_f32 v[72:73], v[8:9], v[72:73]
	v_pk_fma_f32 v[72:73], v[104:105], v[72:73], v[88:89]
	v_cvt_pk_bf16_f32 v86, v70, v71
	v_cvt_pk_bf16_f32 v87, v72, v73
	global_store_dwordx2 v245, v[86:87], s[10:11] offset:512
	v_pk_mul_f32 v[74:75], v[74:75], v[248:249] op_sel_hi:[1,0]
	v_pk_add_f32 v[106:107], v[106:107], 1.0 op_sel_hi:[1,0]
	v_pk_mul_f32 v[74:75], v[10:11], v[74:75]
	v_pk_fma_f32 v[74:75], v[106:107], v[74:75], v[90:91]
	v_pk_mul_f32 v[76:77], v[76:77], v[248:249] op_sel_hi:[1,0]
	v_pk_add_f32 v[108:109], v[108:109], 1.0 op_sel_hi:[1,0]
	v_pk_mul_f32 v[76:77], v[12:13], v[76:77]
	v_pk_fma_f32 v[76:77], v[108:109], v[76:77], v[92:93]
	v_cvt_pk_bf16_f32 v90, v74, v75
	v_cvt_pk_bf16_f32 v91, v76, v77
	global_store_dwordx2 v245, v[90:91], s[10:11] offset:1024
	v_pk_mul_f32 v[78:79], v[78:79], v[248:249] op_sel_hi:[1,0]
	v_pk_add_f32 v[118:119], v[118:119], 1.0 op_sel_hi:[1,0]
	v_pk_mul_f32 v[78:79], v[14:15], v[78:79]
	v_pk_fma_f32 v[78:79], v[118:119], v[78:79], v[94:95]
	v_pk_mul_f32 v[80:81], v[80:81], v[248:249] op_sel_hi:[1,0]
	v_pk_add_f32 v[120:121], v[120:121], 1.0 op_sel_hi:[1,0]
	v_pk_mul_f32 v[80:81], v[16:17], v[80:81]
	v_pk_fma_f32 v[80:81], v[120:121], v[80:81], v[96:97]
	v_cvt_pk_bf16_f32 v94, v78, v79
	v_cvt_pk_bf16_f32 v95, v80, v81
	global_store_dwordx2 v245, v[94:95], s[10:11] offset:1536
	s_add_i32 s21, s20, 14336
	s_mul_hi_u32 s7, s21, 0x38e38e39
	s_lshr_b32 s7, s7, 9
	s_mul_i32 s8, s7, 0x900
	s_sub_i32 s8, s21, s8
	s_lshl_b32 s9, s7, 11
	s_add_i32 s9, s9, s8
	s_add_i32 s9, s9, 0xffffff00
	s_lshl_b32 s10, s7, 8
	s_add_i32 s10, s10, s8
	s_cmpk_gt_i32 s8, 0xff
	s_cselect_b32 s9, s9, s10
	s_cselect_b32 s26, s12, s14
	s_cselect_b32 s27, s13, s15
	s_cselect_b32 s10, s7, 8
	s_lshl_b32 s9, s9, 12
	s_add_u32 s26, s26, s9
	s_addc_u32 s27, s27, 0
	s_add_i32 s10, s10, s82
	s_mul_i32 s10, s10, s24
	s_add_u32 s28, s58, s10
	s_addc_u32 s29, s59, 0
	s_add_u32 s28, s28, 0x0
	s_addc_u32 s29, s29, 0
	s_add_u32 s0, s28, 0x1000
	s_addc_u32 s1, s29, 0
	global_load_dwordx4 v[66:69], v244, s[26:27]
	global_load_dwordx4 v[70:73], v244, s[26:27] offset:1024
	global_load_dwordx4 v[74:77], v244, s[26:27] offset:2048
	global_load_dwordx4 v[78:81], v244, s[26:27] offset:3072
	global_load_dwordx4 v[82:85], v244, s[28:29]
	global_load_dwordx4 v[86:89], v244, s[28:29] offset:1024
	global_load_dwordx4 v[90:93], v244, s[28:29] offset:2048
	global_load_dwordx4 v[94:97], v244, s[28:29] offset:3072
	global_load_dwordx4 v[98:101], v244, s[0:1]
	global_load_dwordx4 v[102:105], v244, s[0:1] offset:1024
	global_load_dwordx4 v[106:109], v244, s[0:1] offset:2048
	global_load_dwordx4 v[118:121], v244, s[0:1] offset:3072
	s_waitcnt vmcnt(32)
; DI unsigned pk_bf16(float lo, float hi) { f32x2 v = {lo, hi}; bf16v2 b = __builtin_convertvector(v, bf16v2); return __builtin_bit_cast(unsigned, b); }
; DI float red64(float x) { for (int o = 32; o > 0; o >>= 1) x += __shfl_xor(x, o); return x; }
; DI void modnorm_rows(const Params& p, int l, int which  , bool from_inputs, bool skip_ctx, int w0, int wstride, int lane) {
;     ...
;     if (i + wstride < nrows) {
;       const int rn = rowof(i + wstride); const float* src = xsrc_row(p, from_inputs, rn / TB, rn % TB);
; #pragma unroll
;       for (int q = 0; q < 4; ++q) vn[q] = *(const f32x4*)(src + q * 256 + lane * 4);
;     }
;     const float* mod = p.MOD + (size_t)(l * 9 + (s < NCTX ? 8 : b)) * 6144 + (which ? 3 * 1024 : 0);
;     f32x4 sh[4], sc[4];
; #pragma unroll
;     for (int q = 0; q < 4; ++q) { sh[q] = *(const f32x4*)(mod + q * 256 + lane * 4); sc[q] = *(const f32x4*)(mod + 1024 + q * 256 + lane * 4); }
;     float ss = 0.f;
; #pragma unroll
;     for (int q = 0; q < 4; ++q) ss += v[q][0] * v[q][0] + v[q][1] * v[q][1] + v[q][2] * v[q][2] + v[q][3] * v[q][3];
;     ss = red64(ss);
;     const float rs = rsqrtf(ss * (1.f / 1024.f) + EPSF);
;     bf16_t* dst = p.HY + (size_t)row * DM;
; #pragma unroll
;     for (int q = 0; q < 4; ++q) {
;       float o[4];
; #pragma unroll
;       for (int j = 0; j < 4; ++j) o[j] = (v[q][j] * rs * gg[q][j]) * (1.f + sc[q][j]) + sh[q][j];
;       u32x2 w = {pk_bf16(o[0], o[1]), pk_bf16(o[2], o[3])};
;       *(u32x2*)(dst + q * 256 + lane * 4) = w;
;     }
;   }
	v_pk_mul_f32 v[246:247], v[122:123], v[122:123]
	v_pk_fma_f32 v[246:247], v[124:125], v[124:125], v[246:247]
	v_pk_fma_f32 v[246:247], v[126:127], v[126:127], v[246:247]
	v_pk_fma_f32 v[246:247], v[128:129], v[128:129], v[246:247]
	v_pk_fma_f32 v[246:247], v[130:131], v[130:131], v[246:247]
	v_pk_fma_f32 v[246:247], v[132:133], v[132:133], v[246:247]
	v_pk_fma_f32 v[246:247], v[134:135], v[134:135], v[246:247]
	v_pk_fma_f32 v[246:247], v[136:137], v[136:137], v[246:247]
	s_nop 0
	v_add_f32_e32 v246, v246, v247
	s_nop 1
	v_add_f32_dpp v246, v246, v246 quad_perm:[1,0,3,2] row_mask:0xf bank_mask:0xf
	s_nop 1
	v_add_f32_dpp v246, v246, v246 quad_perm:[2,3,0,1] row_mask:0xf bank_mask:0xf
	s_nop 1
	v_add_f32_dpp v246, v246, v246 row_half_mirror row_mask:0xf bank_mask:0xf
	s_nop 1
	v_add_f32_dpp v246, v246, v246 row_mirror row_mask:0xf bank_mask:0xf
	s_nop 1
	v_add_f32_dpp v246, v246, v246 row_bcast:15 row_mask:0xa bank_mask:0xf
	s_nop 1
	v_add_f32_dpp v246, v246, v246 row_bcast:31 row_mask:0xc bank_mask:0xf
	s_nop 1
	v_readlane_b32 s0, v246, 63
	s_add_i32 s21, s20, 10240
	s_lshl_b32 s21, s21, 11
	s_add_u32 s10, s16, s21
	s_addc_u32 s11, s17, 0
	v_mov_b32_e32 v248, s0
	v_fmamk_f32 v248, v248, 0x3a800000, v143
	v_rsq_f32_e32 v248, v248
	s_nop 0
	v_pk_mul_f32 v[122:123], v[122:123], v[248:249] op_sel_hi:[1,0]
	v_pk_add_f32 v[176:177], v[176:177], 1.0 op_sel_hi:[1,0]
	v_pk_mul_f32 v[122:123], v[2:3], v[122:123]
	v_pk_fma_f32 v[122:123], v[176:177], v[122:123], v[160:161]
	v_pk_mul_f32 v[124:125], v[124:125], v[248:249] op_sel_hi:[1,0]
	v_pk_add_f32 v[178:179], v[178:179], 1.0 op_sel_hi:[1,0]
	v_pk_mul_f32 v[124:125], v[4:5], v[124:125]
	v_pk_fma_f32 v[124:125], v[178:179], v[124:125], v[162:163]
	v_cvt_pk_bf16_f32 v160, v122, v123
	v_cvt_pk_bf16_f32 v161, v124, v125
	global_store_dwordx2 v245, v[160:161], s[10:11]
	v_pk_mul_f32 v[126:127], v[126:127], v[248:249] op_sel_hi:[1,0]
	v_pk_add_f32 v[180:181], v[180:181], 1.0 op_sel_hi:[1,0]
	v_pk_mul_f32 v[126:127], v[6:7], v[126:127]
	v_pk_fma_f32 v[126:127], v[180:181], v[126:127], v[164:165]
	v_pk_mul_f32 v[128:129], v[128:129], v[248:249] op_sel_hi:[1,0]
	v_pk_add_f32 v[182:183], v[182:183], 1.0 op_sel_hi:[1,0]
	v_pk_mul_f32 v[128:129], v[8:9], v[128:129]
	v_pk_fma_f32 v[128:129], v[182:183], v[128:129], v[166:167]
	v_cvt_pk_bf16_f32 v164, v126, v127
	v_cvt_pk_bf16_f32 v165, v128, v129
	global_store_dwordx2 v245, v[164:165], s[10:11] offset:512
	v_pk_mul_f32 v[130:131], v[130:131], v[248:249] op_sel_hi:[1,0]
	v_pk_add_f32 v[184:185], v[184:185], 1.0 op_sel_hi:[1,0]
	v_pk_mul_f32 v[130:131], v[10:11], v[130:131]
	v_pk_fma_f32 v[130:131], v[184:185], v[130:131], v[168:169]
	v_pk_mul_f32 v[132:133], v[132:133], v[248:249] op_sel_hi:[1,0]
	v_pk_add_f32 v[186:187], v[186:187], 1.0 op_sel_hi:[1,0]
	v_pk_mul_f32 v[132:133], v[12:13], v[132:133]
	v_pk_fma_f32 v[132:133], v[186:187], v[132:133], v[170:171]
	v_cvt_pk_bf16_f32 v168, v130, v131
	v_cvt_pk_bf16_f32 v169, v132, v133
	global_store_dwordx2 v245, v[168:169], s[10:11] offset:1024
	v_pk_mul_f32 v[134:135], v[134:135], v[248:249] op_sel_hi:[1,0]
	v_pk_add_f32 v[188:189], v[188:189], 1.0 op_sel_hi:[1,0]
	v_pk_mul_f32 v[134:135], v[14:15], v[134:135]
	v_pk_fma_f32 v[134:135], v[188:189], v[134:135], v[172:173]
	v_pk_mul_f32 v[136:137], v[136:137], v[248:249] op_sel_hi:[1,0]
	v_pk_add_f32 v[190:191], v[190:191], 1.0 op_sel_hi:[1,0]
	v_pk_mul_f32 v[136:137], v[16:17], v[136:137]
	v_pk_fma_f32 v[136:137], v[190:191], v[136:137], v[174:175]
	v_cvt_pk_bf16_f32 v172, v134, v135
	v_cvt_pk_bf16_f32 v173, v136, v137
	global_store_dwordx2 v245, v[172:173], s[10:11] offset:1536
	s_add_i32 s21, s20, 16384
	s_mul_hi_u32 s7, s21, 0x38e38e39
	s_lshr_b32 s7, s7, 9
	s_mul_i32 s8, s7, 0x900
	s_sub_i32 s8, s21, s8
	s_lshl_b32 s9, s7, 11
	s_add_i32 s9, s9, s8
	s_add_i32 s9, s9, 0xffffff00
	s_lshl_b32 s10, s7, 8
	s_add_i32 s10, s10, s8
	s_cmpk_gt_i32 s8, 0xff
	s_cselect_b32 s9, s9, s10
	s_cselect_b32 s26, s12, s14
	s_cselect_b32 s27, s13, s15
	s_cselect_b32 s10, s7, 8
	s_lshl_b32 s9, s9, 12
	s_add_u32 s26, s26, s9
	s_addc_u32 s27, s27, 0
	s_add_i32 s10, s10, s82
	s_mul_i32 s10, s10, s24
	s_add_u32 s28, s58, s10
	s_addc_u32 s29, s59, 0
	s_add_u32 s28, s28, 0x0
	s_addc_u32 s29, s29, 0
	s_add_u32 s0, s28, 0x1000
	s_addc_u32 s1, s29, 0
	global_load_dwordx4 v[122:125], v244, s[26:27]
	global_load_dwordx4 v[126:129], v244, s[26:27] offset:1024
	global_load_dwordx4 v[130:133], v244, s[26:27] offset:2048
	global_load_dwordx4 v[134:137], v244, s[26:27] offset:3072
	global_load_dwordx4 v[160:163], v244, s[28:29]
	global_load_dwordx4 v[164:167], v244, s[28:29] offset:1024
	global_load_dwordx4 v[168:171], v244, s[28:29] offset:2048
	global_load_dwordx4 v[172:175], v244, s[28:29] offset:3072
	global_load_dwordx4 v[176:179], v244, s[0:1]
	global_load_dwordx4 v[180:183], v244, s[0:1] offset:1024
	global_load_dwordx4 v[184:187], v244, s[0:1] offset:2048
	global_load_dwordx4 v[188:191], v244, s[0:1] offset:3072
	s_waitcnt vmcnt(32)
; DI unsigned pk_bf16(float lo, float hi) { f32x2 v = {lo, hi}; bf16v2 b = __builtin_convertvector(v, bf16v2); return __builtin_bit_cast(unsigned, b); }
; DI float red64(float x) { for (int o = 32; o > 0; o >>= 1) x += __shfl_xor(x, o); return x; }
; DI void modnorm_rows(const Params& p, int l, int which  , bool from_inputs, bool skip_ctx, int w0, int wstride, int lane) {
;     ...
;     for (int q = 0; q < 4; ++q) { sh[q] = *(const f32x4*)(mod + q * 256 + lane * 4); sc[q] = *(const f32x4*)(mod + 1024 + q * 256 + lane * 4); }
;     float ss = 0.f;
; #pragma unroll
;     for (int q = 0; q < 4; ++q) ss += v[q][0] * v[q][0] + v[q][1] * v[q][1] + v[q][2] * v[q][2] + v[q][3] * v[q][3];
;     ss = red64(ss);
;     const float rs = rsqrtf(ss * (1.f / 1024.f) + EPSF);
;     bf16_t* dst = p.HY + (size_t)row * DM;
; #pragma unroll
;     for (int q = 0; q < 4; ++q) {
;       float o[4];
; #pragma unroll
;       for (int j = 0; j < 4; ++j) o[j] = (v[q][j] * rs * gg[q][j]) * (1.f + sc[q][j]) + sh[q][j];
;       u32x2 w = {pk_bf16(o[0], o[1]), pk_bf16(o[2], o[3])};
;       *(u32x2*)(dst + q * 256 + lane * 4) = w;
;     }
;   }
	v_pk_mul_f32 v[246:247], v[18:19], v[18:19]
	v_pk_fma_f32 v[246:247], v[20:21], v[20:21], v[246:247]
	v_pk_fma_f32 v[246:247], v[22:23], v[22:23], v[246:247]
	v_pk_fma_f32 v[246:247], v[24:25], v[24:25], v[246:247]
	v_pk_fma_f32 v[246:247], v[26:27], v[26:27], v[246:247]
	v_pk_fma_f32 v[246:247], v[28:29], v[28:29], v[246:247]
	v_pk_fma_f32 v[246:247], v[30:31], v[30:31], v[246:247]
	v_pk_fma_f32 v[246:247], v[32:33], v[32:33], v[246:247]
	s_nop 0
	v_add_f32_e32 v246, v246, v247
	s_nop 1
	v_add_f32_dpp v246, v246, v246 quad_perm:[1,0,3,2] row_mask:0xf bank_mask:0xf
	s_nop 1
	v_add_f32_dpp v246, v246, v246 quad_perm:[2,3,0,1] row_mask:0xf bank_mask:0xf
	s_nop 1
	v_add_f32_dpp v246, v246, v246 row_half_mirror row_mask:0xf bank_mask:0xf
	s_nop 1
	v_add_f32_dpp v246, v246, v246 row_mirror row_mask:0xf bank_mask:0xf
	s_nop 1
	v_add_f32_dpp v246, v246, v246 row_bcast:15 row_mask:0xa bank_mask:0xf
	s_nop 1
	v_add_f32_dpp v246, v246, v246 row_bcast:31 row_mask:0xc bank_mask:0xf
	s_nop 1
	v_readlane_b32 s0, v246, 63
	s_add_i32 s21, s20, 12288
	s_lshl_b32 s21, s21, 11
	s_add_u32 s10, s16, s21
	s_addc_u32 s11, s17, 0
	v_mov_b32_e32 v248, s0
	v_fmamk_f32 v248, v248, 0x3a800000, v143
	v_rsq_f32_e32 v248, v248
	s_nop 0
	v_pk_mul_f32 v[18:19], v[18:19], v[248:249] op_sel_hi:[1,0]
	v_pk_add_f32 v[50:51], v[50:51], 1.0 op_sel_hi:[1,0]
	v_pk_mul_f32 v[18:19], v[2:3], v[18:19]
	v_pk_fma_f32 v[18:19], v[50:51], v[18:19], v[34:35]
	v_pk_mul_f32 v[20:21], v[20:21], v[248:249] op_sel_hi:[1,0]
	v_pk_add_f32 v[52:53], v[52:53], 1.0 op_sel_hi:[1,0]
	v_pk_mul_f32 v[20:21], v[4:5], v[20:21]
	v_pk_fma_f32 v[20:21], v[52:53], v[20:21], v[36:37]
	v_cvt_pk_bf16_f32 v34, v18, v19
	v_cvt_pk_bf16_f32 v35, v20, v21
	global_store_dwordx2 v245, v[34:35], s[10:11]
	v_pk_mul_f32 v[22:23], v[22:23], v[248:249] op_sel_hi:[1,0]
	v_pk_add_f32 v[54:55], v[54:55], 1.0 op_sel_hi:[1,0]
	v_pk_mul_f32 v[22:23], v[6:7], v[22:23]
	v_pk_fma_f32 v[22:23], v[54:55], v[22:23], v[38:39]
	v_pk_mul_f32 v[24:25], v[24:25], v[248:249] op_sel_hi:[1,0]
	v_pk_add_f32 v[56:57], v[56:57], 1.0 op_sel_hi:[1,0]
	v_pk_mul_f32 v[24:25], v[8:9], v[24:25]
	v_pk_fma_f32 v[24:25], v[56:57], v[24:25], v[40:41]
	v_cvt_pk_bf16_f32 v38, v22, v23
	v_cvt_pk_bf16_f32 v39, v24, v25
	global_store_dwordx2 v245, v[38:39], s[10:11] offset:512
	v_pk_mul_f32 v[26:27], v[26:27], v[248:249] op_sel_hi:[1,0]
	v_pk_add_f32 v[58:59], v[58:59], 1.0 op_sel_hi:[1,0]
	v_pk_mul_f32 v[26:27], v[10:11], v[26:27]
	v_pk_fma_f32 v[26:27], v[58:59], v[26:27], v[42:43]
	v_pk_mul_f32 v[28:29], v[28:29], v[248:249] op_sel_hi:[1,0]
	v_pk_add_f32 v[60:61], v[60:61], 1.0 op_sel_hi:[1,0]
	v_pk_mul_f32 v[28:29], v[12:13], v[28:29]
	v_pk_fma_f32 v[28:29], v[60:61], v[28:29], v[44:45]
	v_cvt_pk_bf16_f32 v42, v26, v27
	v_cvt_pk_bf16_f32 v43, v28, v29
	global_store_dwordx2 v245, v[42:43], s[10:11] offset:1024
	v_pk_mul_f32 v[30:31], v[30:31], v[248:249] op_sel_hi:[1,0]
	v_pk_add_f32 v[62:63], v[62:63], 1.0 op_sel_hi:[1,0]
	v_pk_mul_f32 v[30:31], v[14:15], v[30:31]
	v_pk_fma_f32 v[30:31], v[62:63], v[30:31], v[46:47]
	v_pk_mul_f32 v[32:33], v[32:33], v[248:249] op_sel_hi:[1,0]
	v_pk_add_f32 v[64:65], v[64:65], 1.0 op_sel_hi:[1,0]
	v_pk_mul_f32 v[32:33], v[16:17], v[32:33]
	v_pk_fma_f32 v[32:33], v[64:65], v[32:33], v[48:49]
	v_cvt_pk_bf16_f32 v46, v30, v31
	v_cvt_pk_bf16_f32 v47, v32, v33
	global_store_dwordx2 v245, v[46:47], s[10:11] offset:1536
	s_waitcnt vmcnt(20)
	v_pk_mul_f32 v[246:247], v[66:67], v[66:67]
	v_pk_fma_f32 v[246:247], v[68:69], v[68:69], v[246:247]
	v_pk_fma_f32 v[246:247], v[70:71], v[70:71], v[246:247]
	v_pk_fma_f32 v[246:247], v[72:73], v[72:73], v[246:247]
	v_pk_fma_f32 v[246:247], v[74:75], v[74:75], v[246:247]
	v_pk_fma_f32 v[246:247], v[76:77], v[76:77], v[246:247]
	v_pk_fma_f32 v[246:247], v[78:79], v[78:79], v[246:247]
	v_pk_fma_f32 v[246:247], v[80:81], v[80:81], v[246:247]
	s_nop 0
	v_add_f32_e32 v246, v246, v247
	s_nop 1
	v_add_f32_dpp v246, v246, v246 quad_perm:[1,0,3,2] row_mask:0xf bank_mask:0xf
	s_nop 1
	v_add_f32_dpp v246, v246, v246 quad_perm:[2,3,0,1] row_mask:0xf bank_mask:0xf
	s_nop 1
	v_add_f32_dpp v246, v246, v246 row_half_mirror row_mask:0xf bank_mask:0xf
	s_nop 1
	v_add_f32_dpp v246, v246, v246 row_mirror row_mask:0xf bank_mask:0xf
	s_nop 1
	v_add_f32_dpp v246, v246, v246 row_bcast:15 row_mask:0xa bank_mask:0xf
	s_nop 1
	v_add_f32_dpp v246, v246, v246 row_bcast:31 row_mask:0xc bank_mask:0xf
	s_nop 1
	v_readlane_b32 s0, v246, 63
	s_add_i32 s21, s20, 14336
	s_lshl_b32 s21, s21, 11
	s_add_u32 s10, s16, s21
	s_addc_u32 s11, s17, 0
	v_mov_b32_e32 v248, s0
	v_fmamk_f32 v248, v248, 0x3a800000, v143
	v_rsq_f32_e32 v248, v248
	s_nop 0
	v_pk_mul_f32 v[66:67], v[66:67], v[248:249] op_sel_hi:[1,0]
	v_pk_add_f32 v[98:99], v[98:99], 1.0 op_sel_hi:[1,0]
	v_pk_mul_f32 v[66:67], v[2:3], v[66:67]
	v_pk_fma_f32 v[66:67], v[98:99], v[66:67], v[82:83]
	v_pk_mul_f32 v[68:69], v[68:69], v[248:249] op_sel_hi:[1,0]
	v_pk_add_f32 v[100:101], v[100:101], 1.0 op_sel_hi:[1,0]
	v_pk_mul_f32 v[68:69], v[4:5], v[68:69]
	v_pk_fma_f32 v[68:69], v[100:101], v[68:69], v[84:85]
	v_cvt_pk_bf16_f32 v82, v66, v67
	v_cvt_pk_bf16_f32 v83, v68, v69
	global_store_dwordx2 v245, v[82:83], s[10:11]
	v_pk_mul_f32 v[70:71], v[70:71], v[248:249] op_sel_hi:[1,0]
	v_pk_add_f32 v[102:103], v[102:103], 1.0 op_sel_hi:[1,0]
	v_pk_mul_f32 v[70:71], v[6:7], v[70:71]
	v_pk_fma_f32 v[70:71], v[102:103], v[70:71], v[86:87]
	v_pk_mul_f32 v[72:73], v[72:73], v[248:249] op_sel_hi:[1,0]
	v_pk_add_f32 v[104:105], v[104:105], 1.0 op_sel_hi:[1,0]
	v_pk_mul_f32 v[72:73], v[8:9], v[72:73]
	v_pk_fma_f32 v[72:73], v[104:105], v[72:73], v[88:89]
	v_cvt_pk_bf16_f32 v86, v70, v71
	v_cvt_pk_bf16_f32 v87, v72, v73
	global_store_dwordx2 v245, v[86:87], s[10:11] offset:512
	v_pk_mul_f32 v[74:75], v[74:75], v[248:249] op_sel_hi:[1,0]
	v_pk_add_f32 v[106:107], v[106:107], 1.0 op_sel_hi:[1,0]
	v_pk_mul_f32 v[74:75], v[10:11], v[74:75]
	v_pk_fma_f32 v[74:75], v[106:107], v[74:75], v[90:91]
	v_pk_mul_f32 v[76:77], v[76:77], v[248:249] op_sel_hi:[1,0]
	v_pk_add_f32 v[108:109], v[108:109], 1.0 op_sel_hi:[1,0]
	v_pk_mul_f32 v[76:77], v[12:13], v[76:77]
	v_pk_fma_f32 v[76:77], v[108:109], v[76:77], v[92:93]
	v_cvt_pk_bf16_f32 v90, v74, v75
	v_cvt_pk_bf16_f32 v91, v76, v77
	global_store_dwordx2 v245, v[90:91], s[10:11] offset:1024
	v_pk_mul_f32 v[78:79], v[78:79], v[248:249] op_sel_hi:[1,0]
	v_pk_add_f32 v[118:119], v[118:119], 1.0 op_sel_hi:[1,0]
	v_pk_mul_f32 v[78:79], v[14:15], v[78:79]
	v_pk_fma_f32 v[78:79], v[118:119], v[78:79], v[94:95]
	v_pk_mul_f32 v[80:81], v[80:81], v[248:249] op_sel_hi:[1,0]
	v_pk_add_f32 v[120:121], v[120:121], 1.0 op_sel_hi:[1,0]
	v_pk_mul_f32 v[80:81], v[16:17], v[80:81]
	v_pk_fma_f32 v[80:81], v[120:121], v[80:81], v[96:97]
	v_cvt_pk_bf16_f32 v94, v78, v79
	v_cvt_pk_bf16_f32 v95, v80, v81
	global_store_dwordx2 v245, v[94:95], s[10:11] offset:1536
	s_waitcnt vmcnt(8)
; DI unsigned pk_bf16(float lo, float hi) { f32x2 v = {lo, hi}; bf16v2 b = __builtin_convertvector(v, bf16v2); return __builtin_bit_cast(unsigned, b); }
; DI float red64(float x) { for (int o = 32; o > 0; o >>= 1) x += __shfl_xor(x, o); return x; }
; DI void modnorm_rows(const Params& p, int l, int which  , bool from_inputs, bool skip_ctx, int w0, int wstride, int lane) {
;     ...
;   int i = w0;
;   if (i >= nrows) return;
;   f32x4 vn[4];
;   {
;     const int row = rowof(i); const float* src = xsrc_row(p, from_inputs, row / TB, row % TB);
; #pragma unroll
;     for (int q = 0; q < 4; ++q) vn[q] = *(const f32x4*)(src + q * 256 + lane * 4);
;   }
;   for (; i < nrows; i += wstride) {
;     const int row = rowof(i); const int b = row / TB, s = row % TB;
;     f32x4 v[4];
; #pragma unroll
;     for (int q = 0; q < 4; ++q) v[q] = vn[q];
;     if (i + wstride < nrows) {
;       const int rn = rowof(i + wstride); const float* src = xsrc_row(p, from_inputs, rn / TB, rn % TB);
; #pragma unroll
;       for (int q = 0; q < 4; ++q) vn[q] = *(const f32x4*)(src + q * 256 + lane * 4);
;     ...
;     for (int q = 0; q < 4; ++q) { sh[q] = *(const f32x4*)(mod + q * 256 + lane * 4); sc[q] = *(const f32x4*)(mod + 1024 + q * 256 + lane * 4); }
;     float ss = 0.f;
; #pragma unroll
;     for (int q = 0; q < 4; ++q) ss += v[q][0] * v[q][0] + v[q][1] * v[q][1] + v[q][2] * v[q][2] + v[q][3] * v[q][3];
;     ss = red64(ss);
;     const float rs = rsqrtf(ss * (1.f / 1024.f) + EPSF);
;     bf16_t* dst = p.HY + (size_t)row * DM;
; #pragma unroll
;     for (int q = 0; q < 4; ++q) {
;       float o[4];
; #pragma unroll
;       for (int j = 0; j < 4; ++j) o[j] = (v[q][j] * rs * gg[q][j]) * (1.f + sc[q][j]) + sh[q][j];
;       u32x2 w = {pk_bf16(o[0], o[1]), pk_bf16(o[2], o[3])};
;       *(u32x2*)(dst + q * 256 + lane * 4) = w;
;     }
;   }
	v_pk_mul_f32 v[246:247], v[122:123], v[122:123]
	v_pk_fma_f32 v[246:247], v[124:125], v[124:125], v[246:247]
	v_pk_fma_f32 v[246:247], v[126:127], v[126:127], v[246:247]
	v_pk_fma_f32 v[246:247], v[128:129], v[128:129], v[246:247]
	v_pk_fma_f32 v[246:247], v[130:131], v[130:131], v[246:247]
	v_pk_fma_f32 v[246:247], v[132:133], v[132:133], v[246:247]
	v_pk_fma_f32 v[246:247], v[134:135], v[134:135], v[246:247]
	v_pk_fma_f32 v[246:247], v[136:137], v[136:137], v[246:247]
	s_nop 0
	v_add_f32_e32 v246, v246, v247
	s_nop 1
	v_add_f32_dpp v246, v246, v246 quad_perm:[1,0,3,2] row_mask:0xf bank_mask:0xf
	s_nop 1
	v_add_f32_dpp v246, v246, v246 quad_perm:[2,3,0,1] row_mask:0xf bank_mask:0xf
	s_nop 1
	v_add_f32_dpp v246, v246, v246 row_half_mirror row_mask:0xf bank_mask:0xf
	s_nop 1
	v_add_f32_dpp v246, v246, v246 row_mirror row_mask:0xf bank_mask:0xf
	s_nop 1
	v_add_f32_dpp v246, v246, v246 row_bcast:15 row_mask:0xa bank_mask:0xf
	s_nop 1
	v_add_f32_dpp v246, v246, v246 row_bcast:31 row_mask:0xc bank_mask:0xf
	s_nop 1
	v_readlane_b32 s0, v246, 63
	s_add_i32 s21, s20, 16384
	s_lshl_b32 s21, s21, 11
	s_add_u32 s10, s16, s21
	s_addc_u32 s11, s17, 0
	v_mov_b32_e32 v248, s0
	v_fmamk_f32 v248, v248, 0x3a800000, v143
	v_rsq_f32_e32 v248, v248
	s_nop 0
	v_pk_mul_f32 v[122:123], v[122:123], v[248:249] op_sel_hi:[1,0]
	v_pk_add_f32 v[176:177], v[176:177], 1.0 op_sel_hi:[1,0]
	v_pk_mul_f32 v[122:123], v[2:3], v[122:123]
	v_pk_fma_f32 v[122:123], v[176:177], v[122:123], v[160:161]
	v_pk_mul_f32 v[124:125], v[124:125], v[248:249] op_sel_hi:[1,0]
	v_pk_add_f32 v[178:179], v[178:179], 1.0 op_sel_hi:[1,0]
	v_pk_mul_f32 v[124:125], v[4:5], v[124:125]
	v_pk_fma_f32 v[124:125], v[178:179], v[124:125], v[162:163]
	v_cvt_pk_bf16_f32 v160, v122, v123
	v_cvt_pk_bf16_f32 v161, v124, v125
	global_store_dwordx2 v245, v[160:161], s[10:11]
	v_pk_mul_f32 v[126:127], v[126:127], v[248:249] op_sel_hi:[1,0]
	v_pk_add_f32 v[180:181], v[180:181], 1.0 op_sel_hi:[1,0]
	v_pk_mul_f32 v[126:127], v[6:7], v[126:127]
	v_pk_fma_f32 v[126:127], v[180:181], v[126:127], v[164:165]
	v_pk_mul_f32 v[128:129], v[128:129], v[248:249] op_sel_hi:[1,0]
	v_pk_add_f32 v[182:183], v[182:183], 1.0 op_sel_hi:[1,0]
	v_pk_mul_f32 v[128:129], v[8:9], v[128:129]
	v_pk_fma_f32 v[128:129], v[182:183], v[128:129], v[166:167]
	v_cvt_pk_bf16_f32 v164, v126, v127
	v_cvt_pk_bf16_f32 v165, v128, v129
	global_store_dwordx2 v245, v[164:165], s[10:11] offset:512
	v_pk_mul_f32 v[130:131], v[130:131], v[248:249] op_sel_hi:[1,0]
	v_pk_add_f32 v[184:185], v[184:185], 1.0 op_sel_hi:[1,0]
	v_pk_mul_f32 v[130:131], v[10:11], v[130:131]
	v_pk_fma_f32 v[130:131], v[184:185], v[130:131], v[168:169]
	v_pk_mul_f32 v[132:133], v[132:133], v[248:249] op_sel_hi:[1,0]
	v_pk_add_f32 v[186:187], v[186:187], 1.0 op_sel_hi:[1,0]
	v_pk_mul_f32 v[132:133], v[12:13], v[132:133]
	v_pk_fma_f32 v[132:133], v[186:187], v[132:133], v[170:171]
	v_cvt_pk_bf16_f32 v168, v130, v131
	v_cvt_pk_bf16_f32 v169, v132, v133
	global_store_dwordx2 v245, v[168:169], s[10:11] offset:1024
	v_pk_mul_f32 v[134:135], v[134:135], v[248:249] op_sel_hi:[1,0]
	v_pk_add_f32 v[188:189], v[188:189], 1.0 op_sel_hi:[1,0]
	v_pk_mul_f32 v[134:135], v[14:15], v[134:135]
	v_pk_fma_f32 v[134:135], v[188:189], v[134:135], v[172:173]
	v_pk_mul_f32 v[136:137], v[136:137], v[248:249] op_sel_hi:[1,0]
	v_pk_add_f32 v[190:191], v[190:191], 1.0 op_sel_hi:[1,0]
	v_pk_mul_f32 v[136:137], v[16:17], v[136:137]
	v_pk_fma_f32 v[136:137], v[190:191], v[136:137], v[174:175]
	v_cvt_pk_bf16_f32 v172, v134, v135
	v_cvt_pk_bf16_f32 v173, v136, v137
	global_store_dwordx2 v245, v[172:173], s[10:11] offset:1536
	s_branch .Lnorm1_done
.Lnorm1_l1:
	s_mov_b32 s36, 0
	s_lshr_b32 s37, s20, 7
	s_and_b32 s37, s37, 15
	s_add_i32 s37, s37, 2
	s_lshr_b32 s37, s37, 1
	s_add_i32 s37, s37, 1
	s_cmp_ge_u32 s37, 9
	s_cselect_b32 s38, 9, 0
	s_sub_i32 s37, s37, s38
	s_add_i32 s6, s37, 0
	s_cmp_ge_u32 s6, 9
	s_cselect_b32 s38, 9, 0
	s_sub_i32 s6, s6, s38
	s_lshl_b32 s6, s6, 11
	s_add_i32 s6, s6, s20
	s_lshr_b32 s6, s6, 7
	s_lshl_b32 s6, s6, 2
	s_add_i32 s6, s6, 0x1e40
	v_mov_b32_e32 v110, s6
	global_load_dword v114, v110, s[70:71] sc1
	s_add_i32 s6, s37, 1
	s_cmp_ge_u32 s6, 9
	s_cselect_b32 s38, 9, 0
	s_sub_i32 s6, s6, s38
	s_lshl_b32 s6, s6, 11
	s_add_i32 s6, s6, s20
	s_lshr_b32 s6, s6, 7
	s_lshl_b32 s6, s6, 2
	s_add_i32 s6, s6, 0x1e40
	v_mov_b32_e32 v110, s6
	global_load_dword v116, v110, s[70:71] sc1
	s_add_i32 s6, s37, 2
	s_cmp_ge_u32 s6, 9
	s_cselect_b32 s38, 9, 0
	s_sub_i32 s6, s6, s38
	s_lshl_b32 s6, s6, 11
	s_add_i32 s6, s6, s20
	s_lshr_b32 s6, s6, 7
	s_lshl_b32 s6, s6, 2
	s_add_i32 s6, s6, 0x1e40
	v_mov_b32_e32 v110, s6
	global_load_dword v117, v110, s[70:71] sc1
	s_waitcnt vmcnt(2)
	v_readfirstlane_b32 s6, v114
	s_cmp_ge_u32 s6, 8
	s_cbranch_scc1 .Ldep_norm1d_ok0
	s_add_i32 s6, s37, 0
	s_cmp_ge_u32 s6, 9
	s_cselect_b32 s38, 9, 0
	s_sub_i32 s6, s6, s38
	s_lshl_b32 s6, s6, 11
	s_add_i32 s6, s6, s20
	s_lshr_b32 s6, s6, 7
	s_lshl_b32 s6, s6, 2
	s_add_i32 s6, s6, 0x1e40
	v_mov_b32_e32 v110, s6

; DI void modnorm_rows(const Params& p, int l, int which  , bool from_inputs, bool skip_ctx, int w0, int wstride, int lane) {
;     ...
;   int i = w0;
;   if (i >= nrows) return;
.Ldep_norm1d_ok0:
	s_waitcnt vmcnt(1)
	v_readfirstlane_b32 s6, v116
	s_cmp_ge_u32 s6, 8
	s_cbranch_scc1 .Ldep_norm1d_ok1
	s_add_i32 s6, s37, 1
	s_cmp_ge_u32 s6, 9
	s_cselect_b32 s38, 9, 0
	s_sub_i32 s6, s6, s38
	s_lshl_b32 s6, s6, 11
	s_add_i32 s6, s6, s20
	s_lshr_b32 s6, s6, 7
	s_lshl_b32 s6, s6, 2
	s_add_i32 s6, s6, 0x1e40
	v_mov_b32_e32 v110, s6

; DI void modnorm_rows(const Params& p, int l, int which  , bool from_inputs, bool skip_ctx, int w0, int wstride, int lane) {
;     ...
;   int i = w0;
;   if (i >= nrows) return;
.Ldep_norm1d_ok1:
	s_waitcnt vmcnt(0)
	v_readfirstlane_b32 s6, v117
	s_cmp_ge_u32 s6, 8
	s_cbranch_scc1 .Ldep_norm1d_ok2
	s_add_i32 s6, s37, 2
	s_cmp_ge_u32 s6, 9
	s_cselect_b32 s38, 9, 0
	s_sub_i32 s6, s6, s38
	s_lshl_b32 s6, s6, 11
	s_add_i32 s6, s6, s20
	s_lshr_b32 s6, s6, 7
	s_lshl_b32 s6, s6, 2
	s_add_i32 s6, s6, 0x1e40
	v_mov_b32_e32 v110, s6

; DI void modnorm_rows(const Params& p, int l, int which  , bool from_inputs, bool skip_ctx, int w0, int wstride, int lane) {
;     ...
;   int i = w0;
;   if (i >= nrows) return;
;   f32x4 vn[4];
;   {
;     const int row = rowof(i); const float* src = xsrc_row(p, from_inputs, row / TB, row % TB);
; #pragma unroll
;     for (int q = 0; q < 4; ++q) vn[q] = *(const f32x4*)(src + q * 256 + lane * 4);
;   }
;   for (; i < nrows; i += wstride) {
;     const int row = rowof(i); const int b = row / TB, s = row % TB;
;     f32x4 v[4];
; #pragma unroll
;     for (int q = 0; q < 4; ++q) v[q] = vn[q];
;     if (i + wstride < nrows) {
;       const int rn = rowof(i + wstride); const float* src = xsrc_row(p, from_inputs, rn / TB, rn % TB);
; #pragma unroll
;       for (int q = 0; q < 4; ++q) vn[q] = *(const f32x4*)(src + q * 256 + lane * 4);
.Ldep_norm1d_ok2:
	s_add_i32 s21, s37, 0
	s_cmp_ge_u32 s21, 9
	s_cselect_b32 s38, 9, 0
	s_sub_i32 s21, s21, s38
	s_lshl_b32 s21, s21, 11
	s_add_i32 s21, s21, s20
	s_mul_hi_u32 s7, s21, 0x38e38e39
	s_lshr_b32 s7, s7, 9
	s_mul_i32 s8, s7, 0x900
	s_sub_i32 s8, s21, s8
	s_lshl_b32 s9, s7, 11
	s_add_i32 s9, s9, s8
	s_add_i32 s9, s9, 0xffffff00
	s_lshl_b32 s10, s7, 8
	s_add_i32 s10, s10, s8
	s_cmpk_gt_i32 s8, 0xff
	s_cselect_b32 s9, s9, s10
	s_cselect_b32 s26, s12, s14
	s_cselect_b32 s27, s13, s15
	s_cselect_b32 s10, s7, 8
	s_lshl_b32 s9, s9, 12
	s_add_u32 s26, s26, s9
	s_addc_u32 s27, s27, 0
	s_add_i32 s10, s10, s82
	s_mul_i32 s10, s10, s24
	s_add_u32 s28, s58, s10
	s_addc_u32 s29, s59, 0
	s_add_u32 s28, s28, 0x0
	s_addc_u32 s29, s29, 0
	s_add_u32 s0, s28, 0x1000
	s_addc_u32 s1, s29, 0
	global_load_dwordx4 v[18:21], v244, s[26:27] sc0 sc1
	global_load_dwordx4 v[22:25], v244, s[26:27] offset:1024 sc0 sc1
	global_load_dwordx4 v[26:29], v244, s[26:27] offset:2048 sc0 sc1
	global_load_dwordx4 v[30:33], v244, s[26:27] offset:3072 sc0 sc1
	global_load_dwordx4 v[34:37], v244, s[28:29]
	global_load_dwordx4 v[38:41], v244, s[28:29] offset:1024
	global_load_dwordx4 v[42:45], v244, s[28:29] offset:2048
	global_load_dwordx4 v[46:49], v244, s[28:29] offset:3072
	global_load_dwordx4 v[50:53], v244, s[0:1]
	global_load_dwordx4 v[54:57], v244, s[0:1] offset:1024
	global_load_dwordx4 v[58:61], v244, s[0:1] offset:2048
	global_load_dwordx4 v[62:65], v244, s[0:1] offset:3072
	s_add_i32 s21, s37, 1
	s_cmp_ge_u32 s21, 9
	s_cselect_b32 s38, 9, 0
	s_sub_i32 s21, s21, s38
	s_lshl_b32 s21, s21, 11
	s_add_i32 s21, s21, s20
	s_mul_hi_u32 s7, s21, 0x38e38e39
	s_lshr_b32 s7, s7, 9
	s_mul_i32 s8, s7, 0x900
	s_sub_i32 s8, s21, s8
	s_lshl_b32 s9, s7, 11
	s_add_i32 s9, s9, s8
	s_add_i32 s9, s9, 0xffffff00
	s_lshl_b32 s10, s7, 8
	s_add_i32 s10, s10, s8
	s_cmpk_gt_i32 s8, 0xff
	s_cselect_b32 s9, s9, s10
	s_cselect_b32 s26, s12, s14
	s_cselect_b32 s27, s13, s15
	s_cselect_b32 s10, s7, 8
	s_lshl_b32 s9, s9, 12
	s_add_u32 s26, s26, s9
	s_addc_u32 s27, s27, 0
	s_add_i32 s10, s10, s82
	s_mul_i32 s10, s10, s24
	s_add_u32 s28, s58, s10
	s_addc_u32 s29, s59, 0
	s_add_u32 s28, s28, 0x0
	s_addc_u32 s29, s29, 0
	s_add_u32 s0, s28, 0x1000
	s_addc_u32 s1, s29, 0
	global_load_dwordx4 v[66:69], v244, s[26:27] sc0 sc1
	global_load_dwordx4 v[70:73], v244, s[26:27] offset:1024 sc0 sc1
	global_load_dwordx4 v[74:77], v244, s[26:27] offset:2048 sc0 sc1
	global_load_dwordx4 v[78:81], v244, s[26:27] offset:3072 sc0 sc1
	global_load_dwordx4 v[82:85], v244, s[28:29]
	global_load_dwordx4 v[86:89], v244, s[28:29] offset:1024
	global_load_dwordx4 v[90:93], v244, s[28:29] offset:2048
	global_load_dwordx4 v[94:97], v244, s[28:29] offset:3072
	global_load_dwordx4 v[98:101], v244, s[0:1]
	global_load_dwordx4 v[102:105], v244, s[0:1] offset:1024
	global_load_dwordx4 v[106:109], v244, s[0:1] offset:2048
	global_load_dwordx4 v[118:121], v244, s[0:1] offset:3072
	s_add_i32 s21, s37, 2
	s_cmp_ge_u32 s21, 9
	s_cselect_b32 s38, 9, 0
	s_sub_i32 s21, s21, s38
	s_lshl_b32 s21, s21, 11
	s_add_i32 s21, s21, s20
	s_mul_hi_u32 s7, s21, 0x38e38e39
	s_lshr_b32 s7, s7, 9
	s_mul_i32 s8, s7, 0x900
	s_sub_i32 s8, s21, s8
	s_lshl_b32 s9, s7, 11
	s_add_i32 s9, s9, s8
	s_add_i32 s9, s9, 0xffffff00
	s_lshl_b32 s10, s7, 8
	s_add_i32 s10, s10, s8
	s_cmpk_gt_i32 s8, 0xff
	s_cselect_b32 s9, s9, s10
	s_cselect_b32 s26, s12, s14
	s_cselect_b32 s27, s13, s15
	s_cselect_b32 s10, s7, 8
	s_lshl_b32 s9, s9, 12
	s_add_u32 s26, s26, s9
	s_addc_u32 s27, s27, 0
	s_add_i32 s10, s10, s82
	s_mul_i32 s10, s10, s24
	s_add_u32 s28, s58, s10
	s_addc_u32 s29, s59, 0
	s_add_u32 s28, s28, 0x0
	s_addc_u32 s29, s29, 0
	s_add_u32 s0, s28, 0x1000
	s_addc_u32 s1, s29, 0
	global_load_dwordx4 v[122:125], v244, s[26:27] sc0 sc1
	global_load_dwordx4 v[126:129], v244, s[26:27] offset:1024 sc0 sc1
	global_load_dwordx4 v[130:133], v244, s[26:27] offset:2048 sc0 sc1
	global_load_dwordx4 v[134:137], v244, s[26:27] offset:3072 sc0 sc1
	global_load_dwordx4 v[160:163], v244, s[28:29]
	global_load_dwordx4 v[164:167], v244, s[28:29] offset:1024
	global_load_dwordx4 v[168:171], v244, s[28:29] offset:2048
	global_load_dwordx4 v[172:175], v244, s[28:29] offset:3072
	global_load_dwordx4 v[176:179], v244, s[0:1]
	global_load_dwordx4 v[180:183], v244, s[0:1] offset:1024
	global_load_dwordx4 v[184:187], v244, s[0:1] offset:2048
	global_load_dwordx4 v[188:191], v244, s[0:1] offset:3072
	s_add_i32 s6, s37, 3
	s_cmp_ge_u32 s6, 9
	s_cselect_b32 s38, 9, 0
	s_sub_i32 s6, s6, s38
	s_lshl_b32 s6, s6, 11
	s_add_i32 s6, s6, s20
	s_lshr_b32 s6, s6, 7
	s_lshl_b32 s6, s6, 2
	s_add_i32 s6, s6, 0x1e40
	v_mov_b32_e32 v110, s6
	global_load_dword v114, v110, s[70:71] sc1
	s_waitcnt vmcnt(25)
; DI unsigned pk_bf16(float lo, float hi) { f32x2 v = {lo, hi}; bf16v2 b = __builtin_convertvector(v, bf16v2); return __builtin_bit_cast(unsigned, b); }
; DI float red64(float x) { for (int o = 32; o > 0; o >>= 1) x += __shfl_xor(x, o); return x; }
; DI void modnorm_rows(const Params& p, int l, int which  , bool from_inputs, bool skip_ctx, int w0, int wstride, int lane) {
;     ...
;     for (int q = 0; q < 4; ++q) { sh[q] = *(const f32x4*)(mod + q * 256 + lane * 4); sc[q] = *(const f32x4*)(mod + 1024 + q * 256 + lane * 4); }
;     float ss = 0.f;
; #pragma unroll
;     for (int q = 0; q < 4; ++q) ss += v[q][0] * v[q][0] + v[q][1] * v[q][1] + v[q][2] * v[q][2] + v[q][3] * v[q][3];
;     ss = red64(ss);
;     const float rs = rsqrtf(ss * (1.f / 1024.f) + EPSF);
;     bf16_t* dst = p.HY + (size_t)row * DM;
; #pragma unroll
;     for (int q = 0; q < 4; ++q) {
;       float o[4];
; #pragma unroll
;       for (int j = 0; j < 4; ++j) o[j] = (v[q][j] * rs * gg[q][j]) * (1.f + sc[q][j]) + sh[q][j];
;       u32x2 w = {pk_bf16(o[0], o[1]), pk_bf16(o[2], o[3])};
;       *(u32x2*)(dst + q * 256 + lane * 4) = w;
;     }
;   }
	v_pk_mul_f32 v[246:247], v[18:19], v[18:19]
	v_pk_fma_f32 v[246:247], v[20:21], v[20:21], v[246:247]
	v_pk_fma_f32 v[246:247], v[22:23], v[22:23], v[246:247]
	v_pk_fma_f32 v[246:247], v[24:25], v[24:25], v[246:247]
	v_pk_fma_f32 v[246:247], v[26:27], v[26:27], v[246:247]
	v_pk_fma_f32 v[246:247], v[28:29], v[28:29], v[246:247]
	v_pk_fma_f32 v[246:247], v[30:31], v[30:31], v[246:247]
	v_pk_fma_f32 v[246:247], v[32:33], v[32:33], v[246:247]
	s_nop 0
	v_add_f32_e32 v246, v246, v247
	s_nop 1
	v_add_f32_dpp v246, v246, v246 quad_perm:[1,0,3,2] row_mask:0xf bank_mask:0xf
	s_nop 1
	v_add_f32_dpp v246, v246, v246 quad_perm:[2,3,0,1] row_mask:0xf bank_mask:0xf
	s_nop 1
	v_add_f32_dpp v246, v246, v246 row_half_mirror row_mask:0xf bank_mask:0xf
	s_nop 1
	v_add_f32_dpp v246, v246, v246 row_mirror row_mask:0xf bank_mask:0xf
	s_nop 1
	v_add_f32_dpp v246, v246, v246 row_bcast:15 row_mask:0xa bank_mask:0xf
	s_nop 1
	v_add_f32_dpp v246, v246, v246 row_bcast:31 row_mask:0xc bank_mask:0xf
	s_nop 1
	v_readlane_b32 s0, v246, 63
	s_add_i32 s21, s37, 0
	s_cmp_ge_u32 s21, 9
	s_cselect_b32 s38, 9, 0
	s_sub_i32 s21, s21, s38
	s_lshl_b32 s21, s21, 11
	s_add_i32 s21, s21, s20
	s_lshl_b32 s21, s21, 11
	s_add_u32 s10, s16, s21
	s_addc_u32 s11, s17, 0
	v_mov_b32_e32 v248, s0
	v_fmamk_f32 v248, v248, 0x3a800000, v143
	v_rsq_f32_e32 v248, v248
	s_nop 0
	v_pk_mul_f32 v[18:19], v[18:19], v[248:249] op_sel_hi:[1,0]
	v_pk_add_f32 v[50:51], v[50:51], 1.0 op_sel_hi:[1,0]
	v_pk_mul_f32 v[18:19], v[2:3], v[18:19]
	v_pk_fma_f32 v[18:19], v[50:51], v[18:19], v[34:35]
	v_pk_mul_f32 v[20:21], v[20:21], v[248:249] op_sel_hi:[1,0]
	v_pk_add_f32 v[52:53], v[52:53], 1.0 op_sel_hi:[1,0]
	v_pk_mul_f32 v[20:21], v[4:5], v[20:21]
	v_pk_fma_f32 v[20:21], v[52:53], v[20:21], v[36:37]
	v_cvt_pk_bf16_f32 v34, v18, v19
	v_cvt_pk_bf16_f32 v35, v20, v21
	global_store_dwordx2 v245, v[34:35], s[10:11]
	v_pk_mul_f32 v[22:23], v[22:23], v[248:249] op_sel_hi:[1,0]
	v_pk_add_f32 v[54:55], v[54:55], 1.0 op_sel_hi:[1,0]
	v_pk_mul_f32 v[22:23], v[6:7], v[22:23]
	v_pk_fma_f32 v[22:23], v[54:55], v[22:23], v[38:39]
	v_pk_mul_f32 v[24:25], v[24:25], v[248:249] op_sel_hi:[1,0]
	v_pk_add_f32 v[56:57], v[56:57], 1.0 op_sel_hi:[1,0]
	v_pk_mul_f32 v[24:25], v[8:9], v[24:25]
	v_pk_fma_f32 v[24:25], v[56:57], v[24:25], v[40:41]
	v_cvt_pk_bf16_f32 v38, v22, v23
	v_cvt_pk_bf16_f32 v39, v24, v25
	global_store_dwordx2 v245, v[38:39], s[10:11] offset:512
	v_pk_mul_f32 v[26:27], v[26:27], v[248:249] op_sel_hi:[1,0]
	v_pk_add_f32 v[58:59], v[58:59], 1.0 op_sel_hi:[1,0]
	v_pk_mul_f32 v[26:27], v[10:11], v[26:27]
	v_pk_fma_f32 v[26:27], v[58:59], v[26:27], v[42:43]
	v_pk_mul_f32 v[28:29], v[28:29], v[248:249] op_sel_hi:[1,0]
	v_pk_add_f32 v[60:61], v[60:61], 1.0 op_sel_hi:[1,0]
	v_pk_mul_f32 v[28:29], v[12:13], v[28:29]
	v_pk_fma_f32 v[28:29], v[60:61], v[28:29], v[44:45]
	v_cvt_pk_bf16_f32 v42, v26, v27
	v_cvt_pk_bf16_f32 v43, v28, v29
	global_store_dwordx2 v245, v[42:43], s[10:11] offset:1024
	v_pk_mul_f32 v[30:31], v[30:31], v[248:249] op_sel_hi:[1,0]
	v_pk_add_f32 v[62:63], v[62:63], 1.0 op_sel_hi:[1,0]
	v_pk_mul_f32 v[30:31], v[14:15], v[30:31]
	v_pk_fma_f32 v[30:31], v[62:63], v[30:31], v[46:47]
	v_pk_mul_f32 v[32:33], v[32:33], v[248:249] op_sel_hi:[1,0]
	v_pk_add_f32 v[64:65], v[64:65], 1.0 op_sel_hi:[1,0]
	v_pk_mul_f32 v[32:33], v[16:17], v[32:33]
	v_pk_fma_f32 v[32:33], v[64:65], v[32:33], v[48:49]
	v_cvt_pk_bf16_f32 v46, v30, v31
	v_cvt_pk_bf16_f32 v47, v32, v33
	global_store_dwordx2 v245, v[46:47], s[10:11] offset:1536
	s_waitcnt vmcnt(4)
	v_readfirstlane_b32 s6, v114
	s_cmp_ge_u32 s6, 8
	s_cbranch_scc1 .Ldep_norm1d_ok3
	s_add_i32 s6, s37, 3
	s_cmp_ge_u32 s6, 9
	s_cselect_b32 s38, 9, 0
	s_sub_i32 s6, s6, s38
	s_lshl_b32 s6, s6, 11
	s_add_i32 s6, s6, s20
	s_lshr_b32 s6, s6, 7
	s_lshl_b32 s6, s6, 2
	s_add_i32 s6, s6, 0x1e40
	v_mov_b32_e32 v110, s6

; DI unsigned pk_bf16(float lo, float hi) { f32x2 v = {lo, hi}; bf16v2 b = __builtin_convertvector(v, bf16v2); return __builtin_bit_cast(unsigned, b); }
; DI float red64(float x) { for (int o = 32; o > 0; o >>= 1) x += __shfl_xor(x, o); return x; }
; DI void modnorm_rows(const Params& p, int l, int which  , bool from_inputs, bool skip_ctx, int w0, int wstride, int lane) {
;     ...
;     if (i + wstride < nrows) {
;       const int rn = rowof(i + wstride); const float* src = xsrc_row(p, from_inputs, rn / TB, rn % TB);
; #pragma unroll
;       for (int q = 0; q < 4; ++q) vn[q] = *(const f32x4*)(src + q * 256 + lane * 4);
;     }
;     const float* mod = p.MOD + (size_t)(l * 9 + (s < NCTX ? 8 : b)) * 6144 + (which ? 3 * 1024 : 0);
;     f32x4 sh[4], sc[4];
; #pragma unroll
;     for (int q = 0; q < 4; ++q) { sh[q] = *(const f32x4*)(mod + q * 256 + lane * 4); sc[q] = *(const f32x4*)(mod + 1024 + q * 256 + lane * 4); }
;     float ss = 0.f;
; #pragma unroll
;     for (int q = 0; q < 4; ++q) ss += v[q][0] * v[q][0] + v[q][1] * v[q][1] + v[q][2] * v[q][2] + v[q][3] * v[q][3];
;     ss = red64(ss);
;     const float rs = rsqrtf(ss * (1.f / 1024.f) + EPSF);
;     bf16_t* dst = p.HY + (size_t)row * DM;
; #pragma unroll
;     for (int q = 0; q < 4; ++q) {
;       float o[4];
; #pragma unroll
;       for (int j = 0; j < 4; ++j) o[j] = (v[q][j] * rs * gg[q][j]) * (1.f + sc[q][j]) + sh[q][j];
;       u32x2 w = {pk_bf16(o[0], o[1]), pk_bf16(o[2], o[3])};
;       *(u32x2*)(dst + q * 256 + lane * 4) = w;
;     }
;   }
.Ldep_norm1d_ok3:
	s_add_i32 s21, s37, 3
	s_cmp_ge_u32 s21, 9
	s_cselect_b32 s38, 9, 0
	s_sub_i32 s21, s21, s38
	s_lshl_b32 s21, s21, 11
	s_add_i32 s21, s21, s20
	s_mul_hi_u32 s7, s21, 0x38e38e39
	s_lshr_b32 s7, s7, 9
	s_mul_i32 s8, s7, 0x900
	s_sub_i32 s8, s21, s8
	s_lshl_b32 s9, s7, 11
	s_add_i32 s9, s9, s8
	s_add_i32 s9, s9, 0xffffff00
	s_lshl_b32 s10, s7, 8
	s_add_i32 s10, s10, s8
	s_cmpk_gt_i32 s8, 0xff
	s_cselect_b32 s9, s9, s10
	s_cselect_b32 s26, s12, s14
	s_cselect_b32 s27, s13, s15
	s_cselect_b32 s10, s7, 8
	s_lshl_b32 s9, s9, 12
	s_add_u32 s26, s26, s9
	s_addc_u32 s27, s27, 0
	s_add_i32 s10, s10, s82
	s_mul_i32 s10, s10, s24
	s_add_u32 s28, s58, s10
	s_addc_u32 s29, s59, 0
	s_add_u32 s28, s28, 0x0
	s_addc_u32 s29, s29, 0
	s_add_u32 s0, s28, 0x1000
	s_addc_u32 s1, s29, 0
	global_load_dwordx4 v[18:21], v244, s[26:27] sc0 sc1
	global_load_dwordx4 v[22:25], v244, s[26:27] offset:1024 sc0 sc1
	global_load_dwordx4 v[26:29], v244, s[26:27] offset:2048 sc0 sc1
	global_load_dwordx4 v[30:33], v244, s[26:27] offset:3072 sc0 sc1
	global_load_dwordx4 v[34:37], v244, s[28:29]
	global_load_dwordx4 v[38:41], v244, s[28:29] offset:1024
	global_load_dwordx4 v[42:45], v244, s[28:29] offset:2048
	global_load_dwordx4 v[46:49], v244, s[28:29] offset:3072
	global_load_dwordx4 v[50:53], v244, s[0:1]
	global_load_dwordx4 v[54:57], v244, s[0:1] offset:1024
	global_load_dwordx4 v[58:61], v244, s[0:1] offset:2048
	global_load_dwordx4 v[62:65], v244, s[0:1] offset:3072
	s_add_i32 s6, s37, 4
	s_cmp_ge_u32 s6, 9
	s_cselect_b32 s38, 9, 0
	s_sub_i32 s6, s6, s38
	s_lshl_b32 s6, s6, 11
	s_add_i32 s6, s6, s20
	s_lshr_b32 s6, s6, 7
	s_lshl_b32 s6, s6, 2
	s_add_i32 s6, s6, 0x1e40
	v_mov_b32_e32 v110, s6
	global_load_dword v114, v110, s[70:71] sc1
	s_waitcnt vmcnt(30)
	v_pk_mul_f32 v[246:247], v[66:67], v[66:67]
	v_pk_fma_f32 v[246:247], v[68:69], v[68:69], v[246:247]
	v_pk_fma_f32 v[246:247], v[70:71], v[70:71], v[246:247]
	v_pk_fma_f32 v[246:247], v[72:73], v[72:73], v[246:247]
	v_pk_fma_f32 v[246:247], v[74:75], v[74:75], v[246:247]
	v_pk_fma_f32 v[246:247], v[76:77], v[76:77], v[246:247]
	v_pk_fma_f32 v[246:247], v[78:79], v[78:79], v[246:247]
	v_pk_fma_f32 v[246:247], v[80:81], v[80:81], v[246:247]
	s_nop 0
	v_add_f32_e32 v246, v246, v247
	s_nop 1
	v_add_f32_dpp v246, v246, v246 quad_perm:[1,0,3,2] row_mask:0xf bank_mask:0xf
	s_nop 1
	v_add_f32_dpp v246, v246, v246 quad_perm:[2,3,0,1] row_mask:0xf bank_mask:0xf
	s_nop 1
	v_add_f32_dpp v246, v246, v246 row_half_mirror row_mask:0xf bank_mask:0xf
	s_nop 1
	v_add_f32_dpp v246, v246, v246 row_mirror row_mask:0xf bank_mask:0xf
	s_nop 1
	v_add_f32_dpp v246, v246, v246 row_bcast:15 row_mask:0xa bank_mask:0xf
	s_nop 1
	v_add_f32_dpp v246, v246, v246 row_bcast:31 row_mask:0xc bank_mask:0xf
	s_nop 1
	v_readlane_b32 s0, v246, 63
	s_add_i32 s21, s37, 1
	s_cmp_ge_u32 s21, 9
	s_cselect_b32 s38, 9, 0
	s_sub_i32 s21, s21, s38
	s_lshl_b32 s21, s21, 11
	s_add_i32 s21, s21, s20
	s_lshl_b32 s21, s21, 11
	s_add_u32 s10, s16, s21
	s_addc_u32 s11, s17, 0
	v_mov_b32_e32 v248, s0
	v_fmamk_f32 v248, v248, 0x3a800000, v143
	v_rsq_f32_e32 v248, v248
	s_nop 0
	v_pk_mul_f32 v[66:67], v[66:67], v[248:249] op_sel_hi:[1,0]
	v_pk_add_f32 v[98:99], v[98:99], 1.0 op_sel_hi:[1,0]
	v_pk_mul_f32 v[66:67], v[2:3], v[66:67]
	v_pk_fma_f32 v[66:67], v[98:99], v[66:67], v[82:83]
	v_pk_mul_f32 v[68:69], v[68:69], v[248:249] op_sel_hi:[1,0]
	v_pk_add_f32 v[100:101], v[100:101], 1.0 op_sel_hi:[1,0]
	v_pk_mul_f32 v[68:69], v[4:5], v[68:69]
	v_pk_fma_f32 v[68:69], v[100:101], v[68:69], v[84:85]
	v_cvt_pk_bf16_f32 v82, v66, v67
	v_cvt_pk_bf16_f32 v83, v68, v69
	global_store_dwordx2 v245, v[82:83], s[10:11]
	v_pk_mul_f32 v[70:71], v[70:71], v[248:249] op_sel_hi:[1,0]
	v_pk_add_f32 v[102:103], v[102:103], 1.0 op_sel_hi:[1,0]
	v_pk_mul_f32 v[70:71], v[6:7], v[70:71]
	v_pk_fma_f32 v[70:71], v[102:103], v[70:71], v[86:87]
	v_pk_mul_f32 v[72:73], v[72:73], v[248:249] op_sel_hi:[1,0]
	v_pk_add_f32 v[104:105], v[104:105], 1.0 op_sel_hi:[1,0]
	v_pk_mul_f32 v[72:73], v[8:9], v[72:73]
	v_pk_fma_f32 v[72:73], v[104:105], v[72:73], v[88:89]
	v_cvt_pk_bf16_f32 v86, v70, v71
	v_cvt_pk_bf16_f32 v87, v72, v73
	global_store_dwordx2 v245, v[86:87], s[10:11] offset:512
	v_pk_mul_f32 v[74:75], v[74:75], v[248:249] op_sel_hi:[1,0]
	v_pk_add_f32 v[106:107], v[106:107], 1.0 op_sel_hi:[1,0]
	v_pk_mul_f32 v[74:75], v[10:11], v[74:75]
	v_pk_fma_f32 v[74:75], v[106:107], v[74:75], v[90:91]
	v_pk_mul_f32 v[76:77], v[76:77], v[248:249] op_sel_hi:[1,0]
	v_pk_add_f32 v[108:109], v[108:109], 1.0 op_sel_hi:[1,0]
	v_pk_mul_f32 v[76:77], v[12:13], v[76:77]
	v_pk_fma_f32 v[76:77], v[108:109], v[76:77], v[92:93]
	v_cvt_pk_bf16_f32 v90, v74, v75
	v_cvt_pk_bf16_f32 v91, v76, v77
	global_store_dwordx2 v245, v[90:91], s[10:11] offset:1024
	v_pk_mul_f32 v[78:79], v[78:79], v[248:249] op_sel_hi:[1,0]
	v_pk_add_f32 v[118:119], v[118:119], 1.0 op_sel_hi:[1,0]
	v_pk_mul_f32 v[78:79], v[14:15], v[78:79]
	v_pk_fma_f32 v[78:79], v[118:119], v[78:79], v[94:95]
	v_pk_mul_f32 v[80:81], v[80:81], v[248:249] op_sel_hi:[1,0]
	v_pk_add_f32 v[120:121], v[120:121], 1.0 op_sel_hi:[1,0]
	v_pk_mul_f32 v[80:81], v[16:17], v[80:81]
	v_pk_fma_f32 v[80:81], v[120:121], v[80:81], v[96:97]
	v_cvt_pk_bf16_f32 v94, v78, v79
	v_cvt_pk_bf16_f32 v95, v80, v81
	global_store_dwordx2 v245, v[94:95], s[10:11] offset:1536
	s_waitcnt vmcnt(4)
	v_readfirstlane_b32 s6, v114
	s_cmp_ge_u32 s6, 8
	s_cbranch_scc1 .Ldep_norm1d_ok4
	s_add_i32 s6, s37, 4
	s_cmp_ge_u32 s6, 9
	s_cselect_b32 s38, 9, 0
	s_sub_i32 s6, s6, s38
	s_lshl_b32 s6, s6, 11
	s_add_i32 s6, s6, s20
	s_lshr_b32 s6, s6, 7
	s_lshl_b32 s6, s6, 2
	s_add_i32 s6, s6, 0x1e40
	v_mov_b32_e32 v110, s6

; DI unsigned pk_bf16(float lo, float hi) { f32x2 v = {lo, hi}; bf16v2 b = __builtin_convertvector(v, bf16v2); return __builtin_bit_cast(unsigned, b); }
; DI float red64(float x) { for (int o = 32; o > 0; o >>= 1) x += __shfl_xor(x, o); return x; }
; DI void modnorm_rows(const Params& p, int l, int which  , bool from_inputs, bool skip_ctx, int w0, int wstride, int lane) {
;     ...
;     if (i + wstride < nrows) {
;       const int rn = rowof(i + wstride); const float* src = xsrc_row(p, from_inputs, rn / TB, rn % TB);
; #pragma unroll
;       for (int q = 0; q < 4; ++q) vn[q] = *(const f32x4*)(src + q * 256 + lane * 4);
;     }
;     const float* mod = p.MOD + (size_t)(l * 9 + (s < NCTX ? 8 : b)) * 6144 + (which ? 3 * 1024 : 0);
;     f32x4 sh[4], sc[4];
; #pragma unroll
;     for (int q = 0; q < 4; ++q) { sh[q] = *(const f32x4*)(mod + q * 256 + lane * 4); sc[q] = *(const f32x4*)(mod + 1024 + q * 256 + lane * 4); }
;     float ss = 0.f;
; #pragma unroll
;     for (int q = 0; q < 4; ++q) ss += v[q][0] * v[q][0] + v[q][1] * v[q][1] + v[q][2] * v[q][2] + v[q][3] * v[q][3];
;     ss = red64(ss);
;     const float rs = rsqrtf(ss * (1.f / 1024.f) + EPSF);
;     bf16_t* dst = p.HY + (size_t)row * DM;
; #pragma unroll
;     for (int q = 0; q < 4; ++q) {
;       float o[4];
; #pragma unroll
;       for (int j = 0; j < 4; ++j) o[j] = (v[q][j] * rs * gg[q][j]) * (1.f + sc[q][j]) + sh[q][j];
;       u32x2 w = {pk_bf16(o[0], o[1]), pk_bf16(o[2], o[3])};
;       *(u32x2*)(dst + q * 256 + lane * 4) = w;
;     }
;   }
.Ldep_norm1d_ok4:
	s_add_i32 s21, s37, 4
	s_cmp_ge_u32 s21, 9
	s_cselect_b32 s38, 9, 0
	s_sub_i32 s21, s21, s38
	s_lshl_b32 s21, s21, 11
	s_add_i32 s21, s21, s20
	s_mul_hi_u32 s7, s21, 0x38e38e39
	s_lshr_b32 s7, s7, 9
	s_mul_i32 s8, s7, 0x900
	s_sub_i32 s8, s21, s8
	s_lshl_b32 s9, s7, 11
	s_add_i32 s9, s9, s8
	s_add_i32 s9, s9, 0xffffff00
	s_lshl_b32 s10, s7, 8
	s_add_i32 s10, s10, s8
	s_cmpk_gt_i32 s8, 0xff
	s_cselect_b32 s9, s9, s10
	s_cselect_b32 s26, s12, s14
	s_cselect_b32 s27, s13, s15
	s_cselect_b32 s10, s7, 8
	s_lshl_b32 s9, s9, 12
	s_add_u32 s26, s26, s9
	s_addc_u32 s27, s27, 0
	s_add_i32 s10, s10, s82
	s_mul_i32 s10, s10, s24
	s_add_u32 s28, s58, s10
	s_addc_u32 s29, s59, 0
	s_add_u32 s28, s28, 0x0
	s_addc_u32 s29, s29, 0
	s_add_u32 s0, s28, 0x1000
	s_addc_u32 s1, s29, 0
	global_load_dwordx4 v[66:69], v244, s[26:27] sc0 sc1
	global_load_dwordx4 v[70:73], v244, s[26:27] offset:1024 sc0 sc1
	global_load_dwordx4 v[74:77], v244, s[26:27] offset:2048 sc0 sc1
	global_load_dwordx4 v[78:81], v244, s[26:27] offset:3072 sc0 sc1
	global_load_dwordx4 v[82:85], v244, s[28:29]
	global_load_dwordx4 v[86:89], v244, s[28:29] offset:1024
	global_load_dwordx4 v[90:93], v244, s[28:29] offset:2048
	global_load_dwordx4 v[94:97], v244, s[28:29] offset:3072
	global_load_dwordx4 v[98:101], v244, s[0:1]
	global_load_dwordx4 v[102:105], v244, s[0:1] offset:1024
	global_load_dwordx4 v[106:109], v244, s[0:1] offset:2048
	global_load_dwordx4 v[118:121], v244, s[0:1] offset:3072
	s_add_i32 s6, s37, 5
	s_cmp_ge_u32 s6, 9
	s_cselect_b32 s38, 9, 0
	s_sub_i32 s6, s6, s38
	s_lshl_b32 s6, s6, 11
	s_add_i32 s6, s6, s20
	s_lshr_b32 s6, s6, 7
	s_lshl_b32 s6, s6, 2
	s_add_i32 s6, s6, 0x1e40
	v_mov_b32_e32 v110, s6
	global_load_dword v114, v110, s[70:71] sc1
	s_waitcnt vmcnt(35)
	v_pk_mul_f32 v[246:247], v[122:123], v[122:123]
	v_pk_fma_f32 v[246:247], v[124:125], v[124:125], v[246:247]
	v_pk_fma_f32 v[246:247], v[126:127], v[126:127], v[246:247]
	v_pk_fma_f32 v[246:247], v[128:129], v[128:129], v[246:247]
	v_pk_fma_f32 v[246:247], v[130:131], v[130:131], v[246:247]
	v_pk_fma_f32 v[246:247], v[132:133], v[132:133], v[246:247]
	v_pk_fma_f32 v[246:247], v[134:135], v[134:135], v[246:247]
	v_pk_fma_f32 v[246:247], v[136:137], v[136:137], v[246:247]
	s_nop 0
	v_add_f32_e32 v246, v246, v247
	s_nop 1
	v_add_f32_dpp v246, v246, v246 quad_perm:[1,0,3,2] row_mask:0xf bank_mask:0xf
	s_nop 1
	v_add_f32_dpp v246, v246, v246 quad_perm:[2,3,0,1] row_mask:0xf bank_mask:0xf
	s_nop 1
	v_add_f32_dpp v246, v246, v246 row_half_mirror row_mask:0xf bank_mask:0xf
	s_nop 1
	v_add_f32_dpp v246, v246, v246 row_mirror row_mask:0xf bank_mask:0xf
	s_nop 1
	v_add_f32_dpp v246, v246, v246 row_bcast:15 row_mask:0xa bank_mask:0xf
	s_nop 1
	v_add_f32_dpp v246, v246, v246 row_bcast:31 row_mask:0xc bank_mask:0xf
	s_nop 1
	v_readlane_b32 s0, v246, 63
	s_add_i32 s21, s37, 2
	s_cmp_ge_u32 s21, 9
	s_cselect_b32 s38, 9, 0
	s_sub_i32 s21, s21, s38
	s_lshl_b32 s21, s21, 11
	s_add_i32 s21, s21, s20
	s_lshl_b32 s21, s21, 11
	s_add_u32 s10, s16, s21
	s_addc_u32 s11, s17, 0
	v_mov_b32_e32 v248, s0
	v_fmamk_f32 v248, v248, 0x3a800000, v143
	v_rsq_f32_e32 v248, v248
	s_nop 0
	v_pk_mul_f32 v[122:123], v[122:123], v[248:249] op_sel_hi:[1,0]
	v_pk_add_f32 v[176:177], v[176:177], 1.0 op_sel_hi:[1,0]
	v_pk_mul_f32 v[122:123], v[2:3], v[122:123]
	v_pk_fma_f32 v[122:123], v[176:177], v[122:123], v[160:161]
	v_pk_mul_f32 v[124:125], v[124:125], v[248:249] op_sel_hi:[1,0]
	v_pk_add_f32 v[178:179], v[178:179], 1.0 op_sel_hi:[1,0]
	v_pk_mul_f32 v[124:125], v[4:5], v[124:125]
	v_pk_fma_f32 v[124:125], v[178:179], v[124:125], v[162:163]
	v_cvt_pk_bf16_f32 v160, v122, v123
	v_cvt_pk_bf16_f32 v161, v124, v125
	global_store_dwordx2 v245, v[160:161], s[10:11]
	v_pk_mul_f32 v[126:127], v[126:127], v[248:249] op_sel_hi:[1,0]
	v_pk_add_f32 v[180:181], v[180:181], 1.0 op_sel_hi:[1,0]
	v_pk_mul_f32 v[126:127], v[6:7], v[126:127]
	v_pk_fma_f32 v[126:127], v[180:181], v[126:127], v[164:165]
	v_pk_mul_f32 v[128:129], v[128:129], v[248:249] op_sel_hi:[1,0]
	v_pk_add_f32 v[182:183], v[182:183], 1.0 op_sel_hi:[1,0]
	v_pk_mul_f32 v[128:129], v[8:9], v[128:129]
	v_pk_fma_f32 v[128:129], v[182:183], v[128:129], v[166:167]
	v_cvt_pk_bf16_f32 v164, v126, v127
	v_cvt_pk_bf16_f32 v165, v128, v129
	global_store_dwordx2 v245, v[164:165], s[10:11] offset:512
	v_pk_mul_f32 v[130:131], v[130:131], v[248:249] op_sel_hi:[1,0]
	v_pk_add_f32 v[184:185], v[184:185], 1.0 op_sel_hi:[1,0]
	v_pk_mul_f32 v[130:131], v[10:11], v[130:131]
	v_pk_fma_f32 v[130:131], v[184:185], v[130:131], v[168:169]
	v_pk_mul_f32 v[132:133], v[132:133], v[248:249] op_sel_hi:[1,0]
	v_pk_add_f32 v[186:187], v[186:187], 1.0 op_sel_hi:[1,0]
	v_pk_mul_f32 v[132:133], v[12:13], v[132:133]
	v_pk_fma_f32 v[132:133], v[186:187], v[132:133], v[170:171]
	v_cvt_pk_bf16_f32 v168, v130, v131
	v_cvt_pk_bf16_f32 v169, v132, v133
	global_store_dwordx2 v245, v[168:169], s[10:11] offset:1024
	v_pk_mul_f32 v[134:135], v[134:135], v[248:249] op_sel_hi:[1,0]
	v_pk_add_f32 v[188:189], v[188:189], 1.0 op_sel_hi:[1,0]
	v_pk_mul_f32 v[134:135], v[14:15], v[134:135]
	v_pk_fma_f32 v[134:135], v[188:189], v[134:135], v[172:173]
	v_pk_mul_f32 v[136:137], v[136:137], v[248:249] op_sel_hi:[1,0]
	v_pk_add_f32 v[190:191], v[190:191], 1.0 op_sel_hi:[1,0]
	v_pk_mul_f32 v[136:137], v[16:17], v[136:137]
	v_pk_fma_f32 v[136:137], v[190:191], v[136:137], v[174:175]
	v_cvt_pk_bf16_f32 v172, v134, v135
	v_cvt_pk_bf16_f32 v173, v136, v137
	global_store_dwordx2 v245, v[172:173], s[10:11] offset:1536
	s_waitcnt vmcnt(4)
	v_readfirstlane_b32 s6, v114
	s_cmp_ge_u32 s6, 8
	s_cbranch_scc1 .Ldep_norm1d_ok5
	s_add_i32 s6, s37, 5
	s_cmp_ge_u32 s6, 9
	s_cselect_b32 s38, 9, 0
	s_sub_i32 s6, s6, s38
	s_lshl_b32 s6, s6, 11
	s_add_i32 s6, s6, s20
	s_lshr_b32 s6, s6, 7
	s_lshl_b32 s6, s6, 2
	s_add_i32 s6, s6, 0x1e40
	v_mov_b32_e32 v110, s6

; DI unsigned pk_bf16(float lo, float hi) { f32x2 v = {lo, hi}; bf16v2 b = __builtin_convertvector(v, bf16v2); return __builtin_bit_cast(unsigned, b); }
; DI float red64(float x) { for (int o = 32; o > 0; o >>= 1) x += __shfl_xor(x, o); return x; }
; DI void modnorm_rows(const Params& p, int l, int which  , bool from_inputs, bool skip_ctx, int w0, int wstride, int lane) {
;     ...
;     if (i + wstride < nrows) {
;       const int rn = rowof(i + wstride); const float* src = xsrc_row(p, from_inputs, rn / TB, rn % TB);
; #pragma unroll
;       for (int q = 0; q < 4; ++q) vn[q] = *(const f32x4*)(src + q * 256 + lane * 4);
;     }
;     const float* mod = p.MOD + (size_t)(l * 9 + (s < NCTX ? 8 : b)) * 6144 + (which ? 3 * 1024 : 0);
;     f32x4 sh[4], sc[4];
; #pragma unroll
;     for (int q = 0; q < 4; ++q) { sh[q] = *(const f32x4*)(mod + q * 256 + lane * 4); sc[q] = *(const f32x4*)(mod + 1024 + q * 256 + lane * 4); }
;     float ss = 0.f;
; #pragma unroll
;     for (int q = 0; q < 4; ++q) ss += v[q][0] * v[q][0] + v[q][1] * v[q][1] + v[q][2] * v[q][2] + v[q][3] * v[q][3];
;     ss = red64(ss);
;     const float rs = rsqrtf(ss * (1.f / 1024.f) + EPSF);
;     bf16_t* dst = p.HY + (size_t)row * DM;
; #pragma unroll
;     for (int q = 0; q < 4; ++q) {
;       float o[4];
; #pragma unroll
;       for (int j = 0; j < 4; ++j) o[j] = (v[q][j] * rs * gg[q][j]) * (1.f + sc[q][j]) + sh[q][j];
;       u32x2 w = {pk_bf16(o[0], o[1]), pk_bf16(o[2], o[3])};
;       *(u32x2*)(dst + q * 256 + lane * 4) = w;
;     }
;   }
.Ldep_norm1d_ok5:
	s_add_i32 s21, s37, 5
	s_cmp_ge_u32 s21, 9
	s_cselect_b32 s38, 9, 0
	s_sub_i32 s21, s21, s38
	s_lshl_b32 s21, s21, 11
	s_add_i32 s21, s21, s20
	s_mul_hi_u32 s7, s21, 0x38e38e39
	s_lshr_b32 s7, s7, 9
	s_mul_i32 s8, s7, 0x900
	s_sub_i32 s8, s21, s8
	s_lshl_b32 s9, s7, 11
	s_add_i32 s9, s9, s8
	s_add_i32 s9, s9, 0xffffff00
	s_lshl_b32 s10, s7, 8
	s_add_i32 s10, s10, s8
	s_cmpk_gt_i32 s8, 0xff
	s_cselect_b32 s9, s9, s10
	s_cselect_b32 s26, s12, s14
	s_cselect_b32 s27, s13, s15
	s_cselect_b32 s10, s7, 8
	s_lshl_b32 s9, s9, 12
	s_add_u32 s26, s26, s9
	s_addc_u32 s27, s27, 0
	s_add_i32 s10, s10, s82
	s_mul_i32 s10, s10, s24
	s_add_u32 s28, s58, s10
	s_addc_u32 s29, s59, 0
	s_add_u32 s28, s28, 0x0
	s_addc_u32 s29, s29, 0
	s_add_u32 s0, s28, 0x1000
	s_addc_u32 s1, s29, 0
	global_load_dwordx4 v[122:125], v244, s[26:27] sc0 sc1
	global_load_dwordx4 v[126:129], v244, s[26:27] offset:1024 sc0 sc1
	global_load_dwordx4 v[130:133], v244, s[26:27] offset:2048 sc0 sc1
	global_load_dwordx4 v[134:137], v244, s[26:27] offset:3072 sc0 sc1
	global_load_dwordx4 v[160:163], v244, s[28:29]
	global_load_dwordx4 v[164:167], v244, s[28:29] offset:1024
	global_load_dwordx4 v[168:171], v244, s[28:29] offset:2048
	global_load_dwordx4 v[172:175], v244, s[28:29] offset:3072
	global_load_dwordx4 v[176:179], v244, s[0:1]
	global_load_dwordx4 v[180:183], v244, s[0:1] offset:1024
	global_load_dwordx4 v[184:187], v244, s[0:1] offset:2048
	global_load_dwordx4 v[188:191], v244, s[0:1] offset:3072
	s_add_i32 s6, s37, 6
	s_cmp_ge_u32 s6, 9
	s_cselect_b32 s38, 9, 0
	s_sub_i32 s6, s6, s38
	s_lshl_b32 s6, s6, 11
	s_add_i32 s6, s6, s20
	s_lshr_b32 s6, s6, 7
	s_lshl_b32 s6, s6, 2
	s_add_i32 s6, s6, 0x1e40
	v_mov_b32_e32 v110, s6
	global_load_dword v114, v110, s[70:71] sc1
	s_waitcnt vmcnt(35)
	v_pk_mul_f32 v[246:247], v[18:19], v[18:19]
	v_pk_fma_f32 v[246:247], v[20:21], v[20:21], v[246:247]
	v_pk_fma_f32 v[246:247], v[22:23], v[22:23], v[246:247]
	v_pk_fma_f32 v[246:247], v[24:25], v[24:25], v[246:247]
	v_pk_fma_f32 v[246:247], v[26:27], v[26:27], v[246:247]
	v_pk_fma_f32 v[246:247], v[28:29], v[28:29], v[246:247]
	v_pk_fma_f32 v[246:247], v[30:31], v[30:31], v[246:247]
	v_pk_fma_f32 v[246:247], v[32:33], v[32:33], v[246:247]
	s_nop 0
	v_add_f32_e32 v246, v246, v247
	s_nop 1
	v_add_f32_dpp v246, v246, v246 quad_perm:[1,0,3,2] row_mask:0xf bank_mask:0xf
	s_nop 1
	v_add_f32_dpp v246, v246, v246 quad_perm:[2,3,0,1] row_mask:0xf bank_mask:0xf
	s_nop 1
	v_add_f32_dpp v246, v246, v246 row_half_mirror row_mask:0xf bank_mask:0xf
	s_nop 1
	v_add_f32_dpp v246, v246, v246 row_mirror row_mask:0xf bank_mask:0xf
	s_nop 1
	v_add_f32_dpp v246, v246, v246 row_bcast:15 row_mask:0xa bank_mask:0xf
	s_nop 1
	v_add_f32_dpp v246, v246, v246 row_bcast:31 row_mask:0xc bank_mask:0xf
	s_nop 1
	v_readlane_b32 s0, v246, 63
	s_add_i32 s21, s37, 3
	s_cmp_ge_u32 s21, 9
	s_cselect_b32 s38, 9, 0
	s_sub_i32 s21, s21, s38
	s_lshl_b32 s21, s21, 11
	s_add_i32 s21, s21, s20
	s_lshl_b32 s21, s21, 11
	s_add_u32 s10, s16, s21
	s_addc_u32 s11, s17, 0
	v_mov_b32_e32 v248, s0
	v_fmamk_f32 v248, v248, 0x3a800000, v143
	v_rsq_f32_e32 v248, v248
	s_nop 0
	v_pk_mul_f32 v[18:19], v[18:19], v[248:249] op_sel_hi:[1,0]
	v_pk_add_f32 v[50:51], v[50:51], 1.0 op_sel_hi:[1,0]
	v_pk_mul_f32 v[18:19], v[2:3], v[18:19]
	v_pk_fma_f32 v[18:19], v[50:51], v[18:19], v[34:35]
	v_pk_mul_f32 v[20:21], v[20:21], v[248:249] op_sel_hi:[1,0]
	v_pk_add_f32 v[52:53], v[52:53], 1.0 op_sel_hi:[1,0]
	v_pk_mul_f32 v[20:21], v[4:5], v[20:21]
	v_pk_fma_f32 v[20:21], v[52:53], v[20:21], v[36:37]
	v_cvt_pk_bf16_f32 v34, v18, v19
	v_cvt_pk_bf16_f32 v35, v20, v21
	global_store_dwordx2 v245, v[34:35], s[10:11]
	v_pk_mul_f32 v[22:23], v[22:23], v[248:249] op_sel_hi:[1,0]
	v_pk_add_f32 v[54:55], v[54:55], 1.0 op_sel_hi:[1,0]
	v_pk_mul_f32 v[22:23], v[6:7], v[22:23]
	v_pk_fma_f32 v[22:23], v[54:55], v[22:23], v[38:39]
	v_pk_mul_f32 v[24:25], v[24:25], v[248:249] op_sel_hi:[1,0]
	v_pk_add_f32 v[56:57], v[56:57], 1.0 op_sel_hi:[1,0]
	v_pk_mul_f32 v[24:25], v[8:9], v[24:25]
	v_pk_fma_f32 v[24:25], v[56:57], v[24:25], v[40:41]
	v_cvt_pk_bf16_f32 v38, v22, v23
	v_cvt_pk_bf16_f32 v39, v24, v25
	global_store_dwordx2 v245, v[38:39], s[10:11] offset:512
	v_pk_mul_f32 v[26:27], v[26:27], v[248:249] op_sel_hi:[1,0]
	v_pk_add_f32 v[58:59], v[58:59], 1.0 op_sel_hi:[1,0]
	v_pk_mul_f32 v[26:27], v[10:11], v[26:27]
	v_pk_fma_f32 v[26:27], v[58:59], v[26:27], v[42:43]
	v_pk_mul_f32 v[28:29], v[28:29], v[248:249] op_sel_hi:[1,0]
	v_pk_add_f32 v[60:61], v[60:61], 1.0 op_sel_hi:[1,0]
	v_pk_mul_f32 v[28:29], v[12:13], v[28:29]
	v_pk_fma_f32 v[28:29], v[60:61], v[28:29], v[44:45]
	v_cvt_pk_bf16_f32 v42, v26, v27
	v_cvt_pk_bf16_f32 v43, v28, v29
	global_store_dwordx2 v245, v[42:43], s[10:11] offset:1024
	v_pk_mul_f32 v[30:31], v[30:31], v[248:249] op_sel_hi:[1,0]
	v_pk_add_f32 v[62:63], v[62:63], 1.0 op_sel_hi:[1,0]
	v_pk_mul_f32 v[30:31], v[14:15], v[30:31]
	v_pk_fma_f32 v[30:31], v[62:63], v[30:31], v[46:47]
	v_pk_mul_f32 v[32:33], v[32:33], v[248:249] op_sel_hi:[1,0]
	v_pk_add_f32 v[64:65], v[64:65], 1.0 op_sel_hi:[1,0]
	v_pk_mul_f32 v[32:33], v[16:17], v[32:33]
	v_pk_fma_f32 v[32:33], v[64:65], v[32:33], v[48:49]
	v_cvt_pk_bf16_f32 v46, v30, v31
	v_cvt_pk_bf16_f32 v47, v32, v33
	global_store_dwordx2 v245, v[46:47], s[10:11] offset:1536
	s_waitcnt vmcnt(4)
	v_readfirstlane_b32 s6, v114
	s_cmp_ge_u32 s6, 8
	s_cbranch_scc1 .Ldep_norm1d_ok6
	s_add_i32 s6, s37, 6
	s_cmp_ge_u32 s6, 9
	s_cselect_b32 s38, 9, 0
	s_sub_i32 s6, s6, s38
	s_lshl_b32 s6, s6, 11
	s_add_i32 s6, s6, s20
	s_lshr_b32 s6, s6, 7
	s_lshl_b32 s6, s6, 2
	s_add_i32 s6, s6, 0x1e40
	v_mov_b32_e32 v110, s6

; DI unsigned pk_bf16(float lo, float hi) { f32x2 v = {lo, hi}; bf16v2 b = __builtin_convertvector(v, bf16v2); return __builtin_bit_cast(unsigned, b); }
; DI float red64(float x) { for (int o = 32; o > 0; o >>= 1) x += __shfl_xor(x, o); return x; }
; DI void modnorm_rows(const Params& p, int l, int which  , bool from_inputs, bool skip_ctx, int w0, int wstride, int lane) {
;     ...
;     if (i + wstride < nrows) {
;       const int rn = rowof(i + wstride); const float* src = xsrc_row(p, from_inputs, rn / TB, rn % TB);
; #pragma unroll
;       for (int q = 0; q < 4; ++q) vn[q] = *(const f32x4*)(src + q * 256 + lane * 4);
;     }
;     const float* mod = p.MOD + (size_t)(l * 9 + (s < NCTX ? 8 : b)) * 6144 + (which ? 3 * 1024 : 0);
;     f32x4 sh[4], sc[4];
; #pragma unroll
;     for (int q = 0; q < 4; ++q) { sh[q] = *(const f32x4*)(mod + q * 256 + lane * 4); sc[q] = *(const f32x4*)(mod + 1024 + q * 256 + lane * 4); }
;     float ss = 0.f;
; #pragma unroll
;     for (int q = 0; q < 4; ++q) ss += v[q][0] * v[q][0] + v[q][1] * v[q][1] + v[q][2] * v[q][2] + v[q][3] * v[q][3];
;     ss = red64(ss);
;     const float rs = rsqrtf(ss * (1.f / 1024.f) + EPSF);
;     bf16_t* dst = p.HY + (size_t)row * DM;
; #pragma unroll
;     for (int q = 0; q < 4; ++q) {
;       float o[4];
; #pragma unroll
;       for (int j = 0; j < 4; ++j) o[j] = (v[q][j] * rs * gg[q][j]) * (1.f + sc[q][j]) + sh[q][j];
;       u32x2 w = {pk_bf16(o[0], o[1]), pk_bf16(o[2], o[3])};
;       *(u32x2*)(dst + q * 256 + lane * 4) = w;
;     }
;   }
.Ldep_norm1d_ok6:
	s_add_i32 s21, s37, 6
	s_cmp_ge_u32 s21, 9
	s_cselect_b32 s38, 9, 0
	s_sub_i32 s21, s21, s38
	s_lshl_b32 s21, s21, 11
	s_add_i32 s21, s21, s20
	s_mul_hi_u32 s7, s21, 0x38e38e39
	s_lshr_b32 s7, s7, 9
	s_mul_i32 s8, s7, 0x900
	s_sub_i32 s8, s21, s8
	s_lshl_b32 s9, s7, 11
	s_add_i32 s9, s9, s8
	s_add_i32 s9, s9, 0xffffff00
	s_lshl_b32 s10, s7, 8
	s_add_i32 s10, s10, s8
	s_cmpk_gt_i32 s8, 0xff
	s_cselect_b32 s9, s9, s10
	s_cselect_b32 s26, s12, s14
	s_cselect_b32 s27, s13, s15
	s_cselect_b32 s10, s7, 8
	s_lshl_b32 s9, s9, 12
	s_add_u32 s26, s26, s9
	s_addc_u32 s27, s27, 0
	s_add_i32 s10, s10, s82
	s_mul_i32 s10, s10, s24
	s_add_u32 s28, s58, s10
	s_addc_u32 s29, s59, 0
	s_add_u32 s28, s28, 0x0
	s_addc_u32 s29, s29, 0
	s_add_u32 s0, s28, 0x1000
	s_addc_u32 s1, s29, 0
	global_load_dwordx4 v[18:21], v244, s[26:27] sc0 sc1
	global_load_dwordx4 v[22:25], v244, s[26:27] offset:1024 sc0 sc1
	global_load_dwordx4 v[26:29], v244, s[26:27] offset:2048 sc0 sc1
	global_load_dwordx4 v[30:33], v244, s[26:27] offset:3072 sc0 sc1
	global_load_dwordx4 v[34:37], v244, s[28:29]
	global_load_dwordx4 v[38:41], v244, s[28:29] offset:1024
	global_load_dwordx4 v[42:45], v244, s[28:29] offset:2048
	global_load_dwordx4 v[46:49], v244, s[28:29] offset:3072
	global_load_dwordx4 v[50:53], v244, s[0:1]
	global_load_dwordx4 v[54:57], v244, s[0:1] offset:1024
	global_load_dwordx4 v[58:61], v244, s[0:1] offset:2048
	global_load_dwordx4 v[62:65], v244, s[0:1] offset:3072
	s_add_i32 s6, s37, 7
	s_cmp_ge_u32 s6, 9
	s_cselect_b32 s38, 9, 0
	s_sub_i32 s6, s6, s38
	s_lshl_b32 s6, s6, 11
	s_add_i32 s6, s6, s20
	s_lshr_b32 s6, s6, 7
	s_lshl_b32 s6, s6, 2
	s_add_i32 s6, s6, 0x1e40
	v_mov_b32_e32 v110, s6
	global_load_dword v114, v110, s[70:71] sc1
	s_waitcnt vmcnt(35)
	v_pk_mul_f32 v[246:247], v[66:67], v[66:67]
	v_pk_fma_f32 v[246:247], v[68:69], v[68:69], v[246:247]
	v_pk_fma_f32 v[246:247], v[70:71], v[70:71], v[246:247]
	v_pk_fma_f32 v[246:247], v[72:73], v[72:73], v[246:247]
	v_pk_fma_f32 v[246:247], v[74:75], v[74:75], v[246:247]
	v_pk_fma_f32 v[246:247], v[76:77], v[76:77], v[246:247]
	v_pk_fma_f32 v[246:247], v[78:79], v[78:79], v[246:247]
	v_pk_fma_f32 v[246:247], v[80:81], v[80:81], v[246:247]
	s_nop 0
	v_add_f32_e32 v246, v246, v247
	s_nop 1
	v_add_f32_dpp v246, v246, v246 quad_perm:[1,0,3,2] row_mask:0xf bank_mask:0xf
	s_nop 1
	v_add_f32_dpp v246, v246, v246 quad_perm:[2,3,0,1] row_mask:0xf bank_mask:0xf
	s_nop 1
	v_add_f32_dpp v246, v246, v246 row_half_mirror row_mask:0xf bank_mask:0xf
	s_nop 1
	v_add_f32_dpp v246, v246, v246 row_mirror row_mask:0xf bank_mask:0xf
	s_nop 1
	v_add_f32_dpp v246, v246, v246 row_bcast:15 row_mask:0xa bank_mask:0xf
	s_nop 1
	v_add_f32_dpp v246, v246, v246 row_bcast:31 row_mask:0xc bank_mask:0xf
	s_nop 1
	v_readlane_b32 s0, v246, 63
	s_add_i32 s21, s37, 4
	s_cmp_ge_u32 s21, 9
	s_cselect_b32 s38, 9, 0
	s_sub_i32 s21, s21, s38
	s_lshl_b32 s21, s21, 11
	s_add_i32 s21, s21, s20
	s_lshl_b32 s21, s21, 11
	s_add_u32 s10, s16, s21
	s_addc_u32 s11, s17, 0
	v_mov_b32_e32 v248, s0
	v_fmamk_f32 v248, v248, 0x3a800000, v143
	v_rsq_f32_e32 v248, v248
	s_nop 0
	v_pk_mul_f32 v[66:67], v[66:67], v[248:249] op_sel_hi:[1,0]
	v_pk_add_f32 v[98:99], v[98:99], 1.0 op_sel_hi:[1,0]
	v_pk_mul_f32 v[66:67], v[2:3], v[66:67]
	v_pk_fma_f32 v[66:67], v[98:99], v[66:67], v[82:83]
	v_pk_mul_f32 v[68:69], v[68:69], v[248:249] op_sel_hi:[1,0]
	v_pk_add_f32 v[100:101], v[100:101], 1.0 op_sel_hi:[1,0]
	v_pk_mul_f32 v[68:69], v[4:5], v[68:69]
	v_pk_fma_f32 v[68:69], v[100:101], v[68:69], v[84:85]
	v_cvt_pk_bf16_f32 v82, v66, v67
	v_cvt_pk_bf16_f32 v83, v68, v69
	global_store_dwordx2 v245, v[82:83], s[10:11]
	v_pk_mul_f32 v[70:71], v[70:71], v[248:249] op_sel_hi:[1,0]
	v_pk_add_f32 v[102:103], v[102:103], 1.0 op_sel_hi:[1,0]
	v_pk_mul_f32 v[70:71], v[6:7], v[70:71]
	v_pk_fma_f32 v[70:71], v[102:103], v[70:71], v[86:87]
	v_pk_mul_f32 v[72:73], v[72:73], v[248:249] op_sel_hi:[1,0]
	v_pk_add_f32 v[104:105], v[104:105], 1.0 op_sel_hi:[1,0]
	v_pk_mul_f32 v[72:73], v[8:9], v[72:73]
	v_pk_fma_f32 v[72:73], v[104:105], v[72:73], v[88:89]
	v_cvt_pk_bf16_f32 v86, v70, v71
	v_cvt_pk_bf16_f32 v87, v72, v73
	global_store_dwordx2 v245, v[86:87], s[10:11] offset:512
	v_pk_mul_f32 v[74:75], v[74:75], v[248:249] op_sel_hi:[1,0]
	v_pk_add_f32 v[106:107], v[106:107], 1.0 op_sel_hi:[1,0]
	v_pk_mul_f32 v[74:75], v[10:11], v[74:75]
	v_pk_fma_f32 v[74:75], v[106:107], v[74:75], v[90:91]
	v_pk_mul_f32 v[76:77], v[76:77], v[248:249] op_sel_hi:[1,0]
	v_pk_add_f32 v[108:109], v[108:109], 1.0 op_sel_hi:[1,0]
	v_pk_mul_f32 v[76:77], v[12:13], v[76:77]
	v_pk_fma_f32 v[76:77], v[108:109], v[76:77], v[92:93]
	v_cvt_pk_bf16_f32 v90, v74, v75
	v_cvt_pk_bf16_f32 v91, v76, v77
	global_store_dwordx2 v245, v[90:91], s[10:11] offset:1024
	v_pk_mul_f32 v[78:79], v[78:79], v[248:249] op_sel_hi:[1,0]
	v_pk_add_f32 v[118:119], v[118:119], 1.0 op_sel_hi:[1,0]
	v_pk_mul_f32 v[78:79], v[14:15], v[78:79]
	v_pk_fma_f32 v[78:79], v[118:119], v[78:79], v[94:95]
	v_pk_mul_f32 v[80:81], v[80:81], v[248:249] op_sel_hi:[1,0]
	v_pk_add_f32 v[120:121], v[120:121], 1.0 op_sel_hi:[1,0]
	v_pk_mul_f32 v[80:81], v[16:17], v[80:81]
	v_pk_fma_f32 v[80:81], v[120:121], v[80:81], v[96:97]
	v_cvt_pk_bf16_f32 v94, v78, v79
	v_cvt_pk_bf16_f32 v95, v80, v81
	global_store_dwordx2 v245, v[94:95], s[10:11] offset:1536
	s_waitcnt vmcnt(4)
	v_readfirstlane_b32 s6, v114
	s_cmp_ge_u32 s6, 8
	s_cbranch_scc1 .Ldep_norm1d_ok7
	s_add_i32 s6, s37, 7
	s_cmp_ge_u32 s6, 9
	s_cselect_b32 s38, 9, 0
	s_sub_i32 s6, s6, s38
	s_lshl_b32 s6, s6, 11
	s_add_i32 s6, s6, s20
	s_lshr_b32 s6, s6, 7
	s_lshl_b32 s6, s6, 2
	s_add_i32 s6, s6, 0x1e40
	v_mov_b32_e32 v110, s6

; DI unsigned pk_bf16(float lo, float hi) { f32x2 v = {lo, hi}; bf16v2 b = __builtin_convertvector(v, bf16v2); return __builtin_bit_cast(unsigned, b); }
; DI float red64(float x) { for (int o = 32; o > 0; o >>= 1) x += __shfl_xor(x, o); return x; }
; DI void modnorm_rows(const Params& p, int l, int which  , bool from_inputs, bool skip_ctx, int w0, int wstride, int lane) {
;     ...
;     if (i + wstride < nrows) {
;       const int rn = rowof(i + wstride); const float* src = xsrc_row(p, from_inputs, rn / TB, rn % TB);
; #pragma unroll
;       for (int q = 0; q < 4; ++q) vn[q] = *(const f32x4*)(src + q * 256 + lane * 4);
;     }
;     const float* mod = p.MOD + (size_t)(l * 9 + (s < NCTX ? 8 : b)) * 6144 + (which ? 3 * 1024 : 0);
;     f32x4 sh[4], sc[4];
; #pragma unroll
;     for (int q = 0; q < 4; ++q) { sh[q] = *(const f32x4*)(mod + q * 256 + lane * 4); sc[q] = *(const f32x4*)(mod + 1024 + q * 256 + lane * 4); }
;     float ss = 0.f;
; #pragma unroll
;     for (int q = 0; q < 4; ++q) ss += v[q][0] * v[q][0] + v[q][1] * v[q][1] + v[q][2] * v[q][2] + v[q][3] * v[q][3];
;     ss = red64(ss);
;     const float rs = rsqrtf(ss * (1.f / 1024.f) + EPSF);
;     bf16_t* dst = p.HY + (size_t)row * DM;
; #pragma unroll
;     for (int q = 0; q < 4; ++q) {
;       float o[4];
; #pragma unroll
;       for (int j = 0; j < 4; ++j) o[j] = (v[q][j] * rs * gg[q][j]) * (1.f + sc[q][j]) + sh[q][j];
;       u32x2 w = {pk_bf16(o[0], o[1]), pk_bf16(o[2], o[3])};
;       *(u32x2*)(dst + q * 256 + lane * 4) = w;
;     }
;   }
.Ldep_norm1d_ok7:
	s_add_i32 s21, s37, 7
	s_cmp_ge_u32 s21, 9
	s_cselect_b32 s38, 9, 0
	s_sub_i32 s21, s21, s38
	s_lshl_b32 s21, s21, 11
	s_add_i32 s21, s21, s20
	s_mul_hi_u32 s7, s21, 0x38e38e39
	s_lshr_b32 s7, s7, 9
	s_mul_i32 s8, s7, 0x900
	s_sub_i32 s8, s21, s8
	s_lshl_b32 s9, s7, 11
	s_add_i32 s9, s9, s8
	s_add_i32 s9, s9, 0xffffff00
	s_lshl_b32 s10, s7, 8
	s_add_i32 s10, s10, s8
	s_cmpk_gt_i32 s8, 0xff
	s_cselect_b32 s9, s9, s10
	s_cselect_b32 s26, s12, s14
	s_cselect_b32 s27, s13, s15
	s_cselect_b32 s10, s7, 8
	s_lshl_b32 s9, s9, 12
	s_add_u32 s26, s26, s9
	s_addc_u32 s27, s27, 0
	s_add_i32 s10, s10, s82
	s_mul_i32 s10, s10, s24
	s_add_u32 s28, s58, s10
	s_addc_u32 s29, s59, 0
	s_add_u32 s28, s28, 0x0
	s_addc_u32 s29, s29, 0
	s_add_u32 s0, s28, 0x1000
	s_addc_u32 s1, s29, 0
	global_load_dwordx4 v[66:69], v244, s[26:27] sc0 sc1
	global_load_dwordx4 v[70:73], v244, s[26:27] offset:1024 sc0 sc1
	global_load_dwordx4 v[74:77], v244, s[26:27] offset:2048 sc0 sc1
	global_load_dwordx4 v[78:81], v244, s[26:27] offset:3072 sc0 sc1
	global_load_dwordx4 v[82:85], v244, s[28:29]
	global_load_dwordx4 v[86:89], v244, s[28:29] offset:1024
	global_load_dwordx4 v[90:93], v244, s[28:29] offset:2048
	global_load_dwordx4 v[94:97], v244, s[28:29] offset:3072
	global_load_dwordx4 v[98:101], v244, s[0:1]
	global_load_dwordx4 v[102:105], v244, s[0:1] offset:1024
	global_load_dwordx4 v[106:109], v244, s[0:1] offset:2048
	global_load_dwordx4 v[118:121], v244, s[0:1] offset:3072
	s_add_i32 s6, s37, 8
	s_cmp_ge_u32 s6, 9
	s_cselect_b32 s38, 9, 0
	s_sub_i32 s6, s6, s38
	s_lshl_b32 s6, s6, 11
	s_add_i32 s6, s6, s20
	s_lshr_b32 s6, s6, 7
	s_lshl_b32 s6, s6, 2
	s_add_i32 s6, s6, 0x1e40
	v_mov_b32_e32 v110, s6
	global_load_dword v114, v110, s[70:71] sc1
	s_waitcnt vmcnt(35)
	v_pk_mul_f32 v[246:247], v[122:123], v[122:123]
	v_pk_fma_f32 v[246:247], v[124:125], v[124:125], v[246:247]
	v_pk_fma_f32 v[246:247], v[126:127], v[126:127], v[246:247]
	v_pk_fma_f32 v[246:247], v[128:129], v[128:129], v[246:247]
	v_pk_fma_f32 v[246:247], v[130:131], v[130:131], v[246:247]
	v_pk_fma_f32 v[246:247], v[132:133], v[132:133], v[246:247]
	v_pk_fma_f32 v[246:247], v[134:135], v[134:135], v[246:247]
	v_pk_fma_f32 v[246:247], v[136:137], v[136:137], v[246:247]
	s_nop 0
	v_add_f32_e32 v246, v246, v247
	s_nop 1
	v_add_f32_dpp v246, v246, v246 quad_perm:[1,0,3,2] row_mask:0xf bank_mask:0xf
	s_nop 1
	v_add_f32_dpp v246, v246, v246 quad_perm:[2,3,0,1] row_mask:0xf bank_mask:0xf
	s_nop 1
	v_add_f32_dpp v246, v246, v246 row_half_mirror row_mask:0xf bank_mask:0xf
	s_nop 1
	v_add_f32_dpp v246, v246, v246 row_mirror row_mask:0xf bank_mask:0xf
	s_nop 1
	v_add_f32_dpp v246, v246, v246 row_bcast:15 row_mask:0xa bank_mask:0xf
	s_nop 1
	v_add_f32_dpp v246, v246, v246 row_bcast:31 row_mask:0xc bank_mask:0xf
	s_nop 1
	v_readlane_b32 s0, v246, 63
	s_add_i32 s21, s37, 5
	s_cmp_ge_u32 s21, 9
	s_cselect_b32 s38, 9, 0
	s_sub_i32 s21, s21, s38
	s_lshl_b32 s21, s21, 11
	s_add_i32 s21, s21, s20
	s_lshl_b32 s21, s21, 11
	s_add_u32 s10, s16, s21
	s_addc_u32 s11, s17, 0
	v_mov_b32_e32 v248, s0
	v_fmamk_f32 v248, v248, 0x3a800000, v143
	v_rsq_f32_e32 v248, v248
	s_nop 0
	v_pk_mul_f32 v[122:123], v[122:123], v[248:249] op_sel_hi:[1,0]
	v_pk_add_f32 v[176:177], v[176:177], 1.0 op_sel_hi:[1,0]
	v_pk_mul_f32 v[122:123], v[2:3], v[122:123]
	v_pk_fma_f32 v[122:123], v[176:177], v[122:123], v[160:161]
	v_pk_mul_f32 v[124:125], v[124:125], v[248:249] op_sel_hi:[1,0]
	v_pk_add_f32 v[178:179], v[178:179], 1.0 op_sel_hi:[1,0]
	v_pk_mul_f32 v[124:125], v[4:5], v[124:125]
	v_pk_fma_f32 v[124:125], v[178:179], v[124:125], v[162:163]
	v_cvt_pk_bf16_f32 v160, v122, v123
	v_cvt_pk_bf16_f32 v161, v124, v125
	global_store_dwordx2 v245, v[160:161], s[10:11]
	v_pk_mul_f32 v[126:127], v[126:127], v[248:249] op_sel_hi:[1,0]
	v_pk_add_f32 v[180:181], v[180:181], 1.0 op_sel_hi:[1,0]
	v_pk_mul_f32 v[126:127], v[6:7], v[126:127]
	v_pk_fma_f32 v[126:127], v[180:181], v[126:127], v[164:165]
	v_pk_mul_f32 v[128:129], v[128:129], v[248:249] op_sel_hi:[1,0]
	v_pk_add_f32 v[182:183], v[182:183], 1.0 op_sel_hi:[1,0]
	v_pk_mul_f32 v[128:129], v[8:9], v[128:129]
	v_pk_fma_f32 v[128:129], v[182:183], v[128:129], v[166:167]
	v_cvt_pk_bf16_f32 v164, v126, v127
	v_cvt_pk_bf16_f32 v165, v128, v129
	global_store_dwordx2 v245, v[164:165], s[10:11] offset:512
	v_pk_mul_f32 v[130:131], v[130:131], v[248:249] op_sel_hi:[1,0]
	v_pk_add_f32 v[184:185], v[184:185], 1.0 op_sel_hi:[1,0]
	v_pk_mul_f32 v[130:131], v[10:11], v[130:131]
	v_pk_fma_f32 v[130:131], v[184:185], v[130:131], v[168:169]
	v_pk_mul_f32 v[132:133], v[132:133], v[248:249] op_sel_hi:[1,0]
	v_pk_add_f32 v[186:187], v[186:187], 1.0 op_sel_hi:[1,0]
	v_pk_mul_f32 v[132:133], v[12:13], v[132:133]
	v_pk_fma_f32 v[132:133], v[186:187], v[132:133], v[170:171]
	v_cvt_pk_bf16_f32 v168, v130, v131
	v_cvt_pk_bf16_f32 v169, v132, v133
	global_store_dwordx2 v245, v[168:169], s[10:11] offset:1024
	v_pk_mul_f32 v[134:135], v[134:135], v[248:249] op_sel_hi:[1,0]
	v_pk_add_f32 v[188:189], v[188:189], 1.0 op_sel_hi:[1,0]
	v_pk_mul_f32 v[134:135], v[14:15], v[134:135]
	v_pk_fma_f32 v[134:135], v[188:189], v[134:135], v[172:173]
	v_pk_mul_f32 v[136:137], v[136:137], v[248:249] op_sel_hi:[1,0]
	v_pk_add_f32 v[190:191], v[190:191], 1.0 op_sel_hi:[1,0]
	v_pk_mul_f32 v[136:137], v[16:17], v[136:137]
	v_pk_fma_f32 v[136:137], v[190:191], v[136:137], v[174:175]
	v_cvt_pk_bf16_f32 v172, v134, v135
	v_cvt_pk_bf16_f32 v173, v136, v137
	global_store_dwordx2 v245, v[172:173], s[10:11] offset:1536
	s_waitcnt vmcnt(4)
	v_readfirstlane_b32 s6, v114
	s_cmp_ge_u32 s6, 8
	s_cbranch_scc1 .Ldep_norm1d_ok8
	s_add_i32 s6, s37, 8
	s_cmp_ge_u32 s6, 9
	s_cselect_b32 s38, 9, 0
	s_sub_i32 s6, s6, s38
	s_lshl_b32 s6, s6, 11
	s_add_i32 s6, s6, s20
	s_lshr_b32 s6, s6, 7
	s_lshl_b32 s6, s6, 2
	s_add_i32 s6, s6, 0x1e40
	v_mov_b32_e32 v110, s6

; DI unsigned pk_bf16(float lo, float hi) { f32x2 v = {lo, hi}; bf16v2 b = __builtin_convertvector(v, bf16v2); return __builtin_bit_cast(unsigned, b); }
; DI float red64(float x) { for (int o = 32; o > 0; o >>= 1) x += __shfl_xor(x, o); return x; }
; DI void modnorm_rows(const Params& p, int l, int which  , bool from_inputs, bool skip_ctx, int w0, int wstride, int lane) {
;     ...
;   for (; i < nrows; i += wstride) {
;     const int row = rowof(i); const int b = row / TB, s = row % TB;
;     f32x4 v[4];
; #pragma unroll
;     for (int q = 0; q < 4; ++q) v[q] = vn[q];
;     if (i + wstride < nrows) {
;       const int rn = rowof(i + wstride); const float* src = xsrc_row(p, from_inputs, rn / TB, rn % TB);
; #pragma unroll
;       for (int q = 0; q < 4; ++q) vn[q] = *(const f32x4*)(src + q * 256 + lane * 4);
;     }
;     const float* mod = p.MOD + (size_t)(l * 9 + (s < NCTX ? 8 : b)) * 6144 + (which ? 3 * 1024 : 0);
;     f32x4 sh[4], sc[4];
; #pragma unroll
;     for (int q = 0; q < 4; ++q) { sh[q] = *(const f32x4*)(mod + q * 256 + lane * 4); sc[q] = *(const f32x4*)(mod + 1024 + q * 256 + lane * 4); }
;     float ss = 0.f;
; #pragma unroll
;     for (int q = 0; q < 4; ++q) ss += v[q][0] * v[q][0] + v[q][1] * v[q][1] + v[q][2] * v[q][2] + v[q][3] * v[q][3];
;     ss = red64(ss);
;     const float rs = rsqrtf(ss * (1.f / 1024.f) + EPSF);
;     bf16_t* dst = p.HY + (size_t)row * DM;
; #pragma unroll
;     for (int q = 0; q < 4; ++q) {
;       float o[4];
; #pragma unroll
;       for (int j = 0; j < 4; ++j) o[j] = (v[q][j] * rs * gg[q][j]) * (1.f + sc[q][j]) + sh[q][j];
;       u32x2 w = {pk_bf16(o[0], o[1]), pk_bf16(o[2], o[3])};
;       *(u32x2*)(dst + q * 256 + lane * 4) = w;
;     }
.Ldep_norm1d_ok8:
	s_add_i32 s21, s37, 8
	s_cmp_ge_u32 s21, 9
	s_cselect_b32 s38, 9, 0
	s_sub_i32 s21, s21, s38
	s_lshl_b32 s21, s21, 11
	s_add_i32 s21, s21, s20
	s_mul_hi_u32 s7, s21, 0x38e38e39
	s_lshr_b32 s7, s7, 9
	s_mul_i32 s8, s7, 0x900
	s_sub_i32 s8, s21, s8
	s_lshl_b32 s9, s7, 11
	s_add_i32 s9, s9, s8
	s_add_i32 s9, s9, 0xffffff00
	s_lshl_b32 s10, s7, 8
	s_add_i32 s10, s10, s8
	s_cmpk_gt_i32 s8, 0xff
	s_cselect_b32 s9, s9, s10
	s_cselect_b32 s26, s12, s14
	s_cselect_b32 s27, s13, s15
	s_cselect_b32 s10, s7, 8
	s_lshl_b32 s9, s9, 12
	s_add_u32 s26, s26, s9
	s_addc_u32 s27, s27, 0
	s_add_i32 s10, s10, s82
	s_mul_i32 s10, s10, s24
	s_add_u32 s28, s58, s10
	s_addc_u32 s29, s59, 0
	s_add_u32 s28, s28, 0x0
	s_addc_u32 s29, s29, 0
	s_add_u32 s0, s28, 0x1000
	s_addc_u32 s1, s29, 0
	global_load_dwordx4 v[122:125], v244, s[26:27] sc0 sc1
	global_load_dwordx4 v[126:129], v244, s[26:27] offset:1024 sc0 sc1
	global_load_dwordx4 v[130:133], v244, s[26:27] offset:2048 sc0 sc1
	global_load_dwordx4 v[134:137], v244, s[26:27] offset:3072 sc0 sc1
	global_load_dwordx4 v[160:163], v244, s[28:29]
	global_load_dwordx4 v[164:167], v244, s[28:29] offset:1024
	global_load_dwordx4 v[168:171], v244, s[28:29] offset:2048
	global_load_dwordx4 v[172:175], v244, s[28:29] offset:3072
	global_load_dwordx4 v[176:179], v244, s[0:1]
	global_load_dwordx4 v[180:183], v244, s[0:1] offset:1024
	global_load_dwordx4 v[184:187], v244, s[0:1] offset:2048
	global_load_dwordx4 v[188:191], v244, s[0:1] offset:3072
	s_waitcnt vmcnt(34)
	v_pk_mul_f32 v[246:247], v[18:19], v[18:19]
	v_pk_fma_f32 v[246:247], v[20:21], v[20:21], v[246:247]
	v_pk_fma_f32 v[246:247], v[22:23], v[22:23], v[246:247]
	v_pk_fma_f32 v[246:247], v[24:25], v[24:25], v[246:247]
	v_pk_fma_f32 v[246:247], v[26:27], v[26:27], v[246:247]
	v_pk_fma_f32 v[246:247], v[28:29], v[28:29], v[246:247]
	v_pk_fma_f32 v[246:247], v[30:31], v[30:31], v[246:247]
	v_pk_fma_f32 v[246:247], v[32:33], v[32:33], v[246:247]
	s_nop 0
	v_add_f32_e32 v246, v246, v247
	s_nop 1
	v_add_f32_dpp v246, v246, v246 quad_perm:[1,0,3,2] row_mask:0xf bank_mask:0xf
	s_nop 1
	v_add_f32_dpp v246, v246, v246 quad_perm:[2,3,0,1] row_mask:0xf bank_mask:0xf
	s_nop 1
	v_add_f32_dpp v246, v246, v246 row_half_mirror row_mask:0xf bank_mask:0xf
	s_nop 1
	v_add_f32_dpp v246, v246, v246 row_mirror row_mask:0xf bank_mask:0xf
	s_nop 1
	v_add_f32_dpp v246, v246, v246 row_bcast:15 row_mask:0xa bank_mask:0xf
	s_nop 1
	v_add_f32_dpp v246, v246, v246 row_bcast:31 row_mask:0xc bank_mask:0xf
	s_nop 1
	v_readlane_b32 s0, v246, 63
	s_add_i32 s21, s37, 6
	s_cmp_ge_u32 s21, 9
	s_cselect_b32 s38, 9, 0
	s_sub_i32 s21, s21, s38
	s_lshl_b32 s21, s21, 11
	s_add_i32 s21, s21, s20
	s_lshl_b32 s21, s21, 11
	s_add_u32 s10, s16, s21
	s_addc_u32 s11, s17, 0
	v_mov_b32_e32 v248, s0
	v_fmamk_f32 v248, v248, 0x3a800000, v143
	v_rsq_f32_e32 v248, v248
	s_nop 0
	v_pk_mul_f32 v[18:19], v[18:19], v[248:249] op_sel_hi:[1,0]
	v_pk_add_f32 v[50:51], v[50:51], 1.0 op_sel_hi:[1,0]
	v_pk_mul_f32 v[18:19], v[2:3], v[18:19]
	v_pk_fma_f32 v[18:19], v[50:51], v[18:19], v[34:35]
	v_pk_mul_f32 v[20:21], v[20:21], v[248:249] op_sel_hi:[1,0]
	v_pk_add_f32 v[52:53], v[52:53], 1.0 op_sel_hi:[1,0]
	v_pk_mul_f32 v[20:21], v[4:5], v[20:21]
	v_pk_fma_f32 v[20:21], v[52:53], v[20:21], v[36:37]
	v_cvt_pk_bf16_f32 v34, v18, v19
	v_cvt_pk_bf16_f32 v35, v20, v21
	global_store_dwordx2 v245, v[34:35], s[10:11]
	v_pk_mul_f32 v[22:23], v[22:23], v[248:249] op_sel_hi:[1,0]
	v_pk_add_f32 v[54:55], v[54:55], 1.0 op_sel_hi:[1,0]
	v_pk_mul_f32 v[22:23], v[6:7], v[22:23]
	v_pk_fma_f32 v[22:23], v[54:55], v[22:23], v[38:39]
	v_pk_mul_f32 v[24:25], v[24:25], v[248:249] op_sel_hi:[1,0]
	v_pk_add_f32 v[56:57], v[56:57], 1.0 op_sel_hi:[1,0]
	v_pk_mul_f32 v[24:25], v[8:9], v[24:25]
	v_pk_fma_f32 v[24:25], v[56:57], v[24:25], v[40:41]
	v_cvt_pk_bf16_f32 v38, v22, v23
	v_cvt_pk_bf16_f32 v39, v24, v25
	global_store_dwordx2 v245, v[38:39], s[10:11] offset:512
	v_pk_mul_f32 v[26:27], v[26:27], v[248:249] op_sel_hi:[1,0]
	v_pk_add_f32 v[58:59], v[58:59], 1.0 op_sel_hi:[1,0]
	v_pk_mul_f32 v[26:27], v[10:11], v[26:27]
	v_pk_fma_f32 v[26:27], v[58:59], v[26:27], v[42:43]
	v_pk_mul_f32 v[28:29], v[28:29], v[248:249] op_sel_hi:[1,0]
	v_pk_add_f32 v[60:61], v[60:61], 1.0 op_sel_hi:[1,0]
	v_pk_mul_f32 v[28:29], v[12:13], v[28:29]
	v_pk_fma_f32 v[28:29], v[60:61], v[28:29], v[44:45]
	v_cvt_pk_bf16_f32 v42, v26, v27
	v_cvt_pk_bf16_f32 v43, v28, v29
	global_store_dwordx2 v245, v[42:43], s[10:11] offset:1024
	v_pk_mul_f32 v[30:31], v[30:31], v[248:249] op_sel_hi:[1,0]
	v_pk_add_f32 v[62:63], v[62:63], 1.0 op_sel_hi:[1,0]
	v_pk_mul_f32 v[30:31], v[14:15], v[30:31]
	v_pk_fma_f32 v[30:31], v[62:63], v[30:31], v[46:47]
	v_pk_mul_f32 v[32:33], v[32:33], v[248:249] op_sel_hi:[1,0]
	v_pk_add_f32 v[64:65], v[64:65], 1.0 op_sel_hi:[1,0]
	v_pk_mul_f32 v[32:33], v[16:17], v[32:33]
	v_pk_fma_f32 v[32:33], v[64:65], v[32:33], v[48:49]
	v_cvt_pk_bf16_f32 v46, v30, v31
	v_cvt_pk_bf16_f32 v47, v32, v33
	global_store_dwordx2 v245, v[46:47], s[10:11] offset:1536
	s_waitcnt vmcnt(21)
; DI unsigned pk_bf16(float lo, float hi) { f32x2 v = {lo, hi}; bf16v2 b = __builtin_convertvector(v, bf16v2); return __builtin_bit_cast(unsigned, b); }
; DI float red64(float x) { for (int o = 32; o > 0; o >>= 1) x += __shfl_xor(x, o); return x; }
; DI void modnorm_rows(const Params& p, int l, int which  , bool from_inputs, bool skip_ctx, int w0, int wstride, int lane) {
;     ...
;     float ss = 0.f;
; #pragma unroll
;     for (int q = 0; q < 4; ++q) ss += v[q][0] * v[q][0] + v[q][1] * v[q][1] + v[q][2] * v[q][2] + v[q][3] * v[q][3];
;     ss = red64(ss);
;     const float rs = rsqrtf(ss * (1.f / 1024.f) + EPSF);
;     bf16_t* dst = p.HY + (size_t)row * DM;
; #pragma unroll
;     for (int q = 0; q < 4; ++q) {
;       float o[4];
; #pragma unroll
;       for (int j = 0; j < 4; ++j) o[j] = (v[q][j] * rs * gg[q][j]) * (1.f + sc[q][j]) + sh[q][j];
;       u32x2 w = {pk_bf16(o[0], o[1]), pk_bf16(o[2], o[3])};
;       *(u32x2*)(dst + q * 256 + lane * 4) = w;
;     }
	v_pk_mul_f32 v[246:247], v[66:67], v[66:67]
	v_pk_fma_f32 v[246:247], v[68:69], v[68:69], v[246:247]
	v_pk_fma_f32 v[246:247], v[70:71], v[70:71], v[246:247]
	v_pk_fma_f32 v[246:247], v[72:73], v[72:73], v[246:247]
	v_pk_fma_f32 v[246:247], v[74:75], v[74:75], v[246:247]
	v_pk_fma_f32 v[246:247], v[76:77], v[76:77], v[246:247]
	v_pk_fma_f32 v[246:247], v[78:79], v[78:79], v[246:247]
	v_pk_fma_f32 v[246:247], v[80:81], v[80:81], v[246:247]
	s_nop 0
	v_add_f32_e32 v246, v246, v247
	s_nop 1
	v_add_f32_dpp v246, v246, v246 quad_perm:[1,0,3,2] row_mask:0xf bank_mask:0xf
	s_nop 1
	v_add_f32_dpp v246, v246, v246 quad_perm:[2,3,0,1] row_mask:0xf bank_mask:0xf
	s_nop 1
	v_add_f32_dpp v246, v246, v246 row_half_mirror row_mask:0xf bank_mask:0xf
	s_nop 1
	v_add_f32_dpp v246, v246, v246 row_mirror row_mask:0xf bank_mask:0xf
	s_nop 1
	v_add_f32_dpp v246, v246, v246 row_bcast:15 row_mask:0xa bank_mask:0xf
	s_nop 1
	v_add_f32_dpp v246, v246, v246 row_bcast:31 row_mask:0xc bank_mask:0xf
	s_nop 1
	v_readlane_b32 s0, v246, 63
	s_add_i32 s21, s37, 7
	s_cmp_ge_u32 s21, 9
	s_cselect_b32 s38, 9, 0
	s_sub_i32 s21, s21, s38
	s_lshl_b32 s21, s21, 11
	s_add_i32 s21, s21, s20
	s_lshl_b32 s21, s21, 11
	s_add_u32 s10, s16, s21
	s_addc_u32 s11, s17, 0
	v_mov_b32_e32 v248, s0
	v_fmamk_f32 v248, v248, 0x3a800000, v143
	v_rsq_f32_e32 v248, v248
	s_nop 0
	v_pk_mul_f32 v[66:67], v[66:67], v[248:249] op_sel_hi:[1,0]
	v_pk_add_f32 v[98:99], v[98:99], 1.0 op_sel_hi:[1,0]
	v_pk_mul_f32 v[66:67], v[2:3], v[66:67]
	v_pk_fma_f32 v[66:67], v[98:99], v[66:67], v[82:83]
	v_pk_mul_f32 v[68:69], v[68:69], v[248:249] op_sel_hi:[1,0]
	v_pk_add_f32 v[100:101], v[100:101], 1.0 op_sel_hi:[1,0]
	v_pk_mul_f32 v[68:69], v[4:5], v[68:69]
	v_pk_fma_f32 v[68:69], v[100:101], v[68:69], v[84:85]
	v_cvt_pk_bf16_f32 v82, v66, v67
	v_cvt_pk_bf16_f32 v83, v68, v69
	global_store_dwordx2 v245, v[82:83], s[10:11]
	v_pk_mul_f32 v[70:71], v[70:71], v[248:249] op_sel_hi:[1,0]
	v_pk_add_f32 v[102:103], v[102:103], 1.0 op_sel_hi:[1,0]
	v_pk_mul_f32 v[70:71], v[6:7], v[70:71]
	v_pk_fma_f32 v[70:71], v[102:103], v[70:71], v[86:87]
	v_pk_mul_f32 v[72:73], v[72:73], v[248:249] op_sel_hi:[1,0]
	v_pk_add_f32 v[104:105], v[104:105], 1.0 op_sel_hi:[1,0]
	v_pk_mul_f32 v[72:73], v[8:9], v[72:73]
	v_pk_fma_f32 v[72:73], v[104:105], v[72:73], v[88:89]
	v_cvt_pk_bf16_f32 v86, v70, v71
	v_cvt_pk_bf16_f32 v87, v72, v73
	global_store_dwordx2 v245, v[86:87], s[10:11] offset:512
	v_pk_mul_f32 v[74:75], v[74:75], v[248:249] op_sel_hi:[1,0]
	v_pk_add_f32 v[106:107], v[106:107], 1.0 op_sel_hi:[1,0]
	v_pk_mul_f32 v[74:75], v[10:11], v[74:75]
	v_pk_fma_f32 v[74:75], v[106:107], v[74:75], v[90:91]
	v_pk_mul_f32 v[76:77], v[76:77], v[248:249] op_sel_hi:[1,0]
	v_pk_add_f32 v[108:109], v[108:109], 1.0 op_sel_hi:[1,0]
	v_pk_mul_f32 v[76:77], v[12:13], v[76:77]
	v_pk_fma_f32 v[76:77], v[108:109], v[76:77], v[92:93]
	v_cvt_pk_bf16_f32 v90, v74, v75
	v_cvt_pk_bf16_f32 v91, v76, v77
	global_store_dwordx2 v245, v[90:91], s[10:11] offset:1024
	v_pk_mul_f32 v[78:79], v[78:79], v[248:249] op_sel_hi:[1,0]
	v_pk_add_f32 v[118:119], v[118:119], 1.0 op_sel_hi:[1,0]
	v_pk_mul_f32 v[78:79], v[14:15], v[78:79]
	v_pk_fma_f32 v[78:79], v[118:119], v[78:79], v[94:95]
	v_pk_mul_f32 v[80:81], v[80:81], v[248:249] op_sel_hi:[1,0]
	v_pk_add_f32 v[120:121], v[120:121], 1.0 op_sel_hi:[1,0]
	v_pk_mul_f32 v[80:81], v[16:17], v[80:81]
	v_pk_fma_f32 v[80:81], v[120:121], v[80:81], v[96:97]
	v_cvt_pk_bf16_f32 v94, v78, v79
	v_cvt_pk_bf16_f32 v95, v80, v81
	global_store_dwordx2 v245, v[94:95], s[10:11] offset:1536
	s_waitcnt vmcnt(8)
; DI unsigned pk_bf16(float lo, float hi) { f32x2 v = {lo, hi}; bf16v2 b = __builtin_convertvector(v, bf16v2); return __builtin_bit_cast(unsigned, b); }
; DI float red64(float x) { for (int o = 32; o > 0; o >>= 1) x += __shfl_xor(x, o); return x; }
; DI void modnorm_rows(const Params& p, int l, int which  , bool from_inputs, bool skip_ctx, int w0, int wstride, int lane) {
;     ...
;     float ss = 0.f;
; #pragma unroll
;     for (int q = 0; q < 4; ++q) ss += v[q][0] * v[q][0] + v[q][1] * v[q][1] + v[q][2] * v[q][2] + v[q][3] * v[q][3];
;     ss = red64(ss);
;     const float rs = rsqrtf(ss * (1.f / 1024.f) + EPSF);
;     bf16_t* dst = p.HY + (size_t)row * DM;
; #pragma unroll
;     for (int q = 0; q < 4; ++q) {
;       float o[4];
; #pragma unroll
;       for (int j = 0; j < 4; ++j) o[j] = (v[q][j] * rs * gg[q][j]) * (1.f + sc[q][j]) + sh[q][j];
;       u32x2 w = {pk_bf16(o[0], o[1]), pk_bf16(o[2], o[3])};
;       *(u32x2*)(dst + q * 256 + lane * 4) = w;
;     }
	v_pk_mul_f32 v[246:247], v[122:123], v[122:123]
	v_pk_fma_f32 v[246:247], v[124:125], v[124:125], v[246:247]
	v_pk_fma_f32 v[246:247], v[126:127], v[126:127], v[246:247]
	v_pk_fma_f32 v[246:247], v[128:129], v[128:129], v[246:247]
	v_pk_fma_f32 v[246:247], v[130:131], v[130:131], v[246:247]
	v_pk_fma_f32 v[246:247], v[132:133], v[132:133], v[246:247]
	v_pk_fma_f32 v[246:247], v[134:135], v[134:135], v[246:247]
	v_pk_fma_f32 v[246:247], v[136:137], v[136:137], v[246:247]
	s_nop 0
	v_add_f32_e32 v246, v246, v247
	s_nop 1
	v_add_f32_dpp v246, v246, v246 quad_perm:[1,0,3,2] row_mask:0xf bank_mask:0xf
	s_nop 1
	v_add_f32_dpp v246, v246, v246 quad_perm:[2,3,0,1] row_mask:0xf bank_mask:0xf
	s_nop 1
	v_add_f32_dpp v246, v246, v246 row_half_mirror row_mask:0xf bank_mask:0xf
	s_nop 1
	v_add_f32_dpp v246, v246, v246 row_mirror row_mask:0xf bank_mask:0xf
	s_nop 1
	v_add_f32_dpp v246, v246, v246 row_bcast:15 row_mask:0xa bank_mask:0xf
	s_nop 1
	v_add_f32_dpp v246, v246, v246 row_bcast:31 row_mask:0xc bank_mask:0xf
	s_nop 1
	v_readlane_b32 s0, v246, 63
	s_add_i32 s21, s37, 8
	s_cmp_ge_u32 s21, 9
	s_cselect_b32 s38, 9, 0
	s_sub_i32 s21, s21, s38
	s_lshl_b32 s21, s21, 11
	s_add_i32 s21, s21, s20
	s_lshl_b32 s21, s21, 11
	s_add_u32 s10, s16, s21
	s_addc_u32 s11, s17, 0
	v_mov_b32_e32 v248, s0
	v_fmamk_f32 v248, v248, 0x3a800000, v143
	v_rsq_f32_e32 v248, v248
	s_nop 0
	v_pk_mul_f32 v[122:123], v[122:123], v[248:249] op_sel_hi:[1,0]
	v_pk_add_f32 v[176:177], v[176:177], 1.0 op_sel_hi:[1,0]
	v_pk_mul_f32 v[122:123], v[2:3], v[122:123]
	v_pk_fma_f32 v[122:123], v[176:177], v[122:123], v[160:161]
	v_pk_mul_f32 v[124:125], v[124:125], v[248:249] op_sel_hi:[1,0]
	v_pk_add_f32 v[178:179], v[178:179], 1.0 op_sel_hi:[1,0]
	v_pk_mul_f32 v[124:125], v[4:5], v[124:125]
	v_pk_fma_f32 v[124:125], v[178:179], v[124:125], v[162:163]
	v_cvt_pk_bf16_f32 v160, v122, v123
	v_cvt_pk_bf16_f32 v161, v124, v125
	global_store_dwordx2 v245, v[160:161], s[10:11]
	v_pk_mul_f32 v[126:127], v[126:127], v[248:249] op_sel_hi:[1,0]
	v_pk_add_f32 v[180:181], v[180:181], 1.0 op_sel_hi:[1,0]
	v_pk_mul_f32 v[126:127], v[6:7], v[126:127]
	v_pk_fma_f32 v[126:127], v[180:181], v[126:127], v[164:165]
	v_pk_mul_f32 v[128:129], v[128:129], v[248:249] op_sel_hi:[1,0]
	v_pk_add_f32 v[182:183], v[182:183], 1.0 op_sel_hi:[1,0]
	v_pk_mul_f32 v[128:129], v[8:9], v[128:129]
	v_pk_fma_f32 v[128:129], v[182:183], v[128:129], v[166:167]
	v_cvt_pk_bf16_f32 v164, v126, v127
	v_cvt_pk_bf16_f32 v165, v128, v129
	global_store_dwordx2 v245, v[164:165], s[10:11] offset:512
	v_pk_mul_f32 v[130:131], v[130:131], v[248:249] op_sel_hi:[1,0]
	v_pk_add_f32 v[184:185], v[184:185], 1.0 op_sel_hi:[1,0]
	v_pk_mul_f32 v[130:131], v[10:11], v[130:131]
	v_pk_fma_f32 v[130:131], v[184:185], v[130:131], v[168:169]
	v_pk_mul_f32 v[132:133], v[132:133], v[248:249] op_sel_hi:[1,0]
	v_pk_add_f32 v[186:187], v[186:187], 1.0 op_sel_hi:[1,0]
	v_pk_mul_f32 v[132:133], v[12:13], v[132:133]
	v_pk_fma_f32 v[132:133], v[186:187], v[132:133], v[170:171]
	v_cvt_pk_bf16_f32 v168, v130, v131
	v_cvt_pk_bf16_f32 v169, v132, v133
	global_store_dwordx2 v245, v[168:169], s[10:11] offset:1024
	v_pk_mul_f32 v[134:135], v[134:135], v[248:249] op_sel_hi:[1,0]
	v_pk_add_f32 v[188:189], v[188:189], 1.0 op_sel_hi:[1,0]
	v_pk_mul_f32 v[134:135], v[14:15], v[134:135]
	v_pk_fma_f32 v[134:135], v[188:189], v[134:135], v[172:173]
	v_pk_mul_f32 v[136:137], v[136:137], v[248:249] op_sel_hi:[1,0]
	v_pk_add_f32 v[190:191], v[190:191], 1.0 op_sel_hi:[1,0]
	v_pk_mul_f32 v[136:137], v[16:17], v[136:137]
	v_pk_fma_f32 v[136:137], v[190:191], v[136:137], v[174:175]
	v_cvt_pk_bf16_f32 v172, v134, v135
	v_cvt_pk_bf16_f32 v173, v136, v137
	global_store_dwordx2 v245, v[172:173], s[10:11] offset:1536
	s_branch .Lnorm1_done
